# GEMM load-phase tails: the vmcnt(8) and lgkmcnt(0) waits in front of each phase barrier merged into one s_waitcnt (64 sites)
# speedup vs baseline: 1.0061x; 1.0061x over previous
.LBB0_298:
	s_lshl_b64 s[4:5], s[20:21], 17
	s_add_u32 s24, s2, s4
	s_addc_u32 s25, s19, s5
	s_and_b64 s[4:5], s[36:37], exec
	s_cselect_b32 s37, s25, s31
	s_cselect_b32 s36, s24, s30
	s_add_u32 s56, s30, 0x100
	s_addc_u32 s57, s31, 0
	s_add_u32 s80, s34, 0x100
	s_addc_u32 s81, s35, 0
	s_add_u32 s38, s30, 0x180
	s_addc_u32 s39, s31, 0
	s_add_i32 s4, 0, 0x10000
	s_add_i32 s17, 0, 0x14000
	v_add_u32_e32 v128, s4, v134
	v_add_u32_e32 v129, s17, v134
	ds_read_b128 v[0:3], v128
	ds_read_b128 v[4:7], v128 offset:1024
	ds_read_b128 v[8:11], v128 offset:2048
	ds_read_b128 v[12:15], v128 offset:3072
	ds_read_b128 v[16:19], v129
	ds_read_b128 v[20:23], v129 offset:1024
	ds_read_b128 v[24:27], v129 offset:2048
	ds_read_b128 v[28:31], v129 offset:3072
	s_add_u32 s70, s30, 0x10080
	s_addc_u32 s71, s31, 0
	s_add_i32 s5, s13, 0xc000
	s_mov_b32 m0, s5
	s_add_i32 s15, s13, 0xe000
	ds_read_b128 v[32:35], v135
	ds_read_b128 v[36:39], v135 offset:1024
	ds_read_b128 v[40:43], v135 offset:2048
	ds_read_b128 v[44:47], v135 offset:3072
	ds_read_b128 v[48:51], v135 offset:4096
	ds_read_b128 v[52:55], v135 offset:5120
	ds_read_b128 v[56:59], v135 offset:6144
	ds_read_b128 v[60:63], v135 offset:7168
	s_nop 0
	global_load_lds_dwordx4 v130, s[70:71]
	s_mov_b32 m0, s15
	s_nop 0
	global_load_lds_dwordx4 v132, s[70:71]
	s_waitcnt vmcnt(8) lgkmcnt(0)
	s_setprio 1
	s_barrier
	v_mfma_f32_16x16x32_bf16 v[64:67], v[0:3], v[32:35], 0
	v_mfma_f32_16x16x32_bf16 v[68:71], v[8:11], v[32:35], 0
	v_mfma_f32_16x16x32_bf16 v[72:75], v[0:3], v[40:43], 0
	v_mfma_f32_16x16x32_bf16 v[76:79], v[8:11], v[40:43], 0
	v_mfma_f32_16x16x32_bf16 v[80:83], v[0:3], v[48:51], 0
	v_mfma_f32_16x16x32_bf16 v[84:87], v[8:11], v[48:51], 0
	v_mfma_f32_16x16x32_bf16 v[88:91], v[0:3], v[56:59], 0
	v_mfma_f32_16x16x32_bf16 v[92:95], v[8:11], v[56:59], 0
	v_mfma_f32_16x16x32_bf16 v[64:67], v[4:7], v[36:39], v[64:67]
	v_mfma_f32_16x16x32_bf16 v[68:71], v[12:15], v[36:39], v[68:71]
	v_mfma_f32_16x16x32_bf16 v[72:75], v[4:7], v[44:47], v[72:75]
	v_mfma_f32_16x16x32_bf16 v[76:79], v[12:15], v[44:47], v[76:79]
	v_mfma_f32_16x16x32_bf16 v[80:83], v[4:7], v[52:55], v[80:83]
	v_mfma_f32_16x16x32_bf16 v[84:87], v[12:15], v[52:55], v[84:87]
	v_mfma_f32_16x16x32_bf16 v[88:91], v[4:7], v[60:63], v[88:91]
	v_mfma_f32_16x16x32_bf16 v[92:95], v[12:15], v[60:63], v[92:95]
	v_mfma_f32_16x16x32_bf16 v[96:99], v[16:19], v[32:35], 0
	v_mfma_f32_16x16x32_bf16 v[32:35], v[24:27], v[32:35], 0
	v_mfma_f32_16x16x32_bf16 v[96:99], v[20:23], v[36:39], v[96:99]
	v_mfma_f32_16x16x32_bf16 v[32:35], v[28:31], v[36:39], v[32:35]
	v_mfma_f32_16x16x32_bf16 v[36:39], v[16:19], v[40:43], 0
	v_mfma_f32_16x16x32_bf16 v[40:43], v[24:27], v[40:43], 0
	v_mfma_f32_16x16x32_bf16 v[36:39], v[20:23], v[44:47], v[36:39]
	v_mfma_f32_16x16x32_bf16 v[40:43], v[28:31], v[44:47], v[40:43]
	v_mfma_f32_16x16x32_bf16 v[44:47], v[16:19], v[48:51], 0
	v_mfma_f32_16x16x32_bf16 v[48:51], v[24:27], v[48:51], 0
	v_mfma_f32_16x16x32_bf16 v[44:47], v[20:23], v[52:55], v[44:47]
	v_mfma_f32_16x16x32_bf16 v[48:51], v[28:31], v[52:55], v[48:51]
	v_mfma_f32_16x16x32_bf16 v[52:55], v[16:19], v[56:59], 0
	v_mfma_f32_16x16x32_bf16 v[56:59], v[24:27], v[56:59], 0
	v_mfma_f32_16x16x32_bf16 v[52:55], v[20:23], v[60:63], v[52:55]
	v_mfma_f32_16x16x32_bf16 v[56:59], v[28:31], v[60:63], v[56:59]
	s_barrier
	s_setprio 0
	s_add_i32 s70, s4, s97
	s_add_i32 s4, s70, 0x2000
	s_mov_b32 m0, s70
	s_add_u32 s74, s34, 0x80100
	ds_read_b128 v[60:63], v135 offset:16384
	ds_read_b128 v[100:103], v135 offset:17408
	ds_read_b128 v[104:107], v135 offset:18432
	ds_read_b128 v[108:111], v135 offset:19456
	ds_read_b128 v[112:115], v135 offset:20480
	ds_read_b128 v[116:119], v135 offset:21504
	ds_read_b128 v[120:123], v135 offset:22528
	ds_read_b128 v[124:127], v135 offset:23552
	s_addc_u32 s75, s35, 0
	global_load_lds_dwordx4 v131, s[80:81]
	s_mov_b32 m0, s4
	s_add_i32 s17, s17, s97
	s_add_i32 s21, s17, 0x2000
	global_load_lds_dwordx4 v133, s[80:81]
	s_mov_b32 m0, s17
	s_nop 0
	global_load_lds_dwordx4 v131, s[74:75]
	s_mov_b32 m0, s21
	s_nop 0
	global_load_lds_dwordx4 v133, s[74:75]
	s_mov_b32 m0, s13
	s_nop 0
	global_load_lds_dwordx4 v130, s[56:57]
	s_mov_b32 m0, s27
	s_nop 0
	global_load_lds_dwordx4 v132, s[56:57]
	s_waitcnt vmcnt(8) lgkmcnt(0)
	s_setprio 1
	s_barrier
	v_mfma_f32_16x16x32_bf16 v[136:139], v[0:3], v[60:63], 0
	v_mfma_f32_16x16x32_bf16 v[144:147], v[0:3], v[104:107], 0
	v_mfma_f32_16x16x32_bf16 v[152:155], v[0:3], v[112:115], 0
	v_mfma_f32_16x16x32_bf16 v[0:3], v[0:3], v[120:123], 0
	v_mfma_f32_16x16x32_bf16 v[136:139], v[4:7], v[100:103], v[136:139]
	v_mfma_f32_16x16x32_bf16 v[144:147], v[4:7], v[108:111], v[144:147]
	v_mfma_f32_16x16x32_bf16 v[152:155], v[4:7], v[116:119], v[152:155]
	v_mfma_f32_16x16x32_bf16 v[0:3], v[4:7], v[124:127], v[0:3]
	v_mfma_f32_16x16x32_bf16 v[4:7], v[8:11], v[120:123], 0
	v_mfma_f32_16x16x32_bf16 v[140:143], v[8:11], v[60:63], 0
	v_mfma_f32_16x16x32_bf16 v[148:151], v[8:11], v[104:107], 0
	v_mfma_f32_16x16x32_bf16 v[156:159], v[8:11], v[112:115], 0
	v_mfma_f32_16x16x32_bf16 v[4:7], v[12:15], v[124:127], v[4:7]
	v_mfma_f32_16x16x32_bf16 v[140:143], v[12:15], v[100:103], v[140:143]
	v_mfma_f32_16x16x32_bf16 v[148:151], v[12:15], v[108:111], v[148:151]
	v_mfma_f32_16x16x32_bf16 v[156:159], v[12:15], v[116:119], v[156:159]
	v_mfma_f32_16x16x32_bf16 v[8:11], v[16:19], v[60:63], 0
	v_mfma_f32_16x16x32_bf16 v[12:15], v[24:27], v[60:63], 0
	v_mfma_f32_16x16x32_bf16 v[8:11], v[20:23], v[100:103], v[8:11]
	v_mfma_f32_16x16x32_bf16 v[12:15], v[28:31], v[100:103], v[12:15]
	v_mfma_f32_16x16x32_bf16 v[60:63], v[16:19], v[104:107], 0
	v_mfma_f32_16x16x32_bf16 v[100:103], v[24:27], v[104:107], 0
	v_mfma_f32_16x16x32_bf16 v[104:107], v[16:19], v[112:115], 0
	v_mfma_f32_16x16x32_bf16 v[16:19], v[16:19], v[120:123], 0
	v_mfma_f32_16x16x32_bf16 v[60:63], v[20:23], v[108:111], v[60:63]
	v_mfma_f32_16x16x32_bf16 v[100:103], v[28:31], v[108:111], v[100:103]
	v_mfma_f32_16x16x32_bf16 v[104:107], v[20:23], v[116:119], v[104:107]
	v_mfma_f32_16x16x32_bf16 v[108:111], v[24:27], v[112:115], 0
	v_mfma_f32_16x16x32_bf16 v[16:19], v[20:23], v[124:127], v[16:19]
	v_mfma_f32_16x16x32_bf16 v[20:23], v[24:27], v[120:123], 0
	v_mfma_f32_16x16x32_bf16 v[108:111], v[28:31], v[116:119], v[108:111]
	v_mfma_f32_16x16x32_bf16 v[20:23], v[28:31], v[124:127], v[20:23]
	s_barrier
	s_setprio 0
	s_add_i32 s71, 0, 0x18000
	s_add_i32 s69, 0, 0x1c000
	v_add_u32_e32 v196, s71, v134
	v_add_u32_e32 v198, s69, v134
	ds_read_b128 v[24:27], v196
	ds_read_b128 v[28:31], v196 offset:1024
	ds_read_b128 v[112:115], v196 offset:2048
	ds_read_b128 v[116:119], v196 offset:3072
	ds_read_b128 v[120:123], v198
	ds_read_b128 v[124:127], v198 offset:1024
	ds_read_b128 v[160:163], v198 offset:2048
	ds_read_b128 v[164:167], v198 offset:3072
	s_add_u32 s56, s30, 0x10100
	s_addc_u32 s57, s31, 0
	s_mov_b32 m0, s29
	ds_read_b128 v[168:171], v135 offset:32768
	ds_read_b128 v[172:175], v135 offset:33792
	ds_read_b128 v[176:179], v135 offset:34816
	ds_read_b128 v[180:183], v135 offset:35840
	ds_read_b128 v[184:187], v135 offset:36864
	ds_read_b128 v[188:191], v135 offset:37888
	ds_read_b128 v[192:195], v135 offset:38912
	ds_read_b128 v[200:203], v135 offset:39936
	s_nop 0
	global_load_lds_dwordx4 v130, s[56:57]
	s_mov_b32 m0, s47
	s_nop 0
	global_load_lds_dwordx4 v132, s[56:57]
	s_waitcnt vmcnt(8) lgkmcnt(0)
	s_setprio 1
	s_barrier
	v_mfma_f32_16x16x32_bf16 v[64:67], v[24:27], v[168:171], v[64:67]
	v_mfma_f32_16x16x32_bf16 v[64:67], v[28:31], v[172:175], v[64:67]
	v_mfma_f32_16x16x32_bf16 v[68:71], v[112:115], v[168:171], v[68:71]
	v_mfma_f32_16x16x32_bf16 v[68:71], v[116:119], v[172:175], v[68:71]
	v_mfma_f32_16x16x32_bf16 v[72:75], v[24:27], v[176:179], v[72:75]
	v_mfma_f32_16x16x32_bf16 v[72:75], v[28:31], v[180:183], v[72:75]
	v_mfma_f32_16x16x32_bf16 v[76:79], v[112:115], v[176:179], v[76:79]
	v_mfma_f32_16x16x32_bf16 v[76:79], v[116:119], v[180:183], v[76:79]
	v_mfma_f32_16x16x32_bf16 v[80:83], v[24:27], v[184:187], v[80:83]
	v_mfma_f32_16x16x32_bf16 v[80:83], v[28:31], v[188:191], v[80:83]
	v_mfma_f32_16x16x32_bf16 v[84:87], v[112:115], v[184:187], v[84:87]
	v_mfma_f32_16x16x32_bf16 v[84:87], v[116:119], v[188:191], v[84:87]
	v_mfma_f32_16x16x32_bf16 v[88:91], v[24:27], v[192:195], v[88:91]
	v_mfma_f32_16x16x32_bf16 v[88:91], v[28:31], v[200:203], v[88:91]
	v_mfma_f32_16x16x32_bf16 v[92:95], v[112:115], v[192:195], v[92:95]
	v_mfma_f32_16x16x32_bf16 v[92:95], v[116:119], v[200:203], v[92:95]
	v_mfma_f32_16x16x32_bf16 v[96:99], v[120:123], v[168:171], v[96:99]
	v_mfma_f32_16x16x32_bf16 v[96:99], v[124:127], v[172:175], v[96:99]
	v_mfma_f32_16x16x32_bf16 v[32:35], v[160:163], v[168:171], v[32:35]
	v_mfma_f32_16x16x32_bf16 v[32:35], v[164:167], v[172:175], v[32:35]
	v_mfma_f32_16x16x32_bf16 v[36:39], v[120:123], v[176:179], v[36:39]
	v_mfma_f32_16x16x32_bf16 v[36:39], v[124:127], v[180:183], v[36:39]
	v_mfma_f32_16x16x32_bf16 v[40:43], v[160:163], v[176:179], v[40:43]
	v_mfma_f32_16x16x32_bf16 v[40:43], v[164:167], v[180:183], v[40:43]
	v_mfma_f32_16x16x32_bf16 v[44:47], v[120:123], v[184:187], v[44:47]
	v_mfma_f32_16x16x32_bf16 v[44:47], v[124:127], v[188:191], v[44:47]
	v_mfma_f32_16x16x32_bf16 v[48:51], v[160:163], v[184:187], v[48:51]
	v_mfma_f32_16x16x32_bf16 v[48:51], v[164:167], v[188:191], v[48:51]
	v_mfma_f32_16x16x32_bf16 v[52:55], v[120:123], v[192:195], v[52:55]
	v_mfma_f32_16x16x32_bf16 v[52:55], v[124:127], v[200:203], v[52:55]
	v_mfma_f32_16x16x32_bf16 v[56:59], v[160:163], v[192:195], v[56:59]
	v_mfma_f32_16x16x32_bf16 v[56:59], v[164:167], v[200:203], v[56:59]
	s_barrier
	s_setprio 0
	s_add_u32 s74, s34, 0x180
	s_addc_u32 s75, s35, 0
	s_add_i32 s71, s71, s97
	s_add_i32 s56, s71, 0x2000
	s_mov_b32 m0, s71
	s_add_u32 s34, s34, 0x80180
	ds_read_b128 v[168:171], v135 offset:49152
	ds_read_b128 v[172:175], v135 offset:50176
	ds_read_b128 v[176:179], v135 offset:51200
	ds_read_b128 v[180:183], v135 offset:52224
	ds_read_b128 v[184:187], v135 offset:53248
	ds_read_b128 v[188:191], v135 offset:54272
	ds_read_b128 v[192:195], v135 offset:55296
	ds_read_b128 v[200:203], v135 offset:56320
	s_addc_u32 s35, s35, 0
	global_load_lds_dwordx4 v131, s[74:75]
	s_mov_b32 m0, s56
	s_add_i32 s57, s69, s97
	s_add_i32 s69, s57, 0x2000
	global_load_lds_dwordx4 v133, s[74:75]
	s_mov_b32 m0, s57
	s_nop 0
	global_load_lds_dwordx4 v131, s[34:35]
	s_mov_b32 m0, s69
	s_nop 0
	global_load_lds_dwordx4 v133, s[34:35]
	s_mov_b32 m0, s48
	s_nop 0
	global_load_lds_dwordx4 v130, s[38:39]
	s_mov_b32 m0, s49
	s_nop 0
	global_load_lds_dwordx4 v132, s[38:39]
	s_waitcnt vmcnt(8) lgkmcnt(0)
	s_setprio 1
	s_barrier
	v_mfma_f32_16x16x32_bf16 v[0:3], v[24:27], v[192:195], v[0:3]
	v_mfma_f32_16x16x32_bf16 v[0:3], v[28:31], v[200:203], v[0:3]
	v_mfma_f32_16x16x32_bf16 v[4:7], v[112:115], v[192:195], v[4:7]
	v_mfma_f32_16x16x32_bf16 v[4:7], v[116:119], v[200:203], v[4:7]
	v_mfma_f32_16x16x32_bf16 v[136:139], v[24:27], v[168:171], v[136:139]
	v_mfma_f32_16x16x32_bf16 v[136:139], v[28:31], v[172:175], v[136:139]
	v_mfma_f32_16x16x32_bf16 v[140:143], v[112:115], v[168:171], v[140:143]
	v_mfma_f32_16x16x32_bf16 v[140:143], v[116:119], v[172:175], v[140:143]
	v_mfma_f32_16x16x32_bf16 v[144:147], v[24:27], v[176:179], v[144:147]
	v_mfma_f32_16x16x32_bf16 v[144:147], v[28:31], v[180:183], v[144:147]
	v_mfma_f32_16x16x32_bf16 v[148:151], v[112:115], v[176:179], v[148:151]
	v_mfma_f32_16x16x32_bf16 v[148:151], v[116:119], v[180:183], v[148:151]
	v_mfma_f32_16x16x32_bf16 v[152:155], v[24:27], v[184:187], v[152:155]
	v_mfma_f32_16x16x32_bf16 v[152:155], v[28:31], v[188:191], v[152:155]
	v_mfma_f32_16x16x32_bf16 v[156:159], v[112:115], v[184:187], v[156:159]
	v_mfma_f32_16x16x32_bf16 v[156:159], v[116:119], v[188:191], v[156:159]
	v_mfma_f32_16x16x32_bf16 v[8:11], v[120:123], v[168:171], v[8:11]
	v_mfma_f32_16x16x32_bf16 v[12:15], v[160:163], v[168:171], v[12:15]
	v_mfma_f32_16x16x32_bf16 v[24:27], v[120:123], v[176:179], v[60:63]
	v_mfma_f32_16x16x32_bf16 v[28:31], v[160:163], v[176:179], v[100:103]
	v_mfma_f32_16x16x32_bf16 v[60:63], v[120:123], v[184:187], v[104:107]
	v_mfma_f32_16x16x32_bf16 v[100:103], v[160:163], v[184:187], v[108:111]
	v_mfma_f32_16x16x32_bf16 v[16:19], v[120:123], v[192:195], v[16:19]
	v_mfma_f32_16x16x32_bf16 v[20:23], v[160:163], v[192:195], v[20:23]
	v_mfma_f32_16x16x32_bf16 v[8:11], v[124:127], v[172:175], v[8:11]
	v_mfma_f32_16x16x32_bf16 v[12:15], v[164:167], v[172:175], v[12:15]
	v_mfma_f32_16x16x32_bf16 v[24:27], v[124:127], v[180:183], v[24:27]
	v_mfma_f32_16x16x32_bf16 v[28:31], v[164:167], v[180:183], v[28:31]
	v_mfma_f32_16x16x32_bf16 v[60:63], v[124:127], v[188:191], v[60:63]
	v_mfma_f32_16x16x32_bf16 v[100:103], v[164:167], v[188:191], v[100:103]
	v_mfma_f32_16x16x32_bf16 v[16:19], v[124:127], v[200:203], v[16:19]
	v_mfma_f32_16x16x32_bf16 v[20:23], v[164:167], v[200:203], v[20:23]
	s_barrier
	s_setprio 0
	ds_read_b128 v[104:107], v128
	ds_read_b128 v[108:111], v128 offset:1024
	ds_read_b128 v[112:115], v128 offset:2048
	ds_read_b128 v[116:119], v128 offset:3072
	ds_read_b128 v[120:123], v129
	ds_read_b128 v[124:127], v129 offset:1024
	ds_read_b128 v[160:163], v129 offset:2048
	ds_read_b128 v[164:167], v129 offset:3072
	s_add_u32 s34, s36, 0x80
	s_addc_u32 s35, s37, 0
	s_add_u32 s30, s30, 0x10180
	s_addc_u32 s31, s31, 0
	s_mov_b32 m0, s5
	ds_read_b128 v[168:171], v135
	ds_read_b128 v[172:175], v135 offset:1024
	ds_read_b128 v[176:179], v135 offset:2048
	ds_read_b128 v[180:183], v135 offset:3072
	ds_read_b128 v[184:187], v135 offset:4096
	ds_read_b128 v[188:191], v135 offset:5120
	ds_read_b128 v[192:195], v135 offset:6144
	ds_read_b128 v[200:203], v135 offset:7168
	s_nop 0
	global_load_lds_dwordx4 v130, s[30:31]
	s_mov_b32 m0, s15
	s_nop 0
	global_load_lds_dwordx4 v132, s[30:31]
	s_waitcnt vmcnt(8) lgkmcnt(0)
	s_setprio 1
	s_barrier
	v_mfma_f32_16x16x32_bf16 v[64:67], v[104:107], v[168:171], v[64:67]
	v_mfma_f32_16x16x32_bf16 v[64:67], v[108:111], v[172:175], v[64:67]
	v_mfma_f32_16x16x32_bf16 v[68:71], v[112:115], v[168:171], v[68:71]
	v_mfma_f32_16x16x32_bf16 v[68:71], v[116:119], v[172:175], v[68:71]
	v_mfma_f32_16x16x32_bf16 v[72:75], v[104:107], v[176:179], v[72:75]
	v_mfma_f32_16x16x32_bf16 v[72:75], v[108:111], v[180:183], v[72:75]
	v_mfma_f32_16x16x32_bf16 v[76:79], v[112:115], v[176:179], v[76:79]
	v_mfma_f32_16x16x32_bf16 v[76:79], v[116:119], v[180:183], v[76:79]
	v_mfma_f32_16x16x32_bf16 v[80:83], v[104:107], v[184:187], v[80:83]
	v_mfma_f32_16x16x32_bf16 v[80:83], v[108:111], v[188:191], v[80:83]
	v_mfma_f32_16x16x32_bf16 v[84:87], v[112:115], v[184:187], v[84:87]
	v_mfma_f32_16x16x32_bf16 v[84:87], v[116:119], v[188:191], v[84:87]
	v_mfma_f32_16x16x32_bf16 v[88:91], v[104:107], v[192:195], v[88:91]
	v_mfma_f32_16x16x32_bf16 v[88:91], v[108:111], v[200:203], v[88:91]
	v_mfma_f32_16x16x32_bf16 v[92:95], v[112:115], v[192:195], v[92:95]
	v_mfma_f32_16x16x32_bf16 v[92:95], v[116:119], v[200:203], v[92:95]
	v_mfma_f32_16x16x32_bf16 v[32:35], v[160:163], v[168:171], v[32:35]
	v_mfma_f32_16x16x32_bf16 v[96:99], v[120:123], v[168:171], v[96:99]
	v_mfma_f32_16x16x32_bf16 v[168:171], v[164:167], v[172:175], v[32:35]
	v_mfma_f32_16x16x32_bf16 v[32:35], v[120:123], v[176:179], v[36:39]
	v_mfma_f32_16x16x32_bf16 v[36:39], v[124:127], v[180:183], v[32:35]
	v_mfma_f32_16x16x32_bf16 v[32:35], v[160:163], v[176:179], v[40:43]
	v_mfma_f32_16x16x32_bf16 v[204:207], v[124:127], v[172:175], v[96:99]
	v_mfma_f32_16x16x32_bf16 v[172:175], v[164:167], v[180:183], v[32:35]
	v_mfma_f32_16x16x32_bf16 v[32:35], v[120:123], v[184:187], v[44:47]
	v_mfma_f32_16x16x32_bf16 v[44:47], v[124:127], v[188:191], v[32:35]
	v_mfma_f32_16x16x32_bf16 v[32:35], v[160:163], v[184:187], v[48:51]
	v_mfma_f32_16x16x32_bf16 v[48:51], v[164:167], v[188:191], v[32:35]
	v_mfma_f32_16x16x32_bf16 v[32:35], v[120:123], v[192:195], v[52:55]
	v_mfma_f32_16x16x32_bf16 v[52:55], v[124:127], v[200:203], v[32:35]
	v_mfma_f32_16x16x32_bf16 v[32:35], v[160:163], v[192:195], v[56:59]
	v_mfma_f32_16x16x32_bf16 v[56:59], v[164:167], v[200:203], v[32:35]
	s_barrier
	s_setprio 0
	s_mov_b32 m0, s70
	s_mov_b64 s[30:31], s[22:23]
	s_nop 2
	ds_read_b128 v[32:35], v135 offset:16384
	ds_read_b128 v[40:43], v135 offset:17408
	ds_read_b128 v[96:99], v135 offset:18432
	ds_read_b128 v[176:179], v135 offset:19456
	ds_read_b128 v[180:183], v135 offset:20480
	ds_read_b128 v[184:187], v135 offset:21504
	ds_read_b128 v[188:191], v135 offset:22528
	ds_read_b128 v[192:195], v135 offset:23552
	s_nop 0
	global_load_lds_dwordx4 v131, s[30:31]
	s_mov_b32 m0, s4
	s_add_u32 s4, s22, 0x80000
	s_addc_u32 s5, s23, 0
	global_load_lds_dwordx4 v133, s[30:31]
	s_mov_b32 m0, s17
	s_nop 0
	global_load_lds_dwordx4 v131, s[4:5]
	s_mov_b32 m0, s21
	s_nop 0
	global_load_lds_dwordx4 v133, s[4:5]
	s_mov_b64 s[4:5], s[36:37]
	s_mov_b32 m0, s13
	s_nop 0
	global_load_lds_dwordx4 v130, s[4:5]
	s_mov_b32 m0, s27
	s_nop 0
	global_load_lds_dwordx4 v132, s[4:5]
	s_waitcnt vmcnt(8) lgkmcnt(0)
	s_setprio 1
	s_barrier
	v_mfma_f32_16x16x32_bf16 v[0:3], v[104:107], v[188:191], v[0:3]
	v_mfma_f32_16x16x32_bf16 v[0:3], v[108:111], v[192:195], v[0:3]
	v_mfma_f32_16x16x32_bf16 v[4:7], v[112:115], v[188:191], v[4:7]
	v_mfma_f32_16x16x32_bf16 v[4:7], v[116:119], v[192:195], v[4:7]
	v_mfma_f32_16x16x32_bf16 v[136:139], v[104:107], v[32:35], v[136:139]
	v_mfma_f32_16x16x32_bf16 v[136:139], v[108:111], v[40:43], v[136:139]
	v_mfma_f32_16x16x32_bf16 v[140:143], v[112:115], v[32:35], v[140:143]
	v_mfma_f32_16x16x32_bf16 v[140:143], v[116:119], v[40:43], v[140:143]
	v_mfma_f32_16x16x32_bf16 v[144:147], v[104:107], v[96:99], v[144:147]
	v_mfma_f32_16x16x32_bf16 v[144:147], v[108:111], v[176:179], v[144:147]
	v_mfma_f32_16x16x32_bf16 v[148:151], v[112:115], v[96:99], v[148:151]
	v_mfma_f32_16x16x32_bf16 v[148:151], v[116:119], v[176:179], v[148:151]
	v_mfma_f32_16x16x32_bf16 v[152:155], v[104:107], v[180:183], v[152:155]
	v_mfma_f32_16x16x32_bf16 v[152:155], v[108:111], v[184:187], v[152:155]
	v_mfma_f32_16x16x32_bf16 v[156:159], v[112:115], v[180:183], v[156:159]
	v_mfma_f32_16x16x32_bf16 v[156:159], v[116:119], v[184:187], v[156:159]
	v_mfma_f32_16x16x32_bf16 v[12:15], v[160:163], v[32:35], v[12:15]
	v_mfma_f32_16x16x32_bf16 v[200:203], v[164:167], v[40:43], v[12:15]
	v_mfma_f32_16x16x32_bf16 v[12:15], v[120:123], v[96:99], v[24:27]
	v_mfma_f32_16x16x32_bf16 v[24:27], v[124:127], v[176:179], v[12:15]
	v_mfma_f32_16x16x32_bf16 v[12:15], v[160:163], v[96:99], v[28:31]
	v_mfma_f32_16x16x32_bf16 v[176:179], v[164:167], v[176:179], v[12:15]
	v_mfma_f32_16x16x32_bf16 v[12:15], v[120:123], v[180:183], v[60:63]
	v_mfma_f32_16x16x32_bf16 v[208:211], v[124:127], v[184:187], v[12:15]
	v_mfma_f32_16x16x32_bf16 v[12:15], v[160:163], v[180:183], v[100:103]
	v_mfma_f32_16x16x32_bf16 v[8:11], v[120:123], v[32:35], v[8:11]
	v_mfma_f32_16x16x32_bf16 v[180:183], v[164:167], v[184:187], v[12:15]
	v_mfma_f32_16x16x32_bf16 v[12:15], v[120:123], v[188:191], v[16:19]
	v_mfma_f32_16x16x32_bf16 v[8:11], v[124:127], v[40:43], v[8:11]
	v_mfma_f32_16x16x32_bf16 v[184:187], v[124:127], v[192:195], v[12:15]
	v_mfma_f32_16x16x32_bf16 v[12:15], v[160:163], v[188:191], v[20:23]
	v_mfma_f32_16x16x32_bf16 v[160:163], v[164:167], v[192:195], v[12:15]
	s_barrier
	s_setprio 0
	s_nop 4
	ds_read_b128 v[12:15], v196
	ds_read_b128 v[16:19], v196 offset:1024
	ds_read_b128 v[164:167], v196 offset:2048
	ds_read_b128 v[188:191], v196 offset:3072
	ds_read_b128 v[192:195], v198
	ds_read_b128 v[220:223], v198 offset:1024
	ds_read_b128 v[224:227], v198 offset:2048
	ds_read_b128 v[228:231], v198 offset:3072
	s_add_u32 s4, s36, 0x10000
	s_addc_u32 s5, s37, 0
	s_mov_b32 m0, s29
	ds_read_b128 v[20:23], v135 offset:32768
	ds_read_b128 v[28:31], v135 offset:33792
	ds_read_b128 v[60:63], v135 offset:34816
	ds_read_b128 v[100:103], v135 offset:35840
	ds_read_b128 v[232:235], v135 offset:36864
	ds_read_b128 v[236:239], v135 offset:37888
	ds_read_b128 v[240:243], v135 offset:38912
	ds_read_b128 v[244:247], v135 offset:39936
	s_nop 0
	global_load_lds_dwordx4 v130, s[4:5]
	s_mov_b32 m0, s47
	s_nop 0
	global_load_lds_dwordx4 v132, s[4:5]
	s_waitcnt vmcnt(8) lgkmcnt(0)
	s_setprio 1
	s_barrier
	v_mfma_f32_16x16x32_bf16 v[32:35], v[12:15], v[20:23], v[64:67]
	v_mfma_f32_16x16x32_bf16 v[120:123], v[16:19], v[28:31], v[32:35]
	v_mfma_f32_16x16x32_bf16 v[32:35], v[164:167], v[20:23], v[68:71]
	v_mfma_f32_16x16x32_bf16 v[112:115], v[188:191], v[28:31], v[32:35]
	v_mfma_f32_16x16x32_bf16 v[32:35], v[12:15], v[60:63], v[72:75]
	v_mfma_f32_16x16x32_bf16 v[104:107], v[16:19], v[100:103], v[32:35]
	v_mfma_f32_16x16x32_bf16 v[32:35], v[164:167], v[60:63], v[76:79]
	v_mfma_f32_16x16x32_bf16 v[96:99], v[188:191], v[100:103], v[32:35]
	v_mfma_f32_16x16x32_bf16 v[32:35], v[12:15], v[232:235], v[80:83]
	v_mfma_f32_16x16x32_bf16 v[72:75], v[16:19], v[236:239], v[32:35]
	v_mfma_f32_16x16x32_bf16 v[32:35], v[164:167], v[232:235], v[84:87]
	v_mfma_f32_16x16x32_bf16 v[64:67], v[188:191], v[236:239], v[32:35]
	v_mfma_f32_16x16x32_bf16 v[32:35], v[12:15], v[240:243], v[88:91]
	v_mfma_f32_16x16x32_bf16 v[40:43], v[16:19], v[244:247], v[32:35]
	v_mfma_f32_16x16x32_bf16 v[32:35], v[164:167], v[240:243], v[92:95]
	v_mfma_f32_16x16x32_bf16 v[32:35], v[188:191], v[244:247], v[32:35]
	v_mfma_f32_16x16x32_bf16 v[68:71], v[192:195], v[20:23], v[204:207]
	v_mfma_f32_16x16x32_bf16 v[20:23], v[224:227], v[20:23], v[168:171]
	v_mfma_f32_16x16x32_bf16 v[116:119], v[228:231], v[28:31], v[20:23]
	v_mfma_f32_16x16x32_bf16 v[20:23], v[192:195], v[60:63], v[36:39]
	v_mfma_f32_16x16x32_bf16 v[108:111], v[220:223], v[100:103], v[20:23]
	v_mfma_f32_16x16x32_bf16 v[20:23], v[224:227], v[60:63], v[172:175]
	v_mfma_f32_16x16x32_bf16 v[100:103], v[228:231], v[100:103], v[20:23]
	v_mfma_f32_16x16x32_bf16 v[20:23], v[192:195], v[232:235], v[44:47]
	v_mfma_f32_16x16x32_bf16 v[76:79], v[220:223], v[236:239], v[20:23]
	v_mfma_f32_16x16x32_bf16 v[20:23], v[224:227], v[232:235], v[48:51]
	v_mfma_f32_16x16x32_bf16 v[124:127], v[220:223], v[28:31], v[68:71]
	v_mfma_f32_16x16x32_bf16 v[68:71], v[228:231], v[236:239], v[20:23]
	v_mfma_f32_16x16x32_bf16 v[20:23], v[192:195], v[240:243], v[52:55]
	v_mfma_f32_16x16x32_bf16 v[44:47], v[220:223], v[244:247], v[20:23]
	v_mfma_f32_16x16x32_bf16 v[20:23], v[224:227], v[240:243], v[56:59]
	v_mfma_f32_16x16x32_bf16 v[36:39], v[228:231], v[244:247], v[20:23]
	s_barrier
	s_setprio 0
	s_add_u32 s4, s22, 0x80
	s_mov_b32 m0, s71
	s_addc_u32 s5, s23, 0
	ds_read_b128 v[48:51], v135 offset:49152
	ds_read_b128 v[56:59], v135 offset:50176
	ds_read_b128 v[168:171], v135 offset:51200
	ds_read_b128 v[172:175], v135 offset:52224
	ds_read_b128 v[204:207], v135 offset:53248
	ds_read_b128 v[232:235], v135 offset:54272
	ds_read_b128 v[236:239], v135 offset:55296
	ds_read_b128 v[240:243], v135 offset:56320
	s_nop 0
	global_load_lds_dwordx4 v131, s[4:5]
	s_mov_b32 m0, s56
	s_nop 0
	global_load_lds_dwordx4 v133, s[4:5]
	s_add_u32 s4, s22, 0x80080
	s_addc_u32 s5, s23, 0
	s_mov_b32 m0, s57
	s_nop 0
	global_load_lds_dwordx4 v131, s[4:5]
	s_mov_b32 m0, s69
	s_nop 0
	global_load_lds_dwordx4 v133, s[4:5]
	s_mov_b32 m0, s48
	s_nop 0
	global_load_lds_dwordx4 v130, s[34:35]
	s_mov_b32 m0, s49
	s_nop 0
	global_load_lds_dwordx4 v132, s[34:35]
	s_waitcnt vmcnt(8) lgkmcnt(0)
	s_setprio 1
	s_barrier
	v_mfma_f32_16x16x32_bf16 v[20:23], v[12:15], v[48:51], v[136:139]
	v_mfma_f32_16x16x32_bf16 v[92:95], v[16:19], v[56:59], v[20:23]
	v_mfma_f32_16x16x32_bf16 v[20:23], v[164:167], v[48:51], v[140:143]
	v_mfma_f32_16x16x32_bf16 v[84:87], v[188:191], v[56:59], v[20:23]
	v_mfma_f32_16x16x32_bf16 v[20:23], v[12:15], v[168:171], v[144:147]
	v_mfma_f32_16x16x32_bf16 v[60:63], v[16:19], v[172:175], v[20:23]
	v_mfma_f32_16x16x32_bf16 v[20:23], v[164:167], v[168:171], v[148:151]
	v_mfma_f32_16x16x32_bf16 v[52:55], v[188:191], v[172:175], v[20:23]
	v_mfma_f32_16x16x32_bf16 v[20:23], v[12:15], v[204:207], v[152:155]
	v_mfma_f32_16x16x32_bf16 v[0:3], v[12:15], v[236:239], v[0:3]
	v_mfma_f32_16x16x32_bf16 v[28:31], v[16:19], v[232:235], v[20:23]
	v_mfma_f32_16x16x32_bf16 v[20:23], v[164:167], v[204:207], v[156:159]
	v_mfma_f32_16x16x32_bf16 v[12:15], v[16:19], v[240:243], v[0:3]
	v_mfma_f32_16x16x32_bf16 v[0:3], v[164:167], v[236:239], v[4:7]
	v_mfma_f32_16x16x32_bf16 v[20:23], v[188:191], v[232:235], v[20:23]
	v_mfma_f32_16x16x32_bf16 v[4:7], v[188:191], v[240:243], v[0:3]
	v_mfma_f32_16x16x32_bf16 v[0:3], v[192:195], v[48:51], v[8:11]
	v_mfma_f32_16x16x32_bf16 v[88:91], v[220:223], v[56:59], v[0:3]
	v_mfma_f32_16x16x32_bf16 v[0:3], v[224:227], v[48:51], v[200:203]
	v_mfma_f32_16x16x32_bf16 v[80:83], v[228:231], v[56:59], v[0:3]
	v_mfma_f32_16x16x32_bf16 v[0:3], v[192:195], v[168:171], v[24:27]
	v_mfma_f32_16x16x32_bf16 v[56:59], v[220:223], v[172:175], v[0:3]
	v_mfma_f32_16x16x32_bf16 v[0:3], v[224:227], v[168:171], v[176:179]
	v_mfma_f32_16x16x32_bf16 v[48:51], v[228:231], v[172:175], v[0:3]
	v_mfma_f32_16x16x32_bf16 v[0:3], v[192:195], v[204:207], v[208:211]
	v_mfma_f32_16x16x32_bf16 v[24:27], v[220:223], v[232:235], v[0:3]
	v_mfma_f32_16x16x32_bf16 v[0:3], v[224:227], v[204:207], v[180:183]
	v_mfma_f32_16x16x32_bf16 v[16:19], v[228:231], v[232:235], v[0:3]
	v_mfma_f32_16x16x32_bf16 v[0:3], v[192:195], v[236:239], v[184:187]
	v_mfma_f32_16x16x32_bf16 v[8:11], v[220:223], v[240:243], v[0:3]
	v_mfma_f32_16x16x32_bf16 v[0:3], v[224:227], v[236:239], v[160:163]
	v_mfma_f32_16x16x32_bf16 v[0:3], v[228:231], v[240:243], v[0:3]
	s_barrier
	s_setprio 0
	s_andn2_b64 vcc, exec, s[60:61]
	s_cbranch_vccnz .LBB0_300
	s_barrier

.LBB0_313:
	s_ashr_i32 s15, s14, 31
	s_lshl_b64 s[4:5], s[14:15], 17
	s_add_u32 s20, s2, s4
	s_addc_u32 s21, s19, s5
	s_and_b64 s[4:5], s[16:17], exec
	s_cselect_b32 s39, s21, s31
	s_cselect_b32 s38, s20, s30
	s_ashr_i32 s11, s10, 31
	s_lshl_b64 s[4:5], s[10:11], 9
	s_add_u32 s11, s44, s4
	s_addc_u32 s15, s46, s5
	s_ashr_i32 s13, s12, 31
	s_lshl_b64 s[4:5], s[12:13], 20
	s_add_u32 s22, s11, s4
	s_addc_u32 s23, s15, s5
	s_and_b64 s[4:5], s[16:17], exec
	s_cselect_b32 s35, s23, s37
	s_cselect_b32 s34, s22, s36
	s_add_u32 s56, s30, 0x100
	s_addc_u32 s57, s31, 0
	s_add_u32 s82, s36, 0x100
	s_addc_u32 s83, s37, 0
	s_add_u32 s80, s30, 0x180
	s_addc_u32 s81, s31, 0
	s_add_i32 s4, 0, 0x10000
	s_add_i32 s13, 0, 0x14000
	v_add_u32_e32 v128, s4, v134
	v_add_u32_e32 v129, s13, v134
	ds_read_b128 v[0:3], v128
	ds_read_b128 v[4:7], v128 offset:1024
	ds_read_b128 v[8:11], v128 offset:2048
	ds_read_b128 v[12:15], v128 offset:3072
	ds_read_b128 v[16:19], v129
	ds_read_b128 v[20:23], v129 offset:1024
	ds_read_b128 v[24:27], v129 offset:2048
	ds_read_b128 v[28:31], v129 offset:3072
	s_add_u32 s70, s30, 0x10080
	s_addc_u32 s71, s31, 0
	s_add_i32 s5, s25, 0xc000
	s_mov_b32 m0, s5
	s_add_i32 s11, s25, 0xe000
	ds_read_b128 v[32:35], v135
	ds_read_b128 v[36:39], v135 offset:1024
	ds_read_b128 v[40:43], v135 offset:2048
	ds_read_b128 v[44:47], v135 offset:3072
	ds_read_b128 v[48:51], v135 offset:4096
	ds_read_b128 v[52:55], v135 offset:5120
	ds_read_b128 v[56:59], v135 offset:6144
	ds_read_b128 v[60:63], v135 offset:7168
	s_nop 0
	global_load_lds_dwordx4 v133, s[70:71]
	s_mov_b32 m0, s11
	s_nop 0
	global_load_lds_dwordx4 v131, s[70:71]
	s_waitcnt vmcnt(8) lgkmcnt(0)
	s_setprio 1
	s_barrier
	v_mfma_f32_16x16x32_bf16 v[64:67], v[0:3], v[32:35], 0
	v_mfma_f32_16x16x32_bf16 v[68:71], v[8:11], v[32:35], 0
	v_mfma_f32_16x16x32_bf16 v[72:75], v[0:3], v[40:43], 0
	v_mfma_f32_16x16x32_bf16 v[76:79], v[8:11], v[40:43], 0
	v_mfma_f32_16x16x32_bf16 v[80:83], v[0:3], v[48:51], 0
	v_mfma_f32_16x16x32_bf16 v[84:87], v[8:11], v[48:51], 0
	v_mfma_f32_16x16x32_bf16 v[88:91], v[0:3], v[56:59], 0
	v_mfma_f32_16x16x32_bf16 v[92:95], v[8:11], v[56:59], 0
	v_mfma_f32_16x16x32_bf16 v[64:67], v[4:7], v[36:39], v[64:67]
	v_mfma_f32_16x16x32_bf16 v[68:71], v[12:15], v[36:39], v[68:71]
	v_mfma_f32_16x16x32_bf16 v[72:75], v[4:7], v[44:47], v[72:75]
	v_mfma_f32_16x16x32_bf16 v[76:79], v[12:15], v[44:47], v[76:79]
	v_mfma_f32_16x16x32_bf16 v[80:83], v[4:7], v[52:55], v[80:83]
	v_mfma_f32_16x16x32_bf16 v[84:87], v[12:15], v[52:55], v[84:87]
	v_mfma_f32_16x16x32_bf16 v[88:91], v[4:7], v[60:63], v[88:91]
	v_mfma_f32_16x16x32_bf16 v[92:95], v[12:15], v[60:63], v[92:95]
	v_mfma_f32_16x16x32_bf16 v[96:99], v[16:19], v[32:35], 0
	v_mfma_f32_16x16x32_bf16 v[32:35], v[24:27], v[32:35], 0
	v_mfma_f32_16x16x32_bf16 v[96:99], v[20:23], v[36:39], v[96:99]
	v_mfma_f32_16x16x32_bf16 v[32:35], v[28:31], v[36:39], v[32:35]
	v_mfma_f32_16x16x32_bf16 v[36:39], v[16:19], v[40:43], 0
	v_mfma_f32_16x16x32_bf16 v[40:43], v[24:27], v[40:43], 0
	v_mfma_f32_16x16x32_bf16 v[36:39], v[20:23], v[44:47], v[36:39]
	v_mfma_f32_16x16x32_bf16 v[40:43], v[28:31], v[44:47], v[40:43]
	v_mfma_f32_16x16x32_bf16 v[44:47], v[16:19], v[48:51], 0
	v_mfma_f32_16x16x32_bf16 v[48:51], v[24:27], v[48:51], 0
	v_mfma_f32_16x16x32_bf16 v[44:47], v[20:23], v[52:55], v[44:47]
	v_mfma_f32_16x16x32_bf16 v[48:51], v[28:31], v[52:55], v[48:51]
	v_mfma_f32_16x16x32_bf16 v[52:55], v[16:19], v[56:59], 0
	v_mfma_f32_16x16x32_bf16 v[56:59], v[24:27], v[56:59], 0
	v_mfma_f32_16x16x32_bf16 v[52:55], v[20:23], v[60:63], v[52:55]
	v_mfma_f32_16x16x32_bf16 v[56:59], v[28:31], v[60:63], v[56:59]
	s_barrier
	s_setprio 0
	s_add_i32 s70, s4, s97
	s_add_i32 s4, s70, 0x2000
	s_mov_b32 m0, s70
	s_add_u32 s74, s36, 0x80100
	ds_read_b128 v[60:63], v135 offset:16384
	ds_read_b128 v[100:103], v135 offset:17408
	ds_read_b128 v[104:107], v135 offset:18432
	ds_read_b128 v[108:111], v135 offset:19456
	ds_read_b128 v[112:115], v135 offset:20480
	ds_read_b128 v[116:119], v135 offset:21504
	ds_read_b128 v[120:123], v135 offset:22528
	ds_read_b128 v[124:127], v135 offset:23552
	s_addc_u32 s75, s37, 0
	global_load_lds_dwordx4 v132, s[82:83]
	s_mov_b32 m0, s4
	s_add_i32 s13, s13, s97
	s_add_i32 s15, s13, 0x2000
	global_load_lds_dwordx4 v130, s[82:83]
	s_mov_b32 m0, s13
	s_nop 0
	global_load_lds_dwordx4 v132, s[74:75]
	s_mov_b32 m0, s15
	s_nop 0
	global_load_lds_dwordx4 v130, s[74:75]
	s_mov_b32 m0, s25
	s_nop 0
	global_load_lds_dwordx4 v133, s[56:57]
	s_mov_b32 m0, s27
	s_nop 0
	global_load_lds_dwordx4 v131, s[56:57]
	s_waitcnt vmcnt(8) lgkmcnt(0)
	s_setprio 1
	s_barrier
	v_mfma_f32_16x16x32_bf16 v[136:139], v[0:3], v[60:63], 0
	v_mfma_f32_16x16x32_bf16 v[144:147], v[0:3], v[104:107], 0
	v_mfma_f32_16x16x32_bf16 v[152:155], v[0:3], v[112:115], 0
	v_mfma_f32_16x16x32_bf16 v[0:3], v[0:3], v[120:123], 0
	v_mfma_f32_16x16x32_bf16 v[136:139], v[4:7], v[100:103], v[136:139]
	v_mfma_f32_16x16x32_bf16 v[144:147], v[4:7], v[108:111], v[144:147]
	v_mfma_f32_16x16x32_bf16 v[152:155], v[4:7], v[116:119], v[152:155]
	v_mfma_f32_16x16x32_bf16 v[0:3], v[4:7], v[124:127], v[0:3]
	v_mfma_f32_16x16x32_bf16 v[4:7], v[8:11], v[120:123], 0
	v_mfma_f32_16x16x32_bf16 v[140:143], v[8:11], v[60:63], 0
	v_mfma_f32_16x16x32_bf16 v[148:151], v[8:11], v[104:107], 0
	v_mfma_f32_16x16x32_bf16 v[156:159], v[8:11], v[112:115], 0
	v_mfma_f32_16x16x32_bf16 v[4:7], v[12:15], v[124:127], v[4:7]
	v_mfma_f32_16x16x32_bf16 v[140:143], v[12:15], v[100:103], v[140:143]
	v_mfma_f32_16x16x32_bf16 v[148:151], v[12:15], v[108:111], v[148:151]
	v_mfma_f32_16x16x32_bf16 v[156:159], v[12:15], v[116:119], v[156:159]
	v_mfma_f32_16x16x32_bf16 v[8:11], v[16:19], v[60:63], 0
	v_mfma_f32_16x16x32_bf16 v[12:15], v[24:27], v[60:63], 0
	v_mfma_f32_16x16x32_bf16 v[8:11], v[20:23], v[100:103], v[8:11]
	v_mfma_f32_16x16x32_bf16 v[12:15], v[28:31], v[100:103], v[12:15]
	v_mfma_f32_16x16x32_bf16 v[60:63], v[16:19], v[104:107], 0
	v_mfma_f32_16x16x32_bf16 v[100:103], v[24:27], v[104:107], 0
	v_mfma_f32_16x16x32_bf16 v[104:107], v[16:19], v[112:115], 0
	v_mfma_f32_16x16x32_bf16 v[16:19], v[16:19], v[120:123], 0
	v_mfma_f32_16x16x32_bf16 v[60:63], v[20:23], v[108:111], v[60:63]
	v_mfma_f32_16x16x32_bf16 v[100:103], v[28:31], v[108:111], v[100:103]
	v_mfma_f32_16x16x32_bf16 v[104:107], v[20:23], v[116:119], v[104:107]
	v_mfma_f32_16x16x32_bf16 v[108:111], v[24:27], v[112:115], 0
	v_mfma_f32_16x16x32_bf16 v[16:19], v[20:23], v[124:127], v[16:19]
	v_mfma_f32_16x16x32_bf16 v[20:23], v[24:27], v[120:123], 0
	v_mfma_f32_16x16x32_bf16 v[108:111], v[28:31], v[116:119], v[108:111]
	v_mfma_f32_16x16x32_bf16 v[20:23], v[28:31], v[124:127], v[20:23]
	s_barrier
	s_setprio 0
	s_add_i32 s71, 0, 0x18000
	s_add_i32 s69, 0, 0x1c000
	v_add_u32_e32 v196, s71, v134
	v_add_u32_e32 v198, s69, v134
	ds_read_b128 v[24:27], v196
	ds_read_b128 v[28:31], v196 offset:1024
	ds_read_b128 v[112:115], v196 offset:2048
	ds_read_b128 v[116:119], v196 offset:3072
	ds_read_b128 v[120:123], v198
	ds_read_b128 v[124:127], v198 offset:1024
	ds_read_b128 v[160:163], v198 offset:2048
	ds_read_b128 v[164:167], v198 offset:3072
	s_add_u32 s56, s30, 0x10100
	s_addc_u32 s57, s31, 0
	s_mov_b32 m0, s29
	ds_read_b128 v[168:171], v135 offset:32768
	ds_read_b128 v[172:175], v135 offset:33792
	ds_read_b128 v[176:179], v135 offset:34816
	ds_read_b128 v[180:183], v135 offset:35840
	ds_read_b128 v[184:187], v135 offset:36864
	ds_read_b128 v[188:191], v135 offset:37888
	ds_read_b128 v[192:195], v135 offset:38912
	ds_read_b128 v[200:203], v135 offset:39936
	s_nop 0
	global_load_lds_dwordx4 v133, s[56:57]
	s_mov_b32 m0, s47
	s_nop 0
	global_load_lds_dwordx4 v131, s[56:57]
	s_waitcnt vmcnt(8) lgkmcnt(0)
	s_setprio 1
	s_barrier
	v_mfma_f32_16x16x32_bf16 v[64:67], v[24:27], v[168:171], v[64:67]
	v_mfma_f32_16x16x32_bf16 v[64:67], v[28:31], v[172:175], v[64:67]
	v_mfma_f32_16x16x32_bf16 v[68:71], v[112:115], v[168:171], v[68:71]
	v_mfma_f32_16x16x32_bf16 v[68:71], v[116:119], v[172:175], v[68:71]
	v_mfma_f32_16x16x32_bf16 v[72:75], v[24:27], v[176:179], v[72:75]
	v_mfma_f32_16x16x32_bf16 v[72:75], v[28:31], v[180:183], v[72:75]
	v_mfma_f32_16x16x32_bf16 v[76:79], v[112:115], v[176:179], v[76:79]
	v_mfma_f32_16x16x32_bf16 v[76:79], v[116:119], v[180:183], v[76:79]
	v_mfma_f32_16x16x32_bf16 v[80:83], v[24:27], v[184:187], v[80:83]
	v_mfma_f32_16x16x32_bf16 v[80:83], v[28:31], v[188:191], v[80:83]
	v_mfma_f32_16x16x32_bf16 v[84:87], v[112:115], v[184:187], v[84:87]
	v_mfma_f32_16x16x32_bf16 v[84:87], v[116:119], v[188:191], v[84:87]
	v_mfma_f32_16x16x32_bf16 v[88:91], v[24:27], v[192:195], v[88:91]
	v_mfma_f32_16x16x32_bf16 v[88:91], v[28:31], v[200:203], v[88:91]
	v_mfma_f32_16x16x32_bf16 v[92:95], v[112:115], v[192:195], v[92:95]
	v_mfma_f32_16x16x32_bf16 v[92:95], v[116:119], v[200:203], v[92:95]
	v_mfma_f32_16x16x32_bf16 v[96:99], v[120:123], v[168:171], v[96:99]
	v_mfma_f32_16x16x32_bf16 v[96:99], v[124:127], v[172:175], v[96:99]
	v_mfma_f32_16x16x32_bf16 v[32:35], v[160:163], v[168:171], v[32:35]
	v_mfma_f32_16x16x32_bf16 v[32:35], v[164:167], v[172:175], v[32:35]
	v_mfma_f32_16x16x32_bf16 v[36:39], v[120:123], v[176:179], v[36:39]
	v_mfma_f32_16x16x32_bf16 v[36:39], v[124:127], v[180:183], v[36:39]
	v_mfma_f32_16x16x32_bf16 v[40:43], v[160:163], v[176:179], v[40:43]
	v_mfma_f32_16x16x32_bf16 v[40:43], v[164:167], v[180:183], v[40:43]
	v_mfma_f32_16x16x32_bf16 v[44:47], v[120:123], v[184:187], v[44:47]
	v_mfma_f32_16x16x32_bf16 v[44:47], v[124:127], v[188:191], v[44:47]
	v_mfma_f32_16x16x32_bf16 v[48:51], v[160:163], v[184:187], v[48:51]
	v_mfma_f32_16x16x32_bf16 v[48:51], v[164:167], v[188:191], v[48:51]
	v_mfma_f32_16x16x32_bf16 v[52:55], v[120:123], v[192:195], v[52:55]
	v_mfma_f32_16x16x32_bf16 v[52:55], v[124:127], v[200:203], v[52:55]
	v_mfma_f32_16x16x32_bf16 v[56:59], v[160:163], v[192:195], v[56:59]
	v_mfma_f32_16x16x32_bf16 v[56:59], v[164:167], v[200:203], v[56:59]
	s_barrier
	s_setprio 0
	s_add_u32 s74, s36, 0x180
	s_addc_u32 s75, s37, 0
	s_add_i32 s71, s71, s97
	s_add_i32 s56, s71, 0x2000
	s_mov_b32 m0, s71
	s_add_u32 s36, s36, 0x80180
	ds_read_b128 v[168:171], v135 offset:49152
	ds_read_b128 v[172:175], v135 offset:50176
	ds_read_b128 v[176:179], v135 offset:51200
	ds_read_b128 v[180:183], v135 offset:52224
	ds_read_b128 v[184:187], v135 offset:53248
	ds_read_b128 v[188:191], v135 offset:54272
	ds_read_b128 v[192:195], v135 offset:55296
	ds_read_b128 v[200:203], v135 offset:56320
	s_addc_u32 s37, s37, 0
	global_load_lds_dwordx4 v132, s[74:75]
	s_mov_b32 m0, s56
	s_add_i32 s57, s69, s97
	s_add_i32 s69, s57, 0x2000
	global_load_lds_dwordx4 v130, s[74:75]
	s_mov_b32 m0, s57
	s_nop 0
	global_load_lds_dwordx4 v132, s[36:37]
	s_mov_b32 m0, s69
	s_nop 0
	global_load_lds_dwordx4 v130, s[36:37]
	s_mov_b32 m0, s48
	s_nop 0
	global_load_lds_dwordx4 v133, s[80:81]
	s_mov_b32 m0, s49
	s_nop 0
	global_load_lds_dwordx4 v131, s[80:81]
	s_waitcnt vmcnt(8) lgkmcnt(0)
	s_setprio 1
	s_barrier
	v_mfma_f32_16x16x32_bf16 v[0:3], v[24:27], v[192:195], v[0:3]
	v_mfma_f32_16x16x32_bf16 v[0:3], v[28:31], v[200:203], v[0:3]
	v_mfma_f32_16x16x32_bf16 v[4:7], v[112:115], v[192:195], v[4:7]
	v_mfma_f32_16x16x32_bf16 v[4:7], v[116:119], v[200:203], v[4:7]
	v_mfma_f32_16x16x32_bf16 v[136:139], v[24:27], v[168:171], v[136:139]
	v_mfma_f32_16x16x32_bf16 v[136:139], v[28:31], v[172:175], v[136:139]
	v_mfma_f32_16x16x32_bf16 v[140:143], v[112:115], v[168:171], v[140:143]
	v_mfma_f32_16x16x32_bf16 v[140:143], v[116:119], v[172:175], v[140:143]
	v_mfma_f32_16x16x32_bf16 v[144:147], v[24:27], v[176:179], v[144:147]
	v_mfma_f32_16x16x32_bf16 v[144:147], v[28:31], v[180:183], v[144:147]
	v_mfma_f32_16x16x32_bf16 v[148:151], v[112:115], v[176:179], v[148:151]
	v_mfma_f32_16x16x32_bf16 v[148:151], v[116:119], v[180:183], v[148:151]
	v_mfma_f32_16x16x32_bf16 v[152:155], v[24:27], v[184:187], v[152:155]
	v_mfma_f32_16x16x32_bf16 v[152:155], v[28:31], v[188:191], v[152:155]
	v_mfma_f32_16x16x32_bf16 v[156:159], v[112:115], v[184:187], v[156:159]
	v_mfma_f32_16x16x32_bf16 v[156:159], v[116:119], v[188:191], v[156:159]
	v_mfma_f32_16x16x32_bf16 v[8:11], v[120:123], v[168:171], v[8:11]
	v_mfma_f32_16x16x32_bf16 v[12:15], v[160:163], v[168:171], v[12:15]
	v_mfma_f32_16x16x32_bf16 v[24:27], v[120:123], v[176:179], v[60:63]
	v_mfma_f32_16x16x32_bf16 v[28:31], v[160:163], v[176:179], v[100:103]
	v_mfma_f32_16x16x32_bf16 v[60:63], v[120:123], v[184:187], v[104:107]
	v_mfma_f32_16x16x32_bf16 v[100:103], v[160:163], v[184:187], v[108:111]
	v_mfma_f32_16x16x32_bf16 v[16:19], v[120:123], v[192:195], v[16:19]
	v_mfma_f32_16x16x32_bf16 v[20:23], v[160:163], v[192:195], v[20:23]
	v_mfma_f32_16x16x32_bf16 v[8:11], v[124:127], v[172:175], v[8:11]
	v_mfma_f32_16x16x32_bf16 v[12:15], v[164:167], v[172:175], v[12:15]
	v_mfma_f32_16x16x32_bf16 v[24:27], v[124:127], v[180:183], v[24:27]
	v_mfma_f32_16x16x32_bf16 v[28:31], v[164:167], v[180:183], v[28:31]
	v_mfma_f32_16x16x32_bf16 v[60:63], v[124:127], v[188:191], v[60:63]
	v_mfma_f32_16x16x32_bf16 v[100:103], v[164:167], v[188:191], v[100:103]
	v_mfma_f32_16x16x32_bf16 v[16:19], v[124:127], v[200:203], v[16:19]
	v_mfma_f32_16x16x32_bf16 v[20:23], v[164:167], v[200:203], v[20:23]
	s_barrier
	s_setprio 0
	ds_read_b128 v[104:107], v128
	ds_read_b128 v[108:111], v128 offset:1024
	ds_read_b128 v[112:115], v128 offset:2048
	ds_read_b128 v[116:119], v128 offset:3072
	ds_read_b128 v[120:123], v129
	ds_read_b128 v[124:127], v129 offset:1024
	ds_read_b128 v[160:163], v129 offset:2048
	ds_read_b128 v[164:167], v129 offset:3072
	s_add_u32 s36, s38, 0x80
	s_addc_u32 s37, s39, 0
	s_add_u32 s30, s30, 0x10180
	s_addc_u32 s31, s31, 0
	s_mov_b32 m0, s5
	ds_read_b128 v[168:171], v135
	ds_read_b128 v[172:175], v135 offset:1024
	ds_read_b128 v[176:179], v135 offset:2048
	ds_read_b128 v[180:183], v135 offset:3072
	ds_read_b128 v[184:187], v135 offset:4096
	ds_read_b128 v[188:191], v135 offset:5120
	ds_read_b128 v[192:195], v135 offset:6144
	ds_read_b128 v[200:203], v135 offset:7168
	s_nop 0
	global_load_lds_dwordx4 v133, s[30:31]
	s_mov_b32 m0, s11
	s_nop 0
	global_load_lds_dwordx4 v131, s[30:31]
	s_waitcnt vmcnt(8) lgkmcnt(0)
	s_setprio 1
	s_barrier
	v_mfma_f32_16x16x32_bf16 v[64:67], v[104:107], v[168:171], v[64:67]
	v_mfma_f32_16x16x32_bf16 v[64:67], v[108:111], v[172:175], v[64:67]
	v_mfma_f32_16x16x32_bf16 v[68:71], v[112:115], v[168:171], v[68:71]
	v_mfma_f32_16x16x32_bf16 v[68:71], v[116:119], v[172:175], v[68:71]
	v_mfma_f32_16x16x32_bf16 v[72:75], v[104:107], v[176:179], v[72:75]
	v_mfma_f32_16x16x32_bf16 v[72:75], v[108:111], v[180:183], v[72:75]
	v_mfma_f32_16x16x32_bf16 v[76:79], v[112:115], v[176:179], v[76:79]
	v_mfma_f32_16x16x32_bf16 v[76:79], v[116:119], v[180:183], v[76:79]
	v_mfma_f32_16x16x32_bf16 v[80:83], v[104:107], v[184:187], v[80:83]
	v_mfma_f32_16x16x32_bf16 v[80:83], v[108:111], v[188:191], v[80:83]
	v_mfma_f32_16x16x32_bf16 v[84:87], v[112:115], v[184:187], v[84:87]
	v_mfma_f32_16x16x32_bf16 v[84:87], v[116:119], v[188:191], v[84:87]
	v_mfma_f32_16x16x32_bf16 v[88:91], v[104:107], v[192:195], v[88:91]
	v_mfma_f32_16x16x32_bf16 v[88:91], v[108:111], v[200:203], v[88:91]
	v_mfma_f32_16x16x32_bf16 v[92:95], v[112:115], v[192:195], v[92:95]
	v_mfma_f32_16x16x32_bf16 v[92:95], v[116:119], v[200:203], v[92:95]
	v_mfma_f32_16x16x32_bf16 v[32:35], v[160:163], v[168:171], v[32:35]
	v_mfma_f32_16x16x32_bf16 v[96:99], v[120:123], v[168:171], v[96:99]
	v_mfma_f32_16x16x32_bf16 v[168:171], v[164:167], v[172:175], v[32:35]
	v_mfma_f32_16x16x32_bf16 v[32:35], v[120:123], v[176:179], v[36:39]
	v_mfma_f32_16x16x32_bf16 v[36:39], v[124:127], v[180:183], v[32:35]
	v_mfma_f32_16x16x32_bf16 v[32:35], v[160:163], v[176:179], v[40:43]
	v_mfma_f32_16x16x32_bf16 v[204:207], v[124:127], v[172:175], v[96:99]
	v_mfma_f32_16x16x32_bf16 v[172:175], v[164:167], v[180:183], v[32:35]
	v_mfma_f32_16x16x32_bf16 v[32:35], v[120:123], v[184:187], v[44:47]
	v_mfma_f32_16x16x32_bf16 v[44:47], v[124:127], v[188:191], v[32:35]
	v_mfma_f32_16x16x32_bf16 v[32:35], v[160:163], v[184:187], v[48:51]
	v_mfma_f32_16x16x32_bf16 v[48:51], v[164:167], v[188:191], v[32:35]
	v_mfma_f32_16x16x32_bf16 v[32:35], v[120:123], v[192:195], v[52:55]
	v_mfma_f32_16x16x32_bf16 v[52:55], v[124:127], v[200:203], v[32:35]
	v_mfma_f32_16x16x32_bf16 v[32:35], v[160:163], v[192:195], v[56:59]
	v_mfma_f32_16x16x32_bf16 v[56:59], v[164:167], v[200:203], v[32:35]
	s_barrier
	s_setprio 0
	s_mov_b32 m0, s70
	s_mov_b64 s[30:31], s[34:35]
	s_nop 2
	ds_read_b128 v[32:35], v135 offset:16384
	ds_read_b128 v[40:43], v135 offset:17408
	ds_read_b128 v[96:99], v135 offset:18432
	ds_read_b128 v[176:179], v135 offset:19456
	ds_read_b128 v[180:183], v135 offset:20480
	ds_read_b128 v[184:187], v135 offset:21504
	ds_read_b128 v[188:191], v135 offset:22528
	ds_read_b128 v[192:195], v135 offset:23552
	s_nop 0
	global_load_lds_dwordx4 v132, s[30:31]
	s_mov_b32 m0, s4
	s_add_u32 s4, s34, 0x80000
	s_addc_u32 s5, s35, 0
	global_load_lds_dwordx4 v130, s[30:31]
	s_mov_b32 m0, s13
	s_nop 0
	global_load_lds_dwordx4 v132, s[4:5]
	s_mov_b32 m0, s15
	s_nop 0
	global_load_lds_dwordx4 v130, s[4:5]
	s_mov_b64 s[4:5], s[38:39]
	s_mov_b32 m0, s25
	s_nop 0
	global_load_lds_dwordx4 v133, s[4:5]
	s_mov_b32 m0, s27
	s_nop 0
	global_load_lds_dwordx4 v131, s[4:5]
	s_waitcnt vmcnt(8) lgkmcnt(0)
	s_setprio 1
	s_barrier
	v_mfma_f32_16x16x32_bf16 v[0:3], v[104:107], v[188:191], v[0:3]
	v_mfma_f32_16x16x32_bf16 v[0:3], v[108:111], v[192:195], v[0:3]
	v_mfma_f32_16x16x32_bf16 v[4:7], v[112:115], v[188:191], v[4:7]
	v_mfma_f32_16x16x32_bf16 v[4:7], v[116:119], v[192:195], v[4:7]
	v_mfma_f32_16x16x32_bf16 v[136:139], v[104:107], v[32:35], v[136:139]
	v_mfma_f32_16x16x32_bf16 v[136:139], v[108:111], v[40:43], v[136:139]
	v_mfma_f32_16x16x32_bf16 v[140:143], v[112:115], v[32:35], v[140:143]
	v_mfma_f32_16x16x32_bf16 v[140:143], v[116:119], v[40:43], v[140:143]
	v_mfma_f32_16x16x32_bf16 v[144:147], v[104:107], v[96:99], v[144:147]
	v_mfma_f32_16x16x32_bf16 v[144:147], v[108:111], v[176:179], v[144:147]
	v_mfma_f32_16x16x32_bf16 v[148:151], v[112:115], v[96:99], v[148:151]
	v_mfma_f32_16x16x32_bf16 v[148:151], v[116:119], v[176:179], v[148:151]
	v_mfma_f32_16x16x32_bf16 v[152:155], v[104:107], v[180:183], v[152:155]
	v_mfma_f32_16x16x32_bf16 v[152:155], v[108:111], v[184:187], v[152:155]
	v_mfma_f32_16x16x32_bf16 v[156:159], v[112:115], v[180:183], v[156:159]
	v_mfma_f32_16x16x32_bf16 v[156:159], v[116:119], v[184:187], v[156:159]
	v_mfma_f32_16x16x32_bf16 v[12:15], v[160:163], v[32:35], v[12:15]
	v_mfma_f32_16x16x32_bf16 v[200:203], v[164:167], v[40:43], v[12:15]
	v_mfma_f32_16x16x32_bf16 v[12:15], v[120:123], v[96:99], v[24:27]
	v_mfma_f32_16x16x32_bf16 v[24:27], v[124:127], v[176:179], v[12:15]
	v_mfma_f32_16x16x32_bf16 v[12:15], v[160:163], v[96:99], v[28:31]
	v_mfma_f32_16x16x32_bf16 v[176:179], v[164:167], v[176:179], v[12:15]
	v_mfma_f32_16x16x32_bf16 v[12:15], v[120:123], v[180:183], v[60:63]
	v_mfma_f32_16x16x32_bf16 v[208:211], v[124:127], v[184:187], v[12:15]
	v_mfma_f32_16x16x32_bf16 v[12:15], v[160:163], v[180:183], v[100:103]
	v_mfma_f32_16x16x32_bf16 v[8:11], v[120:123], v[32:35], v[8:11]
	v_mfma_f32_16x16x32_bf16 v[180:183], v[164:167], v[184:187], v[12:15]
	v_mfma_f32_16x16x32_bf16 v[12:15], v[120:123], v[188:191], v[16:19]
	v_mfma_f32_16x16x32_bf16 v[8:11], v[124:127], v[40:43], v[8:11]
	v_mfma_f32_16x16x32_bf16 v[184:187], v[124:127], v[192:195], v[12:15]
	v_mfma_f32_16x16x32_bf16 v[12:15], v[160:163], v[188:191], v[20:23]
	v_mfma_f32_16x16x32_bf16 v[160:163], v[164:167], v[192:195], v[12:15]
	s_barrier
	s_setprio 0
	s_nop 4
	ds_read_b128 v[12:15], v196
	ds_read_b128 v[16:19], v196 offset:1024
	ds_read_b128 v[164:167], v196 offset:2048
	ds_read_b128 v[188:191], v196 offset:3072
	ds_read_b128 v[192:195], v198
	ds_read_b128 v[220:223], v198 offset:1024
	ds_read_b128 v[224:227], v198 offset:2048
	ds_read_b128 v[228:231], v198 offset:3072
	s_add_u32 s4, s38, 0x10000
	s_addc_u32 s5, s39, 0
	s_mov_b32 m0, s29
	ds_read_b128 v[20:23], v135 offset:32768
	ds_read_b128 v[28:31], v135 offset:33792
	ds_read_b128 v[60:63], v135 offset:34816
	ds_read_b128 v[100:103], v135 offset:35840
	ds_read_b128 v[232:235], v135 offset:36864
	ds_read_b128 v[236:239], v135 offset:37888
	ds_read_b128 v[240:243], v135 offset:38912
	ds_read_b128 v[244:247], v135 offset:39936
	s_nop 0
	global_load_lds_dwordx4 v133, s[4:5]
	s_mov_b32 m0, s47
	s_nop 0
	global_load_lds_dwordx4 v131, s[4:5]
	s_waitcnt vmcnt(8) lgkmcnt(0)
	s_setprio 1
	s_barrier
	v_mfma_f32_16x16x32_bf16 v[32:35], v[12:15], v[20:23], v[64:67]
	v_mfma_f32_16x16x32_bf16 v[120:123], v[16:19], v[28:31], v[32:35]
	v_mfma_f32_16x16x32_bf16 v[32:35], v[164:167], v[20:23], v[68:71]
	v_mfma_f32_16x16x32_bf16 v[112:115], v[188:191], v[28:31], v[32:35]
	v_mfma_f32_16x16x32_bf16 v[32:35], v[12:15], v[60:63], v[72:75]
	v_mfma_f32_16x16x32_bf16 v[104:107], v[16:19], v[100:103], v[32:35]
	v_mfma_f32_16x16x32_bf16 v[32:35], v[164:167], v[60:63], v[76:79]
	v_mfma_f32_16x16x32_bf16 v[96:99], v[188:191], v[100:103], v[32:35]
	v_mfma_f32_16x16x32_bf16 v[32:35], v[12:15], v[232:235], v[80:83]
	v_mfma_f32_16x16x32_bf16 v[72:75], v[16:19], v[236:239], v[32:35]
	v_mfma_f32_16x16x32_bf16 v[32:35], v[164:167], v[232:235], v[84:87]
	v_mfma_f32_16x16x32_bf16 v[64:67], v[188:191], v[236:239], v[32:35]
	v_mfma_f32_16x16x32_bf16 v[32:35], v[12:15], v[240:243], v[88:91]
	v_mfma_f32_16x16x32_bf16 v[40:43], v[16:19], v[244:247], v[32:35]
	v_mfma_f32_16x16x32_bf16 v[32:35], v[164:167], v[240:243], v[92:95]
	v_mfma_f32_16x16x32_bf16 v[32:35], v[188:191], v[244:247], v[32:35]
	v_mfma_f32_16x16x32_bf16 v[68:71], v[192:195], v[20:23], v[204:207]
	v_mfma_f32_16x16x32_bf16 v[20:23], v[224:227], v[20:23], v[168:171]
	v_mfma_f32_16x16x32_bf16 v[116:119], v[228:231], v[28:31], v[20:23]
	v_mfma_f32_16x16x32_bf16 v[20:23], v[192:195], v[60:63], v[36:39]
	v_mfma_f32_16x16x32_bf16 v[108:111], v[220:223], v[100:103], v[20:23]
	v_mfma_f32_16x16x32_bf16 v[20:23], v[224:227], v[60:63], v[172:175]
	v_mfma_f32_16x16x32_bf16 v[100:103], v[228:231], v[100:103], v[20:23]
	v_mfma_f32_16x16x32_bf16 v[20:23], v[192:195], v[232:235], v[44:47]
	v_mfma_f32_16x16x32_bf16 v[76:79], v[220:223], v[236:239], v[20:23]
	v_mfma_f32_16x16x32_bf16 v[20:23], v[224:227], v[232:235], v[48:51]
	v_mfma_f32_16x16x32_bf16 v[124:127], v[220:223], v[28:31], v[68:71]
	v_mfma_f32_16x16x32_bf16 v[68:71], v[228:231], v[236:239], v[20:23]
	v_mfma_f32_16x16x32_bf16 v[20:23], v[192:195], v[240:243], v[52:55]
	v_mfma_f32_16x16x32_bf16 v[44:47], v[220:223], v[244:247], v[20:23]
	v_mfma_f32_16x16x32_bf16 v[20:23], v[224:227], v[240:243], v[56:59]
	v_mfma_f32_16x16x32_bf16 v[36:39], v[228:231], v[244:247], v[20:23]
	s_barrier
	s_setprio 0
	s_add_u32 s4, s34, 0x80
	s_mov_b32 m0, s71
	s_addc_u32 s5, s35, 0
	ds_read_b128 v[48:51], v135 offset:49152
	ds_read_b128 v[56:59], v135 offset:50176
	ds_read_b128 v[168:171], v135 offset:51200
	ds_read_b128 v[172:175], v135 offset:52224
	ds_read_b128 v[204:207], v135 offset:53248
	ds_read_b128 v[232:235], v135 offset:54272
	ds_read_b128 v[236:239], v135 offset:55296
	ds_read_b128 v[240:243], v135 offset:56320
	s_nop 0
	global_load_lds_dwordx4 v132, s[4:5]
	s_mov_b32 m0, s56
	s_nop 0
	global_load_lds_dwordx4 v130, s[4:5]
	s_add_u32 s4, s34, 0x80080
	s_addc_u32 s5, s35, 0
	s_mov_b32 m0, s57
	s_nop 0
	global_load_lds_dwordx4 v132, s[4:5]
	s_mov_b32 m0, s69
	s_nop 0
	global_load_lds_dwordx4 v130, s[4:5]
	s_mov_b32 m0, s48
	s_nop 0
	global_load_lds_dwordx4 v133, s[36:37]
	s_mov_b32 m0, s49
	s_nop 0
	global_load_lds_dwordx4 v131, s[36:37]
	s_waitcnt vmcnt(8) lgkmcnt(0)
	s_setprio 1
	s_barrier
	v_mfma_f32_16x16x32_bf16 v[20:23], v[12:15], v[48:51], v[136:139]
	v_mfma_f32_16x16x32_bf16 v[92:95], v[16:19], v[56:59], v[20:23]
	v_mfma_f32_16x16x32_bf16 v[20:23], v[164:167], v[48:51], v[140:143]
	v_mfma_f32_16x16x32_bf16 v[84:87], v[188:191], v[56:59], v[20:23]
	v_mfma_f32_16x16x32_bf16 v[20:23], v[12:15], v[168:171], v[144:147]
	v_mfma_f32_16x16x32_bf16 v[60:63], v[16:19], v[172:175], v[20:23]
	v_mfma_f32_16x16x32_bf16 v[20:23], v[164:167], v[168:171], v[148:151]
	v_mfma_f32_16x16x32_bf16 v[52:55], v[188:191], v[172:175], v[20:23]
	v_mfma_f32_16x16x32_bf16 v[20:23], v[12:15], v[204:207], v[152:155]
	v_mfma_f32_16x16x32_bf16 v[0:3], v[12:15], v[236:239], v[0:3]
	v_mfma_f32_16x16x32_bf16 v[28:31], v[16:19], v[232:235], v[20:23]
	v_mfma_f32_16x16x32_bf16 v[20:23], v[164:167], v[204:207], v[156:159]
	v_mfma_f32_16x16x32_bf16 v[12:15], v[16:19], v[240:243], v[0:3]
	v_mfma_f32_16x16x32_bf16 v[0:3], v[164:167], v[236:239], v[4:7]
	v_mfma_f32_16x16x32_bf16 v[20:23], v[188:191], v[232:235], v[20:23]
	v_mfma_f32_16x16x32_bf16 v[4:7], v[188:191], v[240:243], v[0:3]
	v_mfma_f32_16x16x32_bf16 v[0:3], v[192:195], v[48:51], v[8:11]
	v_mfma_f32_16x16x32_bf16 v[88:91], v[220:223], v[56:59], v[0:3]
	v_mfma_f32_16x16x32_bf16 v[0:3], v[224:227], v[48:51], v[200:203]
	v_mfma_f32_16x16x32_bf16 v[80:83], v[228:231], v[56:59], v[0:3]
	v_mfma_f32_16x16x32_bf16 v[0:3], v[192:195], v[168:171], v[24:27]
	v_mfma_f32_16x16x32_bf16 v[56:59], v[220:223], v[172:175], v[0:3]
	v_mfma_f32_16x16x32_bf16 v[0:3], v[224:227], v[168:171], v[176:179]
	v_mfma_f32_16x16x32_bf16 v[48:51], v[228:231], v[172:175], v[0:3]
	v_mfma_f32_16x16x32_bf16 v[0:3], v[192:195], v[204:207], v[208:211]
	v_mfma_f32_16x16x32_bf16 v[24:27], v[220:223], v[232:235], v[0:3]
	v_mfma_f32_16x16x32_bf16 v[0:3], v[224:227], v[204:207], v[180:183]
	v_mfma_f32_16x16x32_bf16 v[16:19], v[228:231], v[232:235], v[0:3]
	v_mfma_f32_16x16x32_bf16 v[0:3], v[192:195], v[236:239], v[184:187]
	v_mfma_f32_16x16x32_bf16 v[8:11], v[220:223], v[240:243], v[0:3]
	v_mfma_f32_16x16x32_bf16 v[0:3], v[224:227], v[236:239], v[160:163]
	v_mfma_f32_16x16x32_bf16 v[0:3], v[228:231], v[240:243], v[0:3]
	s_barrier
	s_setprio 0
	s_andn2_b64 vcc, exec, s[60:61]
	s_cbranch_vccnz .LBB0_315
	s_barrier

.LBB0_380:
	s_cmp_eq_u32 s15, 28
	s_cselect_b32 s36, s20, s4
	s_cselect_b32 s37, s21, s5
	s_cselect_b32 s34, s26, s11
	s_cselect_b32 s35, s27, s13
	s_add_u32 s30, s36, 0x80
	s_addc_u32 s31, s37, 0
	s_add_i32 s17, 0, 0x10000
	v_add_u32_e32 v128, s17, v134
	s_add_i32 s69, 0, 0x14000
	ds_read_b128 v[136:139], v128
	ds_read_b128 v[140:143], v128 offset:1024
	ds_read_b128 v[144:147], v128 offset:2048
	ds_read_b128 v[148:151], v128 offset:3072
	v_add_u32_e32 v128, s69, v134
	ds_read_b128 v[152:155], v128
	ds_read_b128 v[156:159], v128 offset:1024
	ds_read_b128 v[160:163], v128 offset:2048
	ds_read_b128 v[164:167], v128 offset:3072
	s_mov_b64 s[70:71], s[28:29]
	s_add_i32 m0, s23, 0xc000
	ds_read_b128 v[168:171], v135
	ds_read_b128 v[172:175], v135 offset:1024
	ds_read_b128 v[176:179], v135 offset:2048
	ds_read_b128 v[180:183], v135 offset:3072
	ds_read_b128 v[184:187], v135 offset:4096
	ds_read_b128 v[188:191], v135 offset:5120
	ds_read_b128 v[192:195], v135 offset:6144
	ds_read_b128 v[200:203], v135 offset:7168
	s_nop 0
	global_load_lds_dwordx4 v133, s[70:71]
	s_add_i32 m0, s23, 0xe000
	s_nop 0
	global_load_lds_dwordx4 v131, s[70:71]
	s_waitcnt vmcnt(8) lgkmcnt(0)
	s_setprio 1
	s_barrier
	v_mfma_f32_16x16x32_bf16 v[124:127], v[136:139], v[168:171], v[124:127]
	v_mfma_f32_16x16x32_bf16 v[124:127], v[140:143], v[172:175], v[124:127]
	v_mfma_f32_16x16x32_bf16 v[120:123], v[144:147], v[168:171], v[120:123]
	v_mfma_f32_16x16x32_bf16 v[120:123], v[148:151], v[172:175], v[120:123]
	v_mfma_f32_16x16x32_bf16 v[116:119], v[136:139], v[176:179], v[116:119]
	v_mfma_f32_16x16x32_bf16 v[116:119], v[140:143], v[180:183], v[116:119]
	v_mfma_f32_16x16x32_bf16 v[108:111], v[144:147], v[176:179], v[108:111]
	v_mfma_f32_16x16x32_bf16 v[108:111], v[148:151], v[180:183], v[108:111]
	v_mfma_f32_16x16x32_bf16 v[100:103], v[136:139], v[184:187], v[100:103]
	v_mfma_f32_16x16x32_bf16 v[100:103], v[140:143], v[188:191], v[100:103]
	v_mfma_f32_16x16x32_bf16 v[92:95], v[144:147], v[184:187], v[92:95]
	v_mfma_f32_16x16x32_bf16 v[92:95], v[148:151], v[188:191], v[92:95]
	v_mfma_f32_16x16x32_bf16 v[84:87], v[136:139], v[192:195], v[84:87]
	v_mfma_f32_16x16x32_bf16 v[84:87], v[140:143], v[200:203], v[84:87]
	v_mfma_f32_16x16x32_bf16 v[76:79], v[144:147], v[192:195], v[76:79]
	v_mfma_f32_16x16x32_bf16 v[76:79], v[148:151], v[200:203], v[76:79]
	v_mfma_f32_16x16x32_bf16 v[112:115], v[152:155], v[168:171], v[112:115]
	v_mfma_f32_16x16x32_bf16 v[112:115], v[156:159], v[172:175], v[112:115]
	v_mfma_f32_16x16x32_bf16 v[104:107], v[160:163], v[168:171], v[104:107]
	v_mfma_f32_16x16x32_bf16 v[104:107], v[164:167], v[172:175], v[104:107]
	v_mfma_f32_16x16x32_bf16 v[96:99], v[152:155], v[176:179], v[96:99]
	v_mfma_f32_16x16x32_bf16 v[96:99], v[156:159], v[180:183], v[96:99]
	v_mfma_f32_16x16x32_bf16 v[88:91], v[160:163], v[176:179], v[88:91]
	v_mfma_f32_16x16x32_bf16 v[88:91], v[164:167], v[180:183], v[88:91]
	v_mfma_f32_16x16x32_bf16 v[80:83], v[152:155], v[184:187], v[80:83]
	v_mfma_f32_16x16x32_bf16 v[80:83], v[156:159], v[188:191], v[80:83]
	v_mfma_f32_16x16x32_bf16 v[72:75], v[160:163], v[184:187], v[72:75]
	v_mfma_f32_16x16x32_bf16 v[72:75], v[164:167], v[188:191], v[72:75]
	v_mfma_f32_16x16x32_bf16 v[68:71], v[152:155], v[192:195], v[68:71]
	v_mfma_f32_16x16x32_bf16 v[68:71], v[156:159], v[200:203], v[68:71]
	v_mfma_f32_16x16x32_bf16 v[64:67], v[160:163], v[192:195], v[64:67]
	v_mfma_f32_16x16x32_bf16 v[64:67], v[164:167], v[200:203], v[64:67]
	s_barrier
	s_setprio 0
	s_add_i32 s17, s17, s97
	s_mov_b64 s[70:71], s[34:35]
	s_mov_b32 m0, s17
	ds_read_b128 v[168:171], v135 offset:16384
	ds_read_b128 v[172:175], v135 offset:17408
	ds_read_b128 v[176:179], v135 offset:18432
	ds_read_b128 v[180:183], v135 offset:19456
	ds_read_b128 v[184:187], v135 offset:20480
	ds_read_b128 v[188:191], v135 offset:21504
	ds_read_b128 v[192:195], v135 offset:22528
	ds_read_b128 v[200:203], v135 offset:23552
	s_nop 0
	global_load_lds_dwordx4 v132, s[70:71]
	s_add_i32 m0, s17, 0x2000
	s_nop 0
	global_load_lds_dwordx4 v130, s[70:71]
	s_add_u32 s70, s34, 0x200000
	s_addc_u32 s71, s35, 0
	s_add_i32 s17, s69, s97
	s_mov_b32 m0, s17
	s_nop 0
	global_load_lds_dwordx4 v132, s[70:71]
	s_add_i32 m0, s17, 0x2000
	s_nop 0
	global_load_lds_dwordx4 v130, s[70:71]
	s_mov_b64 s[70:71], s[36:37]
	s_mov_b32 m0, s23
	s_nop 0
	global_load_lds_dwordx4 v133, s[70:71]
	s_mov_b32 m0, s25
	s_nop 0
	global_load_lds_dwordx4 v131, s[70:71]
	s_waitcnt vmcnt(8) lgkmcnt(0)
	s_setprio 1
	s_barrier
	v_mfma_f32_16x16x32_bf16 v[60:63], v[136:139], v[168:171], v[60:63]
	v_mfma_f32_16x16x32_bf16 v[60:63], v[140:143], v[172:175], v[60:63]
	v_mfma_f32_16x16x32_bf16 v[56:59], v[144:147], v[168:171], v[56:59]
	v_mfma_f32_16x16x32_bf16 v[56:59], v[148:151], v[172:175], v[56:59]
	v_mfma_f32_16x16x32_bf16 v[52:55], v[136:139], v[176:179], v[52:55]
	v_mfma_f32_16x16x32_bf16 v[52:55], v[140:143], v[180:183], v[52:55]
	v_mfma_f32_16x16x32_bf16 v[44:47], v[144:147], v[176:179], v[44:47]
	v_mfma_f32_16x16x32_bf16 v[44:47], v[148:151], v[180:183], v[44:47]
	v_mfma_f32_16x16x32_bf16 v[36:39], v[136:139], v[184:187], v[36:39]
	v_mfma_f32_16x16x32_bf16 v[36:39], v[140:143], v[188:191], v[36:39]
	v_mfma_f32_16x16x32_bf16 v[28:31], v[144:147], v[184:187], v[28:31]
	v_mfma_f32_16x16x32_bf16 v[28:31], v[148:151], v[188:191], v[28:31]
	v_mfma_f32_16x16x32_bf16 v[20:23], v[136:139], v[192:195], v[20:23]
	v_mfma_f32_16x16x32_bf16 v[20:23], v[140:143], v[200:203], v[20:23]
	v_mfma_f32_16x16x32_bf16 v[12:15], v[144:147], v[192:195], v[12:15]
	v_mfma_f32_16x16x32_bf16 v[12:15], v[148:151], v[200:203], v[12:15]
	v_mfma_f32_16x16x32_bf16 v[48:51], v[152:155], v[168:171], v[48:51]
	v_mfma_f32_16x16x32_bf16 v[48:51], v[156:159], v[172:175], v[48:51]
	v_mfma_f32_16x16x32_bf16 v[40:43], v[160:163], v[168:171], v[40:43]
	v_mfma_f32_16x16x32_bf16 v[40:43], v[164:167], v[172:175], v[40:43]
	v_mfma_f32_16x16x32_bf16 v[32:35], v[152:155], v[176:179], v[32:35]
	v_mfma_f32_16x16x32_bf16 v[32:35], v[156:159], v[180:183], v[32:35]
	v_mfma_f32_16x16x32_bf16 v[24:27], v[160:163], v[176:179], v[24:27]
	v_mfma_f32_16x16x32_bf16 v[24:27], v[164:167], v[180:183], v[24:27]
	v_mfma_f32_16x16x32_bf16 v[16:19], v[152:155], v[184:187], v[16:19]
	v_mfma_f32_16x16x32_bf16 v[16:19], v[156:159], v[188:191], v[16:19]
	v_mfma_f32_16x16x32_bf16 v[8:11], v[160:163], v[184:187], v[8:11]
	v_mfma_f32_16x16x32_bf16 v[8:11], v[164:167], v[188:191], v[8:11]
	v_mfma_f32_16x16x32_bf16 v[4:7], v[152:155], v[192:195], v[4:7]
	v_mfma_f32_16x16x32_bf16 v[4:7], v[156:159], v[200:203], v[4:7]
	v_mfma_f32_16x16x32_bf16 v[0:3], v[160:163], v[192:195], v[0:3]
	v_mfma_f32_16x16x32_bf16 v[0:3], v[164:167], v[200:203], v[0:3]
	s_barrier
	s_setprio 0
	s_add_i32 s17, 0, 0x18000
	v_add_u32_e32 v128, s17, v134
	s_add_i32 s69, 0, 0x1c000
	ds_read_b128 v[136:139], v128
	ds_read_b128 v[140:143], v128 offset:1024
	ds_read_b128 v[144:147], v128 offset:2048
	ds_read_b128 v[148:151], v128 offset:3072
	v_add_u32_e32 v128, s69, v134
	ds_read_b128 v[152:155], v128
	ds_read_b128 v[156:159], v128 offset:1024
	ds_read_b128 v[160:163], v128 offset:2048
	ds_read_b128 v[164:167], v128 offset:3072
	s_add_u32 s36, s36, 0x80000
	s_addc_u32 s37, s37, 0
	s_mov_b32 m0, s46
	ds_read_b128 v[168:171], v135 offset:32768
	ds_read_b128 v[172:175], v135 offset:33792
	ds_read_b128 v[176:179], v135 offset:34816
	ds_read_b128 v[180:183], v135 offset:35840
	ds_read_b128 v[184:187], v135 offset:36864
	ds_read_b128 v[188:191], v135 offset:37888
	ds_read_b128 v[192:195], v135 offset:38912
	ds_read_b128 v[200:203], v135 offset:39936
	s_nop 0
	global_load_lds_dwordx4 v133, s[36:37]
	s_mov_b32 m0, s47
	s_nop 0
	global_load_lds_dwordx4 v131, s[36:37]
	s_waitcnt vmcnt(8) lgkmcnt(0)
	s_setprio 1
	s_barrier
	v_mfma_f32_16x16x32_bf16 v[124:127], v[136:139], v[168:171], v[124:127]
	v_mfma_f32_16x16x32_bf16 v[124:127], v[140:143], v[172:175], v[124:127]
	v_mfma_f32_16x16x32_bf16 v[120:123], v[144:147], v[168:171], v[120:123]
	v_mfma_f32_16x16x32_bf16 v[120:123], v[148:151], v[172:175], v[120:123]
	v_mfma_f32_16x16x32_bf16 v[116:119], v[136:139], v[176:179], v[116:119]
	v_mfma_f32_16x16x32_bf16 v[116:119], v[140:143], v[180:183], v[116:119]
	v_mfma_f32_16x16x32_bf16 v[108:111], v[144:147], v[176:179], v[108:111]
	v_mfma_f32_16x16x32_bf16 v[108:111], v[148:151], v[180:183], v[108:111]
	v_mfma_f32_16x16x32_bf16 v[100:103], v[136:139], v[184:187], v[100:103]
	v_mfma_f32_16x16x32_bf16 v[100:103], v[140:143], v[188:191], v[100:103]
	v_mfma_f32_16x16x32_bf16 v[92:95], v[144:147], v[184:187], v[92:95]
	v_mfma_f32_16x16x32_bf16 v[92:95], v[148:151], v[188:191], v[92:95]
	v_mfma_f32_16x16x32_bf16 v[84:87], v[136:139], v[192:195], v[84:87]
	v_mfma_f32_16x16x32_bf16 v[84:87], v[140:143], v[200:203], v[84:87]
	v_mfma_f32_16x16x32_bf16 v[76:79], v[144:147], v[192:195], v[76:79]
	v_mfma_f32_16x16x32_bf16 v[76:79], v[148:151], v[200:203], v[76:79]
	v_mfma_f32_16x16x32_bf16 v[112:115], v[152:155], v[168:171], v[112:115]
	v_mfma_f32_16x16x32_bf16 v[112:115], v[156:159], v[172:175], v[112:115]
	v_mfma_f32_16x16x32_bf16 v[104:107], v[160:163], v[168:171], v[104:107]
	v_mfma_f32_16x16x32_bf16 v[104:107], v[164:167], v[172:175], v[104:107]
	v_mfma_f32_16x16x32_bf16 v[96:99], v[152:155], v[176:179], v[96:99]
	v_mfma_f32_16x16x32_bf16 v[96:99], v[156:159], v[180:183], v[96:99]
	v_mfma_f32_16x16x32_bf16 v[88:91], v[160:163], v[176:179], v[88:91]
	v_mfma_f32_16x16x32_bf16 v[88:91], v[164:167], v[180:183], v[88:91]
	v_mfma_f32_16x16x32_bf16 v[80:83], v[152:155], v[184:187], v[80:83]
	v_mfma_f32_16x16x32_bf16 v[80:83], v[156:159], v[188:191], v[80:83]
	v_mfma_f32_16x16x32_bf16 v[72:75], v[160:163], v[184:187], v[72:75]
	v_mfma_f32_16x16x32_bf16 v[72:75], v[164:167], v[188:191], v[72:75]
	v_mfma_f32_16x16x32_bf16 v[68:71], v[152:155], v[192:195], v[68:71]
	v_mfma_f32_16x16x32_bf16 v[68:71], v[156:159], v[200:203], v[68:71]
	v_mfma_f32_16x16x32_bf16 v[64:67], v[160:163], v[192:195], v[64:67]
	v_mfma_f32_16x16x32_bf16 v[64:67], v[164:167], v[200:203], v[64:67]
	s_barrier
	s_setprio 0
	s_add_u32 s36, s34, 0x80
	s_addc_u32 s37, s35, 0
	s_add_i32 s17, s17, s97
	s_mov_b32 m0, s17
	ds_read_b128 v[168:171], v135 offset:49152
	ds_read_b128 v[172:175], v135 offset:50176
	ds_read_b128 v[176:179], v135 offset:51200
	ds_read_b128 v[180:183], v135 offset:52224
	ds_read_b128 v[184:187], v135 offset:53248
	ds_read_b128 v[188:191], v135 offset:54272
	ds_read_b128 v[192:195], v135 offset:55296
	ds_read_b128 v[200:203], v135 offset:56320
	s_nop 0
	global_load_lds_dwordx4 v132, s[36:37]
	s_add_i32 m0, s17, 0x2000
	s_add_u32 s34, s34, 0x200080
	s_addc_u32 s35, s35, 0
	s_add_i32 s17, s69, s97
	s_nop 0
	global_load_lds_dwordx4 v130, s[36:37]
	s_mov_b32 m0, s17
	s_nop 0
	global_load_lds_dwordx4 v132, s[34:35]
	s_add_i32 m0, s17, 0x2000
	s_nop 0
	global_load_lds_dwordx4 v130, s[34:35]
	s_mov_b32 m0, s56
	s_nop 0
	global_load_lds_dwordx4 v133, s[30:31]
	s_mov_b32 m0, s57
	s_nop 0
	global_load_lds_dwordx4 v131, s[30:31]
	s_waitcnt vmcnt(8) lgkmcnt(0)
	s_setprio 1
	s_barrier
	v_mfma_f32_16x16x32_bf16 v[60:63], v[136:139], v[168:171], v[60:63]
	v_mfma_f32_16x16x32_bf16 v[60:63], v[140:143], v[172:175], v[60:63]
	v_mfma_f32_16x16x32_bf16 v[56:59], v[144:147], v[168:171], v[56:59]
	v_mfma_f32_16x16x32_bf16 v[56:59], v[148:151], v[172:175], v[56:59]
	v_mfma_f32_16x16x32_bf16 v[52:55], v[136:139], v[176:179], v[52:55]
	v_mfma_f32_16x16x32_bf16 v[52:55], v[140:143], v[180:183], v[52:55]
	v_mfma_f32_16x16x32_bf16 v[44:47], v[144:147], v[176:179], v[44:47]
	v_mfma_f32_16x16x32_bf16 v[44:47], v[148:151], v[180:183], v[44:47]
	v_mfma_f32_16x16x32_bf16 v[36:39], v[136:139], v[184:187], v[36:39]
	v_mfma_f32_16x16x32_bf16 v[36:39], v[140:143], v[188:191], v[36:39]
	v_mfma_f32_16x16x32_bf16 v[28:31], v[144:147], v[184:187], v[28:31]
	v_mfma_f32_16x16x32_bf16 v[28:31], v[148:151], v[188:191], v[28:31]
	v_mfma_f32_16x16x32_bf16 v[20:23], v[136:139], v[192:195], v[20:23]
	v_mfma_f32_16x16x32_bf16 v[20:23], v[140:143], v[200:203], v[20:23]
	v_mfma_f32_16x16x32_bf16 v[12:15], v[144:147], v[192:195], v[12:15]
	v_mfma_f32_16x16x32_bf16 v[12:15], v[148:151], v[200:203], v[12:15]
	v_mfma_f32_16x16x32_bf16 v[48:51], v[152:155], v[168:171], v[48:51]
	v_mfma_f32_16x16x32_bf16 v[48:51], v[156:159], v[172:175], v[48:51]
	v_mfma_f32_16x16x32_bf16 v[40:43], v[160:163], v[168:171], v[40:43]
	v_mfma_f32_16x16x32_bf16 v[40:43], v[164:167], v[172:175], v[40:43]
	v_mfma_f32_16x16x32_bf16 v[32:35], v[152:155], v[176:179], v[32:35]
	v_mfma_f32_16x16x32_bf16 v[32:35], v[156:159], v[180:183], v[32:35]
	v_mfma_f32_16x16x32_bf16 v[24:27], v[160:163], v[176:179], v[24:27]
	v_mfma_f32_16x16x32_bf16 v[24:27], v[164:167], v[180:183], v[24:27]
	v_mfma_f32_16x16x32_bf16 v[16:19], v[152:155], v[184:187], v[16:19]
	v_mfma_f32_16x16x32_bf16 v[16:19], v[156:159], v[188:191], v[16:19]
	v_mfma_f32_16x16x32_bf16 v[8:11], v[160:163], v[184:187], v[8:11]
	v_mfma_f32_16x16x32_bf16 v[8:11], v[164:167], v[188:191], v[8:11]
	v_mfma_f32_16x16x32_bf16 v[4:7], v[152:155], v[192:195], v[4:7]
	v_mfma_f32_16x16x32_bf16 v[4:7], v[156:159], v[200:203], v[4:7]
	v_mfma_f32_16x16x32_bf16 v[0:3], v[160:163], v[192:195], v[0:3]
	v_mfma_f32_16x16x32_bf16 v[0:3], v[164:167], v[200:203], v[0:3]
	s_barrier
	s_setprio 0
	s_add_i32 s15, s15, 2
	s_add_u32 s4, s4, 0x100
	s_addc_u32 s5, s5, 0
	s_add_u32 s11, s11, 0x100
	s_addc_u32 s13, s13, 0
	s_add_u32 s28, s28, 0x100
	s_addc_u32 s29, s29, 0
	s_cmp_gt_u32 s15, 29
	s_cbranch_scc0 .LBB0_380
	s_and_b64 vcc, exec, s[60:61]
	s_cbranch_vccz .LBB0_383
	s_barrier

.LBB0_397:
	s_cmp_eq_u32 s69, 4
	s_cselect_b32 s34, s15, s49
	s_cselect_b32 s35, s5, s56
	s_cselect_b32 s30, s48, s57
	s_cselect_b32 s31, s13, s65
	s_add_u32 s28, s34, 0x80
	s_addc_u32 s29, s35, 0
	s_add_i32 s72, 0, 0x10000
	v_add_u32_e32 v128, s72, v134
	s_add_i32 s74, 0, 0x14000
	ds_read_b128 v[136:139], v128
	ds_read_b128 v[140:143], v128 offset:1024
	ds_read_b128 v[144:147], v128 offset:2048
	ds_read_b128 v[148:151], v128 offset:3072
	v_add_u32_e32 v128, s74, v134
	ds_read_b128 v[152:155], v128
	ds_read_b128 v[156:159], v128 offset:1024
	ds_read_b128 v[160:163], v128 offset:2048
	ds_read_b128 v[164:167], v128 offset:3072
	s_mov_b64 s[70:71], s[26:27]
	s_add_i32 m0, s25, 0xc000
	ds_read_b128 v[168:171], v135
	ds_read_b128 v[172:175], v135 offset:1024
	ds_read_b128 v[176:179], v135 offset:2048
	ds_read_b128 v[180:183], v135 offset:3072
	ds_read_b128 v[184:187], v135 offset:4096
	ds_read_b128 v[188:191], v135 offset:5120
	ds_read_b128 v[192:195], v135 offset:6144
	ds_read_b128 v[200:203], v135 offset:7168
	s_nop 0
	global_load_lds_dwordx4 v133, s[70:71]
	s_add_i32 m0, s25, 0xe000
	s_nop 0
	global_load_lds_dwordx4 v131, s[70:71]
	s_waitcnt vmcnt(8) lgkmcnt(0)
	s_setprio 1
	s_barrier
	v_mfma_f32_16x16x32_bf16 v[124:127], v[136:139], v[168:171], v[124:127]
	v_mfma_f32_16x16x32_bf16 v[124:127], v[140:143], v[172:175], v[124:127]
	v_mfma_f32_16x16x32_bf16 v[120:123], v[144:147], v[168:171], v[120:123]
	v_mfma_f32_16x16x32_bf16 v[120:123], v[148:151], v[172:175], v[120:123]
	v_mfma_f32_16x16x32_bf16 v[116:119], v[136:139], v[176:179], v[116:119]
	v_mfma_f32_16x16x32_bf16 v[116:119], v[140:143], v[180:183], v[116:119]
	v_mfma_f32_16x16x32_bf16 v[108:111], v[144:147], v[176:179], v[108:111]
	v_mfma_f32_16x16x32_bf16 v[108:111], v[148:151], v[180:183], v[108:111]
	v_mfma_f32_16x16x32_bf16 v[100:103], v[136:139], v[184:187], v[100:103]
	v_mfma_f32_16x16x32_bf16 v[100:103], v[140:143], v[188:191], v[100:103]
	v_mfma_f32_16x16x32_bf16 v[92:95], v[144:147], v[184:187], v[92:95]
	v_mfma_f32_16x16x32_bf16 v[92:95], v[148:151], v[188:191], v[92:95]
	v_mfma_f32_16x16x32_bf16 v[84:87], v[136:139], v[192:195], v[84:87]
	v_mfma_f32_16x16x32_bf16 v[84:87], v[140:143], v[200:203], v[84:87]
	v_mfma_f32_16x16x32_bf16 v[76:79], v[144:147], v[192:195], v[76:79]
	v_mfma_f32_16x16x32_bf16 v[76:79], v[148:151], v[200:203], v[76:79]
	v_mfma_f32_16x16x32_bf16 v[112:115], v[152:155], v[168:171], v[112:115]
	v_mfma_f32_16x16x32_bf16 v[112:115], v[156:159], v[172:175], v[112:115]
	v_mfma_f32_16x16x32_bf16 v[104:107], v[160:163], v[168:171], v[104:107]
	v_mfma_f32_16x16x32_bf16 v[104:107], v[164:167], v[172:175], v[104:107]
	v_mfma_f32_16x16x32_bf16 v[96:99], v[152:155], v[176:179], v[96:99]
	v_mfma_f32_16x16x32_bf16 v[96:99], v[156:159], v[180:183], v[96:99]
	v_mfma_f32_16x16x32_bf16 v[88:91], v[160:163], v[176:179], v[88:91]
	v_mfma_f32_16x16x32_bf16 v[88:91], v[164:167], v[180:183], v[88:91]
	v_mfma_f32_16x16x32_bf16 v[80:83], v[152:155], v[184:187], v[80:83]
	v_mfma_f32_16x16x32_bf16 v[80:83], v[156:159], v[188:191], v[80:83]
	v_mfma_f32_16x16x32_bf16 v[72:75], v[160:163], v[184:187], v[72:75]
	v_mfma_f32_16x16x32_bf16 v[72:75], v[164:167], v[188:191], v[72:75]
	v_mfma_f32_16x16x32_bf16 v[68:71], v[152:155], v[192:195], v[68:71]
	v_mfma_f32_16x16x32_bf16 v[68:71], v[156:159], v[200:203], v[68:71]
	v_mfma_f32_16x16x32_bf16 v[64:67], v[160:163], v[192:195], v[64:67]
	v_mfma_f32_16x16x32_bf16 v[64:67], v[164:167], v[200:203], v[64:67]
	s_barrier
	s_setprio 0
	s_add_i32 s72, s72, s97
	s_mov_b64 s[70:71], s[30:31]
	s_mov_b32 m0, s72
	ds_read_b128 v[168:171], v135 offset:16384
	ds_read_b128 v[172:175], v135 offset:17408
	ds_read_b128 v[176:179], v135 offset:18432
	ds_read_b128 v[180:183], v135 offset:19456
	ds_read_b128 v[184:187], v135 offset:20480
	ds_read_b128 v[188:191], v135 offset:21504
	ds_read_b128 v[192:195], v135 offset:22528
	ds_read_b128 v[200:203], v135 offset:23552
	s_nop 0
	global_load_lds_dwordx4 v132, s[70:71]
	s_add_i32 m0, s72, 0x2000
	s_nop 0
	global_load_lds_dwordx4 v130, s[70:71]
	s_add_u32 s70, s30, 0x20000
	s_addc_u32 s71, s31, 0
	s_add_i32 s72, s74, s97
	s_mov_b32 m0, s72
	s_nop 0
	global_load_lds_dwordx4 v132, s[70:71]
	s_add_i32 m0, s72, 0x2000
	s_nop 0
	global_load_lds_dwordx4 v130, s[70:71]
	s_mov_b64 s[70:71], s[34:35]
	s_mov_b32 m0, s25
	s_nop 0
	global_load_lds_dwordx4 v133, s[70:71]
	s_mov_b32 m0, s37
	s_nop 0
	global_load_lds_dwordx4 v131, s[70:71]
	s_waitcnt vmcnt(8) lgkmcnt(0)
	s_setprio 1
	s_barrier
	v_mfma_f32_16x16x32_bf16 v[60:63], v[136:139], v[168:171], v[60:63]
	v_mfma_f32_16x16x32_bf16 v[60:63], v[140:143], v[172:175], v[60:63]
	v_mfma_f32_16x16x32_bf16 v[56:59], v[144:147], v[168:171], v[56:59]
	v_mfma_f32_16x16x32_bf16 v[56:59], v[148:151], v[172:175], v[56:59]
	v_mfma_f32_16x16x32_bf16 v[52:55], v[136:139], v[176:179], v[52:55]
	v_mfma_f32_16x16x32_bf16 v[52:55], v[140:143], v[180:183], v[52:55]
	v_mfma_f32_16x16x32_bf16 v[44:47], v[144:147], v[176:179], v[44:47]
	v_mfma_f32_16x16x32_bf16 v[44:47], v[148:151], v[180:183], v[44:47]
	v_mfma_f32_16x16x32_bf16 v[36:39], v[136:139], v[184:187], v[36:39]
	v_mfma_f32_16x16x32_bf16 v[36:39], v[140:143], v[188:191], v[36:39]
	v_mfma_f32_16x16x32_bf16 v[28:31], v[144:147], v[184:187], v[28:31]
	v_mfma_f32_16x16x32_bf16 v[28:31], v[148:151], v[188:191], v[28:31]
	v_mfma_f32_16x16x32_bf16 v[20:23], v[136:139], v[192:195], v[20:23]
	v_mfma_f32_16x16x32_bf16 v[20:23], v[140:143], v[200:203], v[20:23]
	v_mfma_f32_16x16x32_bf16 v[12:15], v[144:147], v[192:195], v[12:15]
	v_mfma_f32_16x16x32_bf16 v[12:15], v[148:151], v[200:203], v[12:15]
	v_mfma_f32_16x16x32_bf16 v[48:51], v[152:155], v[168:171], v[48:51]
	v_mfma_f32_16x16x32_bf16 v[48:51], v[156:159], v[172:175], v[48:51]
	v_mfma_f32_16x16x32_bf16 v[40:43], v[160:163], v[168:171], v[40:43]
	v_mfma_f32_16x16x32_bf16 v[40:43], v[164:167], v[172:175], v[40:43]
	v_mfma_f32_16x16x32_bf16 v[32:35], v[152:155], v[176:179], v[32:35]
	v_mfma_f32_16x16x32_bf16 v[32:35], v[156:159], v[180:183], v[32:35]
	v_mfma_f32_16x16x32_bf16 v[24:27], v[160:163], v[176:179], v[24:27]
	v_mfma_f32_16x16x32_bf16 v[24:27], v[164:167], v[180:183], v[24:27]
	v_mfma_f32_16x16x32_bf16 v[16:19], v[152:155], v[184:187], v[16:19]
	v_mfma_f32_16x16x32_bf16 v[16:19], v[156:159], v[188:191], v[16:19]
	v_mfma_f32_16x16x32_bf16 v[8:11], v[160:163], v[184:187], v[8:11]
	v_mfma_f32_16x16x32_bf16 v[8:11], v[164:167], v[188:191], v[8:11]
	v_mfma_f32_16x16x32_bf16 v[4:7], v[152:155], v[192:195], v[4:7]
	v_mfma_f32_16x16x32_bf16 v[4:7], v[156:159], v[200:203], v[4:7]
	v_mfma_f32_16x16x32_bf16 v[0:3], v[160:163], v[192:195], v[0:3]
	v_mfma_f32_16x16x32_bf16 v[0:3], v[164:167], v[200:203], v[0:3]
	s_barrier
	s_setprio 0
	s_add_i32 s70, 0, 0x18000
	v_add_u32_e32 v128, s70, v134
	s_add_i32 s71, 0, 0x1c000
	ds_read_b128 v[136:139], v128
	ds_read_b128 v[140:143], v128 offset:1024
	ds_read_b128 v[144:147], v128 offset:2048
	ds_read_b128 v[148:151], v128 offset:3072
	v_add_u32_e32 v128, s71, v134
	ds_read_b128 v[152:155], v128
	ds_read_b128 v[156:159], v128 offset:1024
	ds_read_b128 v[160:163], v128 offset:2048
	ds_read_b128 v[164:167], v128 offset:3072
	s_add_u32 s34, s34, 0x20000
	s_addc_u32 s35, s35, 0
	s_mov_b32 m0, s38
	ds_read_b128 v[168:171], v135 offset:32768
	ds_read_b128 v[172:175], v135 offset:33792
	ds_read_b128 v[176:179], v135 offset:34816
	ds_read_b128 v[180:183], v135 offset:35840
	ds_read_b128 v[184:187], v135 offset:36864
	ds_read_b128 v[188:191], v135 offset:37888
	ds_read_b128 v[192:195], v135 offset:38912
	ds_read_b128 v[200:203], v135 offset:39936
	s_nop 0
	global_load_lds_dwordx4 v133, s[34:35]
	s_mov_b32 m0, s39
	s_nop 0
	global_load_lds_dwordx4 v131, s[34:35]
	s_waitcnt vmcnt(8) lgkmcnt(0)
	s_setprio 1
	s_barrier
	v_mfma_f32_16x16x32_bf16 v[124:127], v[136:139], v[168:171], v[124:127]
	v_mfma_f32_16x16x32_bf16 v[124:127], v[140:143], v[172:175], v[124:127]
	v_mfma_f32_16x16x32_bf16 v[120:123], v[144:147], v[168:171], v[120:123]
	v_mfma_f32_16x16x32_bf16 v[120:123], v[148:151], v[172:175], v[120:123]
	v_mfma_f32_16x16x32_bf16 v[116:119], v[136:139], v[176:179], v[116:119]
	v_mfma_f32_16x16x32_bf16 v[116:119], v[140:143], v[180:183], v[116:119]
	v_mfma_f32_16x16x32_bf16 v[108:111], v[144:147], v[176:179], v[108:111]
	v_mfma_f32_16x16x32_bf16 v[108:111], v[148:151], v[180:183], v[108:111]
	v_mfma_f32_16x16x32_bf16 v[100:103], v[136:139], v[184:187], v[100:103]
	v_mfma_f32_16x16x32_bf16 v[100:103], v[140:143], v[188:191], v[100:103]
	v_mfma_f32_16x16x32_bf16 v[92:95], v[144:147], v[184:187], v[92:95]
	v_mfma_f32_16x16x32_bf16 v[92:95], v[148:151], v[188:191], v[92:95]
	v_mfma_f32_16x16x32_bf16 v[84:87], v[136:139], v[192:195], v[84:87]
	v_mfma_f32_16x16x32_bf16 v[84:87], v[140:143], v[200:203], v[84:87]
	v_mfma_f32_16x16x32_bf16 v[76:79], v[144:147], v[192:195], v[76:79]
	v_mfma_f32_16x16x32_bf16 v[76:79], v[148:151], v[200:203], v[76:79]
	v_mfma_f32_16x16x32_bf16 v[112:115], v[152:155], v[168:171], v[112:115]
	v_mfma_f32_16x16x32_bf16 v[112:115], v[156:159], v[172:175], v[112:115]
	v_mfma_f32_16x16x32_bf16 v[104:107], v[160:163], v[168:171], v[104:107]
	v_mfma_f32_16x16x32_bf16 v[104:107], v[164:167], v[172:175], v[104:107]
	v_mfma_f32_16x16x32_bf16 v[96:99], v[152:155], v[176:179], v[96:99]
	v_mfma_f32_16x16x32_bf16 v[96:99], v[156:159], v[180:183], v[96:99]
	v_mfma_f32_16x16x32_bf16 v[88:91], v[160:163], v[176:179], v[88:91]
	v_mfma_f32_16x16x32_bf16 v[88:91], v[164:167], v[180:183], v[88:91]
	v_mfma_f32_16x16x32_bf16 v[80:83], v[152:155], v[184:187], v[80:83]
	v_mfma_f32_16x16x32_bf16 v[80:83], v[156:159], v[188:191], v[80:83]
	v_mfma_f32_16x16x32_bf16 v[72:75], v[160:163], v[184:187], v[72:75]
	v_mfma_f32_16x16x32_bf16 v[72:75], v[164:167], v[188:191], v[72:75]
	v_mfma_f32_16x16x32_bf16 v[68:71], v[152:155], v[192:195], v[68:71]
	v_mfma_f32_16x16x32_bf16 v[68:71], v[156:159], v[200:203], v[68:71]
	v_mfma_f32_16x16x32_bf16 v[64:67], v[160:163], v[192:195], v[64:67]
	v_mfma_f32_16x16x32_bf16 v[64:67], v[164:167], v[200:203], v[64:67]
	s_barrier
	s_setprio 0
	s_add_u32 s34, s30, 0x80
	s_addc_u32 s35, s31, 0
	s_add_i32 s70, s70, s97
	s_mov_b32 m0, s70
	ds_read_b128 v[168:171], v135 offset:49152
	ds_read_b128 v[172:175], v135 offset:50176
	ds_read_b128 v[176:179], v135 offset:51200
	ds_read_b128 v[180:183], v135 offset:52224
	ds_read_b128 v[184:187], v135 offset:53248
	ds_read_b128 v[188:191], v135 offset:54272
	ds_read_b128 v[192:195], v135 offset:55296
	ds_read_b128 v[200:203], v135 offset:56320
	s_nop 0
	global_load_lds_dwordx4 v132, s[34:35]
	s_add_i32 m0, s70, 0x2000
	s_add_u32 s30, s30, 0x20080
	s_addc_u32 s31, s31, 0
	global_load_lds_dwordx4 v130, s[34:35]
	s_add_i32 s34, s71, s97
	s_mov_b32 m0, s34
	s_nop 0
	global_load_lds_dwordx4 v132, s[30:31]
	s_add_i32 m0, s34, 0x2000
	s_nop 0
	global_load_lds_dwordx4 v130, s[30:31]
	s_mov_b32 m0, s44
	s_nop 0
	global_load_lds_dwordx4 v133, s[28:29]
	s_mov_b32 m0, s46
	s_nop 0
	global_load_lds_dwordx4 v131, s[28:29]
	s_waitcnt vmcnt(8) lgkmcnt(0)
	s_setprio 1
	s_barrier
	v_mfma_f32_16x16x32_bf16 v[60:63], v[136:139], v[168:171], v[60:63]
	v_mfma_f32_16x16x32_bf16 v[60:63], v[140:143], v[172:175], v[60:63]
	v_mfma_f32_16x16x32_bf16 v[56:59], v[144:147], v[168:171], v[56:59]
	v_mfma_f32_16x16x32_bf16 v[56:59], v[148:151], v[172:175], v[56:59]
	v_mfma_f32_16x16x32_bf16 v[52:55], v[136:139], v[176:179], v[52:55]
	v_mfma_f32_16x16x32_bf16 v[52:55], v[140:143], v[180:183], v[52:55]
	v_mfma_f32_16x16x32_bf16 v[44:47], v[144:147], v[176:179], v[44:47]
	v_mfma_f32_16x16x32_bf16 v[44:47], v[148:151], v[180:183], v[44:47]
	v_mfma_f32_16x16x32_bf16 v[36:39], v[136:139], v[184:187], v[36:39]
	v_mfma_f32_16x16x32_bf16 v[36:39], v[140:143], v[188:191], v[36:39]
	v_mfma_f32_16x16x32_bf16 v[28:31], v[144:147], v[184:187], v[28:31]
	v_mfma_f32_16x16x32_bf16 v[28:31], v[148:151], v[188:191], v[28:31]
	v_mfma_f32_16x16x32_bf16 v[20:23], v[136:139], v[192:195], v[20:23]
	v_mfma_f32_16x16x32_bf16 v[20:23], v[140:143], v[200:203], v[20:23]
	v_mfma_f32_16x16x32_bf16 v[12:15], v[144:147], v[192:195], v[12:15]
	v_mfma_f32_16x16x32_bf16 v[12:15], v[148:151], v[200:203], v[12:15]
	v_mfma_f32_16x16x32_bf16 v[48:51], v[152:155], v[168:171], v[48:51]
	v_mfma_f32_16x16x32_bf16 v[48:51], v[156:159], v[172:175], v[48:51]
	v_mfma_f32_16x16x32_bf16 v[40:43], v[160:163], v[168:171], v[40:43]
	v_mfma_f32_16x16x32_bf16 v[40:43], v[164:167], v[172:175], v[40:43]
	v_mfma_f32_16x16x32_bf16 v[32:35], v[152:155], v[176:179], v[32:35]
	v_mfma_f32_16x16x32_bf16 v[32:35], v[156:159], v[180:183], v[32:35]
	v_mfma_f32_16x16x32_bf16 v[24:27], v[160:163], v[176:179], v[24:27]
	v_mfma_f32_16x16x32_bf16 v[24:27], v[164:167], v[180:183], v[24:27]
	v_mfma_f32_16x16x32_bf16 v[16:19], v[152:155], v[184:187], v[16:19]
	v_mfma_f32_16x16x32_bf16 v[16:19], v[156:159], v[188:191], v[16:19]
	v_mfma_f32_16x16x32_bf16 v[8:11], v[160:163], v[184:187], v[8:11]
	v_mfma_f32_16x16x32_bf16 v[8:11], v[164:167], v[188:191], v[8:11]
	v_mfma_f32_16x16x32_bf16 v[4:7], v[152:155], v[192:195], v[4:7]
	v_mfma_f32_16x16x32_bf16 v[4:7], v[156:159], v[200:203], v[4:7]
	v_mfma_f32_16x16x32_bf16 v[0:3], v[160:163], v[192:195], v[0:3]
	v_mfma_f32_16x16x32_bf16 v[0:3], v[164:167], v[200:203], v[0:3]
	s_barrier
	s_setprio 0
	s_add_i32 s69, s69, 2
	s_add_u32 s49, s49, 0x100
	s_addc_u32 s56, s56, 0
	s_add_u32 s57, s57, 0x100
	s_addc_u32 s65, s65, 0
	s_add_u32 s26, s26, 0x100
	s_addc_u32 s27, s27, 0
	s_cmp_gt_u32 s69, 5
	s_cbranch_scc0 .LBB0_397
	s_and_b64 vcc, exec, s[60:61]
	s_cbranch_vccz .LBB0_400
	s_barrier

.LBB0_527:
	s_cmp_eq_u32 s85, 28
	s_cselect_b32 s56, s5, s39
	s_cselect_b32 s57, s4, s69
	s_cselect_b32 s86, s37, s72
	s_cselect_b32 s87, s11, s74
	s_add_u32 s12, s56, 0x80
	s_addc_u32 s13, s57, 0
	s_add_i32 vcc_lo, 0, 0x10000
	s_add_i32 vcc_hi, 0, 0x14000
	v_add_u32_e32 v136, vcc_lo, v184
	v_add_u32_e32 v156, vcc_hi, v184
	ds_read_b128 v[104:107], v136
	ds_read_b128 v[108:111], v136 offset:1024
	ds_read_b128 v[132:135], v136 offset:2048
	ds_read_b128 v[136:139], v136 offset:3072
	ds_read_b128 v[144:147], v156
	ds_read_b128 v[148:151], v156 offset:1024
	ds_read_b128 v[152:155], v156 offset:2048
	ds_read_b128 v[156:159], v156 offset:3072
	s_mov_b64 s[8:9], s[16:17]
	s_add_i32 m0, s89, 0xc000
	ds_read_b128 v[160:163], v185
	ds_read_b128 v[164:167], v185 offset:1024
	ds_read_b128 v[168:171], v185 offset:2048
	ds_read_b128 v[172:175], v185 offset:3072
	ds_read_b128 v[186:189], v185 offset:4096
	ds_read_b128 v[190:193], v185 offset:5120
	ds_read_b128 v[200:203], v185 offset:6144
	ds_read_b128 v[204:207], v185 offset:7168
	s_nop 0
	global_load_lds_dwordx4 v179, s[8:9]
	s_add_i32 m0, s89, 0xe000
	s_nop 0
	global_load_lds_dwordx4 v182, s[8:9]
	s_waitcnt vmcnt(8) lgkmcnt(0)
	s_setprio 1
	s_barrier
	v_mfma_f32_16x16x32_bf16 v[140:143], v[104:107], v[160:163], v[140:143]
	v_mfma_f32_16x16x32_bf16 v[140:143], v[108:111], v[164:167], v[140:143]
	v_mfma_f32_16x16x32_bf16 v[128:131], v[132:135], v[160:163], v[128:131]
	v_mfma_f32_16x16x32_bf16 v[128:131], v[136:139], v[164:167], v[128:131]
	v_mfma_f32_16x16x32_bf16 v[124:127], v[104:107], v[168:171], v[124:127]
	v_mfma_f32_16x16x32_bf16 v[124:127], v[108:111], v[172:175], v[124:127]
	v_mfma_f32_16x16x32_bf16 v[112:115], v[132:135], v[168:171], v[112:115]
	v_mfma_f32_16x16x32_bf16 v[112:115], v[136:139], v[172:175], v[112:115]
	v_mfma_f32_16x16x32_bf16 v[96:99], v[104:107], v[186:189], v[96:99]
	v_mfma_f32_16x16x32_bf16 v[96:99], v[108:111], v[190:193], v[96:99]
	v_mfma_f32_16x16x32_bf16 v[88:91], v[132:135], v[186:189], v[88:91]
	v_mfma_f32_16x16x32_bf16 v[88:91], v[136:139], v[190:193], v[88:91]
	v_mfma_f32_16x16x32_bf16 v[84:87], v[104:107], v[200:203], v[84:87]
	v_mfma_f32_16x16x32_bf16 v[84:87], v[108:111], v[204:207], v[84:87]
	v_mfma_f32_16x16x32_bf16 v[72:75], v[132:135], v[200:203], v[72:75]
	v_mfma_f32_16x16x32_bf16 v[72:75], v[136:139], v[204:207], v[72:75]
	v_mfma_f32_16x16x32_bf16 v[120:123], v[144:147], v[160:163], v[120:123]
	v_mfma_f32_16x16x32_bf16 v[120:123], v[148:151], v[164:167], v[120:123]
	v_mfma_f32_16x16x32_bf16 v[116:119], v[152:155], v[160:163], v[116:119]
	v_mfma_f32_16x16x32_bf16 v[116:119], v[156:159], v[164:167], v[116:119]
	v_mfma_f32_16x16x32_bf16 v[100:103], v[144:147], v[168:171], v[100:103]
	v_mfma_f32_16x16x32_bf16 v[100:103], v[148:151], v[172:175], v[100:103]
	v_mfma_f32_16x16x32_bf16 v[92:95], v[152:155], v[168:171], v[92:95]
	v_mfma_f32_16x16x32_bf16 v[92:95], v[156:159], v[172:175], v[92:95]
	v_mfma_f32_16x16x32_bf16 v[80:83], v[144:147], v[186:189], v[80:83]
	v_mfma_f32_16x16x32_bf16 v[80:83], v[148:151], v[190:193], v[80:83]
	v_mfma_f32_16x16x32_bf16 v[76:79], v[152:155], v[186:189], v[76:79]
	v_mfma_f32_16x16x32_bf16 v[76:79], v[156:159], v[190:193], v[76:79]
	v_mfma_f32_16x16x32_bf16 v[68:71], v[144:147], v[200:203], v[68:71]
	v_mfma_f32_16x16x32_bf16 v[68:71], v[148:151], v[204:207], v[68:71]
	v_mfma_f32_16x16x32_bf16 v[64:67], v[152:155], v[200:203], v[64:67]
	v_mfma_f32_16x16x32_bf16 v[64:67], v[156:159], v[204:207], v[64:67]
	s_barrier
	s_setprio 0
	s_add_i32 vcc_lo, vcc_lo, s97
	s_mov_b64 s[8:9], s[86:87]
	s_mov_b32 m0, vcc_lo
	ds_read_b128 v[160:163], v185 offset:16384
	ds_read_b128 v[164:167], v185 offset:17408
	ds_read_b128 v[168:171], v185 offset:18432
	ds_read_b128 v[172:175], v185 offset:19456
	ds_read_b128 v[186:189], v185 offset:20480
	ds_read_b128 v[190:193], v185 offset:21504
	ds_read_b128 v[200:203], v185 offset:22528
	ds_read_b128 v[204:207], v185 offset:23552
	s_nop 0
	global_load_lds_dwordx4 v181, s[8:9]
	s_add_i32 m0, vcc_lo, 0x2000
	s_nop 0
	global_load_lds_dwordx4 v183, s[8:9]
	s_add_u32 s8, s86, 0x80000
	s_addc_u32 s9, s87, 0
	s_add_i32 vcc_lo, vcc_hi, s97
	s_mov_b32 m0, vcc_lo
	s_nop 0
	global_load_lds_dwordx4 v181, s[8:9]
	s_add_i32 m0, vcc_lo, 0x2000
	s_nop 0
	global_load_lds_dwordx4 v183, s[8:9]
	s_mov_b64 s[8:9], s[56:57]
	s_mov_b32 m0, s89
	s_nop 0
	global_load_lds_dwordx4 v179, s[8:9]
	s_mov_b32 m0, s92
	s_nop 0
	global_load_lds_dwordx4 v182, s[8:9]
	s_waitcnt vmcnt(8) lgkmcnt(0)
	s_setprio 1
	s_barrier
	v_mfma_f32_16x16x32_bf16 v[60:63], v[104:107], v[160:163], v[60:63]
	v_mfma_f32_16x16x32_bf16 v[60:63], v[108:111], v[164:167], v[60:63]
	v_mfma_f32_16x16x32_bf16 v[56:59], v[132:135], v[160:163], v[56:59]
	v_mfma_f32_16x16x32_bf16 v[56:59], v[136:139], v[164:167], v[56:59]
	v_mfma_f32_16x16x32_bf16 v[48:51], v[104:107], v[168:171], v[48:51]
	v_mfma_f32_16x16x32_bf16 v[48:51], v[108:111], v[172:175], v[48:51]
	v_mfma_f32_16x16x32_bf16 v[40:43], v[132:135], v[168:171], v[40:43]
	v_mfma_f32_16x16x32_bf16 v[40:43], v[136:139], v[172:175], v[40:43]
	v_mfma_f32_16x16x32_bf16 v[32:35], v[104:107], v[186:189], v[32:35]
	v_mfma_f32_16x16x32_bf16 v[32:35], v[108:111], v[190:193], v[32:35]
	v_mfma_f32_16x16x32_bf16 v[24:27], v[132:135], v[186:189], v[24:27]
	v_mfma_f32_16x16x32_bf16 v[24:27], v[136:139], v[190:193], v[24:27]
	v_mfma_f32_16x16x32_bf16 v[16:19], v[104:107], v[200:203], v[16:19]
	v_mfma_f32_16x16x32_bf16 v[16:19], v[108:111], v[204:207], v[16:19]
	v_mfma_f32_16x16x32_bf16 v[8:11], v[132:135], v[200:203], v[8:11]
	v_mfma_f32_16x16x32_bf16 v[8:11], v[136:139], v[204:207], v[8:11]
	v_mfma_f32_16x16x32_bf16 v[52:55], v[144:147], v[160:163], v[52:55]
	v_mfma_f32_16x16x32_bf16 v[52:55], v[148:151], v[164:167], v[52:55]
	v_mfma_f32_16x16x32_bf16 v[44:47], v[152:155], v[160:163], v[44:47]
	v_mfma_f32_16x16x32_bf16 v[44:47], v[156:159], v[164:167], v[44:47]
	v_mfma_f32_16x16x32_bf16 v[36:39], v[144:147], v[168:171], v[36:39]
	v_mfma_f32_16x16x32_bf16 v[36:39], v[148:151], v[172:175], v[36:39]
	v_mfma_f32_16x16x32_bf16 v[28:31], v[152:155], v[168:171], v[28:31]
	v_mfma_f32_16x16x32_bf16 v[28:31], v[156:159], v[172:175], v[28:31]
	v_mfma_f32_16x16x32_bf16 v[20:23], v[144:147], v[186:189], v[20:23]
	v_mfma_f32_16x16x32_bf16 v[20:23], v[148:151], v[190:193], v[20:23]
	v_mfma_f32_16x16x32_bf16 v[12:15], v[152:155], v[186:189], v[12:15]
	v_mfma_f32_16x16x32_bf16 v[12:15], v[156:159], v[190:193], v[12:15]
	v_mfma_f32_16x16x32_bf16 v[4:7], v[144:147], v[200:203], v[4:7]
	v_mfma_f32_16x16x32_bf16 v[4:7], v[148:151], v[204:207], v[4:7]
	v_mfma_f32_16x16x32_bf16 v[0:3], v[152:155], v[200:203], v[0:3]
	v_mfma_f32_16x16x32_bf16 v[0:3], v[156:159], v[204:207], v[0:3]
	s_barrier
	s_setprio 0
	s_add_i32 vcc_lo, 0, 0x18000
	s_add_i32 vcc_hi, 0, 0x1c000
	v_add_u32_e32 v136, vcc_lo, v184
	v_add_u32_e32 v156, vcc_hi, v184
	ds_read_b128 v[104:107], v136
	ds_read_b128 v[108:111], v136 offset:1024
	ds_read_b128 v[132:135], v136 offset:2048
	ds_read_b128 v[136:139], v136 offset:3072
	ds_read_b128 v[144:147], v156
	ds_read_b128 v[148:151], v156 offset:1024
	ds_read_b128 v[152:155], v156 offset:2048
	ds_read_b128 v[156:159], v156 offset:3072
	s_add_u32 s8, s56, 0x80000
	s_addc_u32 s9, s57, 0
	s_mov_b32 m0, s93
	ds_read_b128 v[160:163], v185 offset:32768
	ds_read_b128 v[164:167], v185 offset:33792
	ds_read_b128 v[168:171], v185 offset:34816
	ds_read_b128 v[172:175], v185 offset:35840
	ds_read_b128 v[186:189], v185 offset:36864
	ds_read_b128 v[190:193], v185 offset:37888
	ds_read_b128 v[200:203], v185 offset:38912
	ds_read_b128 v[204:207], v185 offset:39936
	s_nop 0
	global_load_lds_dwordx4 v179, s[8:9]
	s_mov_b32 m0, s48
	s_nop 0
	global_load_lds_dwordx4 v182, s[8:9]
	s_waitcnt vmcnt(8) lgkmcnt(0)
	s_setprio 1
	s_barrier
	v_mfma_f32_16x16x32_bf16 v[140:143], v[104:107], v[160:163], v[140:143]
	v_mfma_f32_16x16x32_bf16 v[140:143], v[108:111], v[164:167], v[140:143]
	v_mfma_f32_16x16x32_bf16 v[128:131], v[132:135], v[160:163], v[128:131]
	v_mfma_f32_16x16x32_bf16 v[128:131], v[136:139], v[164:167], v[128:131]
	v_mfma_f32_16x16x32_bf16 v[124:127], v[104:107], v[168:171], v[124:127]
	v_mfma_f32_16x16x32_bf16 v[124:127], v[108:111], v[172:175], v[124:127]
	v_mfma_f32_16x16x32_bf16 v[112:115], v[132:135], v[168:171], v[112:115]
	v_mfma_f32_16x16x32_bf16 v[112:115], v[136:139], v[172:175], v[112:115]
	v_mfma_f32_16x16x32_bf16 v[96:99], v[104:107], v[186:189], v[96:99]
	v_mfma_f32_16x16x32_bf16 v[96:99], v[108:111], v[190:193], v[96:99]
	v_mfma_f32_16x16x32_bf16 v[88:91], v[132:135], v[186:189], v[88:91]
	v_mfma_f32_16x16x32_bf16 v[88:91], v[136:139], v[190:193], v[88:91]
	v_mfma_f32_16x16x32_bf16 v[84:87], v[104:107], v[200:203], v[84:87]
	v_mfma_f32_16x16x32_bf16 v[84:87], v[108:111], v[204:207], v[84:87]
	v_mfma_f32_16x16x32_bf16 v[72:75], v[132:135], v[200:203], v[72:75]
	v_mfma_f32_16x16x32_bf16 v[72:75], v[136:139], v[204:207], v[72:75]
	v_mfma_f32_16x16x32_bf16 v[120:123], v[144:147], v[160:163], v[120:123]
	v_mfma_f32_16x16x32_bf16 v[120:123], v[148:151], v[164:167], v[120:123]
	v_mfma_f32_16x16x32_bf16 v[116:119], v[152:155], v[160:163], v[116:119]
	v_mfma_f32_16x16x32_bf16 v[116:119], v[156:159], v[164:167], v[116:119]
	v_mfma_f32_16x16x32_bf16 v[100:103], v[144:147], v[168:171], v[100:103]
	v_mfma_f32_16x16x32_bf16 v[100:103], v[148:151], v[172:175], v[100:103]
	v_mfma_f32_16x16x32_bf16 v[92:95], v[152:155], v[168:171], v[92:95]
	v_mfma_f32_16x16x32_bf16 v[92:95], v[156:159], v[172:175], v[92:95]
	v_mfma_f32_16x16x32_bf16 v[80:83], v[144:147], v[186:189], v[80:83]
	v_mfma_f32_16x16x32_bf16 v[80:83], v[148:151], v[190:193], v[80:83]
	v_mfma_f32_16x16x32_bf16 v[76:79], v[152:155], v[186:189], v[76:79]
	v_mfma_f32_16x16x32_bf16 v[76:79], v[156:159], v[190:193], v[76:79]
	v_mfma_f32_16x16x32_bf16 v[68:71], v[144:147], v[200:203], v[68:71]
	v_mfma_f32_16x16x32_bf16 v[68:71], v[148:151], v[204:207], v[68:71]
	v_mfma_f32_16x16x32_bf16 v[64:67], v[152:155], v[200:203], v[64:67]
	v_mfma_f32_16x16x32_bf16 v[64:67], v[156:159], v[204:207], v[64:67]
	s_barrier
	s_setprio 0
	s_add_u32 s8, s86, 0x80
	s_addc_u32 s9, s87, 0
	s_add_i32 s56, vcc_lo, s97
	s_mov_b32 m0, s56
	ds_read_b128 v[160:163], v185 offset:49152
	ds_read_b128 v[164:167], v185 offset:50176
	ds_read_b128 v[168:171], v185 offset:51200
	ds_read_b128 v[172:175], v185 offset:52224
	ds_read_b128 v[186:189], v185 offset:53248
	ds_read_b128 v[190:193], v185 offset:54272
	ds_read_b128 v[200:203], v185 offset:55296
	ds_read_b128 v[204:207], v185 offset:56320
	s_nop 0
	global_load_lds_dwordx4 v181, s[8:9]
	s_add_i32 m0, s56, 0x2000
	s_nop 0
	global_load_lds_dwordx4 v183, s[8:9]
	s_add_u32 s8, s86, 0x80080
	s_addc_u32 s9, s87, 0
	s_add_i32 s56, vcc_hi, s97
	s_mov_b32 m0, s56
	s_nop 0
	global_load_lds_dwordx4 v181, s[8:9]
	s_add_i32 m0, s56, 0x2000
	s_nop 0
	global_load_lds_dwordx4 v183, s[8:9]
	s_mov_b32 m0, s46
	s_nop 0
	global_load_lds_dwordx4 v179, s[12:13]
	s_mov_b32 m0, s70
	s_nop 0
	global_load_lds_dwordx4 v182, s[12:13]
	s_waitcnt vmcnt(8) lgkmcnt(0)
	s_setprio 1
	s_barrier
	v_mfma_f32_16x16x32_bf16 v[60:63], v[104:107], v[160:163], v[60:63]
	v_mfma_f32_16x16x32_bf16 v[60:63], v[108:111], v[164:167], v[60:63]
	v_mfma_f32_16x16x32_bf16 v[56:59], v[132:135], v[160:163], v[56:59]
	v_mfma_f32_16x16x32_bf16 v[56:59], v[136:139], v[164:167], v[56:59]
	v_mfma_f32_16x16x32_bf16 v[48:51], v[104:107], v[168:171], v[48:51]
	v_mfma_f32_16x16x32_bf16 v[48:51], v[108:111], v[172:175], v[48:51]
	v_mfma_f32_16x16x32_bf16 v[40:43], v[132:135], v[168:171], v[40:43]
	v_mfma_f32_16x16x32_bf16 v[40:43], v[136:139], v[172:175], v[40:43]
	v_mfma_f32_16x16x32_bf16 v[32:35], v[104:107], v[186:189], v[32:35]
	v_mfma_f32_16x16x32_bf16 v[32:35], v[108:111], v[190:193], v[32:35]
	v_mfma_f32_16x16x32_bf16 v[24:27], v[132:135], v[186:189], v[24:27]
	v_mfma_f32_16x16x32_bf16 v[24:27], v[136:139], v[190:193], v[24:27]
	v_mfma_f32_16x16x32_bf16 v[16:19], v[104:107], v[200:203], v[16:19]
	v_mfma_f32_16x16x32_bf16 v[16:19], v[108:111], v[204:207], v[16:19]
	v_mfma_f32_16x16x32_bf16 v[8:11], v[132:135], v[200:203], v[8:11]
	v_mfma_f32_16x16x32_bf16 v[8:11], v[136:139], v[204:207], v[8:11]
	v_mfma_f32_16x16x32_bf16 v[52:55], v[144:147], v[160:163], v[52:55]
	v_mfma_f32_16x16x32_bf16 v[52:55], v[148:151], v[164:167], v[52:55]
	v_mfma_f32_16x16x32_bf16 v[44:47], v[152:155], v[160:163], v[44:47]
	v_mfma_f32_16x16x32_bf16 v[44:47], v[156:159], v[164:167], v[44:47]
	v_mfma_f32_16x16x32_bf16 v[36:39], v[144:147], v[168:171], v[36:39]
	v_mfma_f32_16x16x32_bf16 v[36:39], v[148:151], v[172:175], v[36:39]
	v_mfma_f32_16x16x32_bf16 v[28:31], v[152:155], v[168:171], v[28:31]
	v_mfma_f32_16x16x32_bf16 v[28:31], v[156:159], v[172:175], v[28:31]
	v_mfma_f32_16x16x32_bf16 v[20:23], v[144:147], v[186:189], v[20:23]
	v_mfma_f32_16x16x32_bf16 v[20:23], v[148:151], v[190:193], v[20:23]
	v_mfma_f32_16x16x32_bf16 v[12:15], v[152:155], v[186:189], v[12:15]
	v_mfma_f32_16x16x32_bf16 v[12:15], v[156:159], v[190:193], v[12:15]
	v_mfma_f32_16x16x32_bf16 v[4:7], v[144:147], v[200:203], v[4:7]
	v_mfma_f32_16x16x32_bf16 v[4:7], v[148:151], v[204:207], v[4:7]
	v_mfma_f32_16x16x32_bf16 v[0:3], v[152:155], v[200:203], v[0:3]
	v_mfma_f32_16x16x32_bf16 v[0:3], v[156:159], v[204:207], v[0:3]
	s_barrier
	s_setprio 0
	s_add_i32 s85, s85, 2
	s_add_u32 s39, s39, 0x100
	s_addc_u32 s69, s69, 0
	s_add_u32 s72, s72, 0x100
	s_addc_u32 s74, s74, 0
	s_add_u32 s16, s16, 0x100
	s_addc_u32 s17, s17, 0
	s_cmp_gt_u32 s85, 29
	s_cbranch_scc0 .LBB0_527
	s_and_b64 vcc, exec, s[60:61]
	s_cbranch_vccz .LBB0_530
	s_barrier

.LBB0_604:
	s_cmp_eq_u32 s21, 4
	s_cselect_b32 s38, s22, s4
	s_cselect_b32 s39, s23, s5
	s_cselect_b32 s36, s24, s15
	s_cselect_b32 s37, s25, s17
	s_add_u32 s34, s38, 0x80
	s_addc_u32 s35, s39, 0
	s_add_i32 s65, 0, 0x10000
	s_add_i32 s69, 0, 0x14000
	v_add_u32_e32 v132, s65, v154
	v_add_u32_e32 v148, s69, v154
	ds_read_b128 v[112:115], v132
	ds_read_b128 v[120:123], v132 offset:1024
	ds_read_b128 v[128:131], v132 offset:2048
	ds_read_b128 v[132:135], v132 offset:3072
	ds_read_b128 v[144:147], v148
	ds_read_b128 v[156:159], v148 offset:1024
	ds_read_b128 v[160:163], v148 offset:2048
	ds_read_b128 v[164:167], v148 offset:3072
	s_add_u32 s70, s4, 0x7ff80
	s_addc_u32 s71, s5, 0
	s_add_i32 m0, s27, 0xc000
	ds_read_b128 v[168:171], v155
	ds_read_b128 v[172:175], v155 offset:1024
	ds_read_b128 v[176:179], v155 offset:2048
	ds_read_b128 v[180:183], v155 offset:3072
	ds_read_b128 v[184:187], v155 offset:4096
	ds_read_b128 v[188:191], v155 offset:5120
	ds_read_b128 v[192:195], v155 offset:6144
	ds_read_b128 v[200:203], v155 offset:7168
	s_nop 0
	global_load_lds_dwordx4 v151, s[70:71]
	s_add_i32 m0, s27, 0xe000
	s_nop 0
	global_load_lds_dwordx4 v150, s[70:71]
	s_waitcnt vmcnt(8) lgkmcnt(0)
	s_setprio 1
	s_barrier
	v_mfma_f32_16x16x32_bf16 v[140:143], v[112:115], v[168:171], v[140:143]
	v_mfma_f32_16x16x32_bf16 v[140:143], v[120:123], v[172:175], v[140:143]
	v_mfma_f32_16x16x32_bf16 v[136:139], v[128:131], v[168:171], v[136:139]
	v_mfma_f32_16x16x32_bf16 v[136:139], v[132:135], v[172:175], v[136:139]
	v_mfma_f32_16x16x32_bf16 v[108:111], v[112:115], v[176:179], v[108:111]
	v_mfma_f32_16x16x32_bf16 v[108:111], v[120:123], v[180:183], v[108:111]
	v_mfma_f32_16x16x32_bf16 v[104:107], v[128:131], v[176:179], v[104:107]
	v_mfma_f32_16x16x32_bf16 v[104:107], v[132:135], v[180:183], v[104:107]
	v_mfma_f32_16x16x32_bf16 v[92:95], v[112:115], v[184:187], v[92:95]
	v_mfma_f32_16x16x32_bf16 v[92:95], v[120:123], v[188:191], v[92:95]
	v_mfma_f32_16x16x32_bf16 v[88:91], v[128:131], v[184:187], v[88:91]
	v_mfma_f32_16x16x32_bf16 v[88:91], v[132:135], v[188:191], v[88:91]
	v_mfma_f32_16x16x32_bf16 v[76:79], v[112:115], v[192:195], v[76:79]
	v_mfma_f32_16x16x32_bf16 v[76:79], v[120:123], v[200:203], v[76:79]
	v_mfma_f32_16x16x32_bf16 v[72:75], v[128:131], v[192:195], v[72:75]
	v_mfma_f32_16x16x32_bf16 v[72:75], v[132:135], v[200:203], v[72:75]
	v_mfma_f32_16x16x32_bf16 v[124:127], v[144:147], v[168:171], v[124:127]
	v_mfma_f32_16x16x32_bf16 v[124:127], v[156:159], v[172:175], v[124:127]
	v_mfma_f32_16x16x32_bf16 v[116:119], v[160:163], v[168:171], v[116:119]
	v_mfma_f32_16x16x32_bf16 v[116:119], v[164:167], v[172:175], v[116:119]
	v_mfma_f32_16x16x32_bf16 v[100:103], v[144:147], v[176:179], v[100:103]
	v_mfma_f32_16x16x32_bf16 v[100:103], v[156:159], v[180:183], v[100:103]
	v_mfma_f32_16x16x32_bf16 v[96:99], v[160:163], v[176:179], v[96:99]
	v_mfma_f32_16x16x32_bf16 v[96:99], v[164:167], v[180:183], v[96:99]
	v_mfma_f32_16x16x32_bf16 v[84:87], v[144:147], v[184:187], v[84:87]
	v_mfma_f32_16x16x32_bf16 v[84:87], v[156:159], v[188:191], v[84:87]
	v_mfma_f32_16x16x32_bf16 v[80:83], v[160:163], v[184:187], v[80:83]
	v_mfma_f32_16x16x32_bf16 v[80:83], v[164:167], v[188:191], v[80:83]
	v_mfma_f32_16x16x32_bf16 v[68:71], v[144:147], v[192:195], v[68:71]
	v_mfma_f32_16x16x32_bf16 v[68:71], v[156:159], v[200:203], v[68:71]
	v_mfma_f32_16x16x32_bf16 v[64:67], v[160:163], v[192:195], v[64:67]
	v_mfma_f32_16x16x32_bf16 v[64:67], v[164:167], v[200:203], v[64:67]
	s_barrier
	s_setprio 0
	s_add_i32 s65, s65, s97
	s_mov_b64 s[70:71], s[36:37]
	s_mov_b32 m0, s65
	ds_read_b128 v[168:171], v155 offset:16384
	ds_read_b128 v[172:175], v155 offset:17408
	ds_read_b128 v[176:179], v155 offset:18432
	ds_read_b128 v[180:183], v155 offset:19456
	ds_read_b128 v[184:187], v155 offset:20480
	ds_read_b128 v[188:191], v155 offset:21504
	ds_read_b128 v[192:195], v155 offset:22528
	ds_read_b128 v[200:203], v155 offset:23552
	s_nop 0
	global_load_lds_dwordx4 v152, s[70:71]
	s_add_i32 m0, s65, 0x2000
	s_nop 0
	global_load_lds_dwordx4 v153, s[70:71]
	s_add_u32 s70, s36, 0x80000
	s_addc_u32 s71, s37, 0
	s_add_i32 s65, s69, s97
	s_mov_b32 m0, s65
	s_nop 0
	global_load_lds_dwordx4 v152, s[70:71]
	s_add_i32 m0, s65, 0x2000
	s_nop 0
	global_load_lds_dwordx4 v153, s[70:71]
	s_mov_b64 s[70:71], s[38:39]
	s_mov_b32 m0, s27
	s_nop 0
	global_load_lds_dwordx4 v151, s[70:71]
	s_mov_b32 m0, s29
	s_nop 0
	global_load_lds_dwordx4 v150, s[70:71]
	s_waitcnt vmcnt(8) lgkmcnt(0)
	s_setprio 1
	s_barrier
	v_mfma_f32_16x16x32_bf16 v[60:63], v[112:115], v[168:171], v[60:63]
	v_mfma_f32_16x16x32_bf16 v[60:63], v[120:123], v[172:175], v[60:63]
	v_mfma_f32_16x16x32_bf16 v[56:59], v[128:131], v[168:171], v[56:59]
	v_mfma_f32_16x16x32_bf16 v[56:59], v[132:135], v[172:175], v[56:59]
	v_mfma_f32_16x16x32_bf16 v[52:55], v[112:115], v[176:179], v[52:55]
	v_mfma_f32_16x16x32_bf16 v[52:55], v[120:123], v[180:183], v[52:55]
	v_mfma_f32_16x16x32_bf16 v[44:47], v[128:131], v[176:179], v[44:47]
	v_mfma_f32_16x16x32_bf16 v[44:47], v[132:135], v[180:183], v[44:47]
	v_mfma_f32_16x16x32_bf16 v[36:39], v[112:115], v[184:187], v[36:39]
	v_mfma_f32_16x16x32_bf16 v[36:39], v[120:123], v[188:191], v[36:39]
	v_mfma_f32_16x16x32_bf16 v[28:31], v[128:131], v[184:187], v[28:31]
	v_mfma_f32_16x16x32_bf16 v[28:31], v[132:135], v[188:191], v[28:31]
	v_mfma_f32_16x16x32_bf16 v[20:23], v[112:115], v[192:195], v[20:23]
	v_mfma_f32_16x16x32_bf16 v[20:23], v[120:123], v[200:203], v[20:23]
	v_mfma_f32_16x16x32_bf16 v[8:11], v[128:131], v[192:195], v[8:11]
	v_mfma_f32_16x16x32_bf16 v[8:11], v[132:135], v[200:203], v[8:11]
	v_mfma_f32_16x16x32_bf16 v[48:51], v[144:147], v[168:171], v[48:51]
	v_mfma_f32_16x16x32_bf16 v[48:51], v[156:159], v[172:175], v[48:51]
	v_mfma_f32_16x16x32_bf16 v[40:43], v[160:163], v[168:171], v[40:43]
	v_mfma_f32_16x16x32_bf16 v[40:43], v[164:167], v[172:175], v[40:43]
	v_mfma_f32_16x16x32_bf16 v[32:35], v[144:147], v[176:179], v[32:35]
	v_mfma_f32_16x16x32_bf16 v[32:35], v[156:159], v[180:183], v[32:35]
	v_mfma_f32_16x16x32_bf16 v[24:27], v[160:163], v[176:179], v[24:27]
	v_mfma_f32_16x16x32_bf16 v[24:27], v[164:167], v[180:183], v[24:27]
	v_mfma_f32_16x16x32_bf16 v[16:19], v[144:147], v[184:187], v[16:19]
	v_mfma_f32_16x16x32_bf16 v[16:19], v[156:159], v[188:191], v[16:19]
	v_mfma_f32_16x16x32_bf16 v[12:15], v[160:163], v[184:187], v[12:15]
	v_mfma_f32_16x16x32_bf16 v[12:15], v[164:167], v[188:191], v[12:15]
	v_mfma_f32_16x16x32_bf16 v[4:7], v[144:147], v[192:195], v[4:7]
	v_mfma_f32_16x16x32_bf16 v[4:7], v[156:159], v[200:203], v[4:7]
	v_mfma_f32_16x16x32_bf16 v[0:3], v[160:163], v[192:195], v[0:3]
	v_mfma_f32_16x16x32_bf16 v[0:3], v[164:167], v[200:203], v[0:3]
	s_barrier
	s_setprio 0
	s_add_i32 s65, 0, 0x18000
	s_add_i32 s69, 0, 0x1c000
	v_add_u32_e32 v132, s65, v154
	v_add_u32_e32 v148, s69, v154
	ds_read_b128 v[112:115], v132
	ds_read_b128 v[120:123], v132 offset:1024
	ds_read_b128 v[128:131], v132 offset:2048
	ds_read_b128 v[132:135], v132 offset:3072
	ds_read_b128 v[144:147], v148
	ds_read_b128 v[156:159], v148 offset:1024
	ds_read_b128 v[160:163], v148 offset:2048
	ds_read_b128 v[164:167], v148 offset:3072
	s_add_u32 s38, s38, 0x80000
	s_addc_u32 s39, s39, 0
	s_mov_b32 m0, s31
	ds_read_b128 v[168:171], v155 offset:32768
	ds_read_b128 v[172:175], v155 offset:33792
	ds_read_b128 v[176:179], v155 offset:34816
	ds_read_b128 v[180:183], v155 offset:35840
	ds_read_b128 v[184:187], v155 offset:36864
	ds_read_b128 v[188:191], v155 offset:37888
	ds_read_b128 v[192:195], v155 offset:38912
	ds_read_b128 v[200:203], v155 offset:39936
	s_nop 0
	global_load_lds_dwordx4 v151, s[38:39]
	s_mov_b32 m0, s48
	s_nop 0
	global_load_lds_dwordx4 v150, s[38:39]
	s_waitcnt vmcnt(8) lgkmcnt(0)
	s_setprio 1
	s_barrier
	v_mfma_f32_16x16x32_bf16 v[140:143], v[112:115], v[168:171], v[140:143]
	v_mfma_f32_16x16x32_bf16 v[140:143], v[120:123], v[172:175], v[140:143]
	v_mfma_f32_16x16x32_bf16 v[136:139], v[128:131], v[168:171], v[136:139]
	v_mfma_f32_16x16x32_bf16 v[136:139], v[132:135], v[172:175], v[136:139]
	v_mfma_f32_16x16x32_bf16 v[108:111], v[112:115], v[176:179], v[108:111]
	v_mfma_f32_16x16x32_bf16 v[108:111], v[120:123], v[180:183], v[108:111]
	v_mfma_f32_16x16x32_bf16 v[104:107], v[128:131], v[176:179], v[104:107]
	v_mfma_f32_16x16x32_bf16 v[104:107], v[132:135], v[180:183], v[104:107]
	v_mfma_f32_16x16x32_bf16 v[92:95], v[112:115], v[184:187], v[92:95]
	v_mfma_f32_16x16x32_bf16 v[92:95], v[120:123], v[188:191], v[92:95]
	v_mfma_f32_16x16x32_bf16 v[88:91], v[128:131], v[184:187], v[88:91]
	v_mfma_f32_16x16x32_bf16 v[88:91], v[132:135], v[188:191], v[88:91]
	v_mfma_f32_16x16x32_bf16 v[76:79], v[112:115], v[192:195], v[76:79]
	v_mfma_f32_16x16x32_bf16 v[76:79], v[120:123], v[200:203], v[76:79]
	v_mfma_f32_16x16x32_bf16 v[72:75], v[128:131], v[192:195], v[72:75]
	v_mfma_f32_16x16x32_bf16 v[72:75], v[132:135], v[200:203], v[72:75]
	v_mfma_f32_16x16x32_bf16 v[124:127], v[144:147], v[168:171], v[124:127]
	v_mfma_f32_16x16x32_bf16 v[124:127], v[156:159], v[172:175], v[124:127]
	v_mfma_f32_16x16x32_bf16 v[116:119], v[160:163], v[168:171], v[116:119]
	v_mfma_f32_16x16x32_bf16 v[116:119], v[164:167], v[172:175], v[116:119]
	v_mfma_f32_16x16x32_bf16 v[100:103], v[144:147], v[176:179], v[100:103]
	v_mfma_f32_16x16x32_bf16 v[100:103], v[156:159], v[180:183], v[100:103]
	v_mfma_f32_16x16x32_bf16 v[96:99], v[160:163], v[176:179], v[96:99]
	v_mfma_f32_16x16x32_bf16 v[96:99], v[164:167], v[180:183], v[96:99]
	v_mfma_f32_16x16x32_bf16 v[84:87], v[144:147], v[184:187], v[84:87]
	v_mfma_f32_16x16x32_bf16 v[84:87], v[156:159], v[188:191], v[84:87]
	v_mfma_f32_16x16x32_bf16 v[80:83], v[160:163], v[184:187], v[80:83]
	v_mfma_f32_16x16x32_bf16 v[80:83], v[164:167], v[188:191], v[80:83]
	v_mfma_f32_16x16x32_bf16 v[68:71], v[144:147], v[192:195], v[68:71]
	v_mfma_f32_16x16x32_bf16 v[68:71], v[156:159], v[200:203], v[68:71]
	v_mfma_f32_16x16x32_bf16 v[64:67], v[160:163], v[192:195], v[64:67]
	v_mfma_f32_16x16x32_bf16 v[64:67], v[164:167], v[200:203], v[64:67]
	s_barrier
	s_setprio 0
	s_add_u32 s38, s36, 0x80
	s_addc_u32 s39, s37, 0
	s_add_i32 s65, s65, s97
	s_mov_b32 m0, s65
	ds_read_b128 v[168:171], v155 offset:49152
	ds_read_b128 v[172:175], v155 offset:50176
	ds_read_b128 v[176:179], v155 offset:51200
	ds_read_b128 v[180:183], v155 offset:52224
	ds_read_b128 v[184:187], v155 offset:53248
	ds_read_b128 v[188:191], v155 offset:54272
	ds_read_b128 v[192:195], v155 offset:55296
	ds_read_b128 v[200:203], v155 offset:56320
	s_nop 0
	global_load_lds_dwordx4 v152, s[38:39]
	s_add_i32 m0, s65, 0x2000
	s_add_u32 s36, s36, 0x80080
	s_addc_u32 s37, s37, 0
	global_load_lds_dwordx4 v153, s[38:39]
	s_add_i32 s38, s69, s97
	s_mov_b32 m0, s38
	s_nop 0
	global_load_lds_dwordx4 v152, s[36:37]
	s_add_i32 m0, s38, 0x2000
	s_nop 0
	global_load_lds_dwordx4 v153, s[36:37]
	s_mov_b32 m0, s49
	s_nop 0
	global_load_lds_dwordx4 v151, s[34:35]
	s_mov_b32 m0, s56
	s_nop 0
	global_load_lds_dwordx4 v150, s[34:35]
	s_waitcnt vmcnt(8) lgkmcnt(0)
	s_setprio 1
	s_barrier
	v_mfma_f32_16x16x32_bf16 v[60:63], v[112:115], v[168:171], v[60:63]
	v_mfma_f32_16x16x32_bf16 v[60:63], v[120:123], v[172:175], v[60:63]
	v_mfma_f32_16x16x32_bf16 v[56:59], v[128:131], v[168:171], v[56:59]
	v_mfma_f32_16x16x32_bf16 v[56:59], v[132:135], v[172:175], v[56:59]
	v_mfma_f32_16x16x32_bf16 v[52:55], v[112:115], v[176:179], v[52:55]
	v_mfma_f32_16x16x32_bf16 v[52:55], v[120:123], v[180:183], v[52:55]
	v_mfma_f32_16x16x32_bf16 v[44:47], v[128:131], v[176:179], v[44:47]
	v_mfma_f32_16x16x32_bf16 v[44:47], v[132:135], v[180:183], v[44:47]
	v_mfma_f32_16x16x32_bf16 v[36:39], v[112:115], v[184:187], v[36:39]
	v_mfma_f32_16x16x32_bf16 v[36:39], v[120:123], v[188:191], v[36:39]
	v_mfma_f32_16x16x32_bf16 v[28:31], v[128:131], v[184:187], v[28:31]
	v_mfma_f32_16x16x32_bf16 v[28:31], v[132:135], v[188:191], v[28:31]
	v_mfma_f32_16x16x32_bf16 v[20:23], v[112:115], v[192:195], v[20:23]
	v_mfma_f32_16x16x32_bf16 v[20:23], v[120:123], v[200:203], v[20:23]
	v_mfma_f32_16x16x32_bf16 v[8:11], v[128:131], v[192:195], v[8:11]
	v_mfma_f32_16x16x32_bf16 v[8:11], v[132:135], v[200:203], v[8:11]
	v_mfma_f32_16x16x32_bf16 v[48:51], v[144:147], v[168:171], v[48:51]
	v_mfma_f32_16x16x32_bf16 v[48:51], v[156:159], v[172:175], v[48:51]
	v_mfma_f32_16x16x32_bf16 v[40:43], v[160:163], v[168:171], v[40:43]
	v_mfma_f32_16x16x32_bf16 v[40:43], v[164:167], v[172:175], v[40:43]
	v_mfma_f32_16x16x32_bf16 v[32:35], v[144:147], v[176:179], v[32:35]
	v_mfma_f32_16x16x32_bf16 v[32:35], v[156:159], v[180:183], v[32:35]
	v_mfma_f32_16x16x32_bf16 v[24:27], v[160:163], v[176:179], v[24:27]
	v_mfma_f32_16x16x32_bf16 v[24:27], v[164:167], v[180:183], v[24:27]
	v_mfma_f32_16x16x32_bf16 v[16:19], v[144:147], v[184:187], v[16:19]
	v_mfma_f32_16x16x32_bf16 v[16:19], v[156:159], v[188:191], v[16:19]
	v_mfma_f32_16x16x32_bf16 v[12:15], v[160:163], v[184:187], v[12:15]
	v_mfma_f32_16x16x32_bf16 v[12:15], v[164:167], v[188:191], v[12:15]
	v_mfma_f32_16x16x32_bf16 v[4:7], v[144:147], v[192:195], v[4:7]
	v_mfma_f32_16x16x32_bf16 v[4:7], v[156:159], v[200:203], v[4:7]
	v_mfma_f32_16x16x32_bf16 v[0:3], v[160:163], v[192:195], v[0:3]
	v_mfma_f32_16x16x32_bf16 v[0:3], v[164:167], v[200:203], v[0:3]
	s_barrier
	s_setprio 0
	s_add_i32 s21, s21, 2
	s_add_u32 s4, s4, 0x100
	s_addc_u32 s5, s5, 0
	s_add_u32 s15, s15, 0x100
	s_addc_u32 s17, s17, 0
	s_cmp_gt_u32 s21, 5
	s_cbranch_scc0 .LBB0_604
	s_and_b64 vcc, exec, s[60:61]
	s_cbranch_vccz .LBB0_607
	s_barrier

.LBB0_676:
	s_add_u32 s30, s28, 0x100
	s_addc_u32 s31, s29, 0
	s_cmp_eq_u32 s69, 28
	s_cselect_b32 s38, s5, s30
	s_cselect_b32 s39, s4, s31
	s_cselect_b32 s36, s17, s21
	s_cselect_b32 s37, s13, s27
	s_add_u32 s34, s38, 0x80
	s_addc_u32 s35, s39, 0
	s_add_i32 s74, 0, 0x10000
	s_add_i32 s84, 0, 0x14000
	v_add_u32_e32 v140, s74, v150
	v_add_u32_e32 v144, s84, v150
	ds_read_b128 v[128:131], v140
	ds_read_b128 v[132:135], v140 offset:1024
	ds_read_b128 v[136:139], v140 offset:2048
	ds_read_b128 v[140:143], v140 offset:3072
	ds_read_b128 v[152:155], v144
	ds_read_b128 v[156:159], v144 offset:1024
	ds_read_b128 v[160:163], v144 offset:2048
	ds_read_b128 v[164:167], v144 offset:3072
	s_add_u32 s28, s28, 0x80080
	s_addc_u32 s29, s29, 0
	s_add_i32 m0, s48, 0xc000
	ds_read_b128 v[168:171], v151
	ds_read_b128 v[172:175], v151 offset:1024
	ds_read_b128 v[176:179], v151 offset:2048
	ds_read_b128 v[180:183], v151 offset:3072
	ds_read_b128 v[184:187], v151 offset:4096
	ds_read_b128 v[188:191], v151 offset:5120
	ds_read_b128 v[192:195], v151 offset:6144
	ds_read_b128 v[200:203], v151 offset:7168
	s_nop 0
	global_load_lds_dwordx4 v146, s[28:29]
	s_add_i32 m0, s48, 0xe000
	s_nop 0
	global_load_lds_dwordx4 v148, s[28:29]
	s_waitcnt vmcnt(8) lgkmcnt(0)
	s_setprio 1
	s_barrier
	v_mfma_f32_16x16x32_bf16 v[124:127], v[128:131], v[168:171], v[124:127]
	v_mfma_f32_16x16x32_bf16 v[124:127], v[132:135], v[172:175], v[124:127]
	v_mfma_f32_16x16x32_bf16 v[120:123], v[136:139], v[168:171], v[120:123]
	v_mfma_f32_16x16x32_bf16 v[120:123], v[140:143], v[172:175], v[120:123]
	v_mfma_f32_16x16x32_bf16 v[108:111], v[128:131], v[176:179], v[108:111]
	v_mfma_f32_16x16x32_bf16 v[108:111], v[132:135], v[180:183], v[108:111]
	v_mfma_f32_16x16x32_bf16 v[104:107], v[136:139], v[176:179], v[104:107]
	v_mfma_f32_16x16x32_bf16 v[104:107], v[140:143], v[180:183], v[104:107]
	v_mfma_f32_16x16x32_bf16 v[96:99], v[128:131], v[184:187], v[96:99]
	v_mfma_f32_16x16x32_bf16 v[96:99], v[132:135], v[188:191], v[96:99]
	v_mfma_f32_16x16x32_bf16 v[88:91], v[136:139], v[184:187], v[88:91]
	v_mfma_f32_16x16x32_bf16 v[88:91], v[140:143], v[188:191], v[88:91]
	v_mfma_f32_16x16x32_bf16 v[80:83], v[128:131], v[192:195], v[80:83]
	v_mfma_f32_16x16x32_bf16 v[80:83], v[132:135], v[200:203], v[80:83]
	v_mfma_f32_16x16x32_bf16 v[72:75], v[136:139], v[192:195], v[72:75]
	v_mfma_f32_16x16x32_bf16 v[72:75], v[140:143], v[200:203], v[72:75]
	v_mfma_f32_16x16x32_bf16 v[116:119], v[152:155], v[168:171], v[116:119]
	v_mfma_f32_16x16x32_bf16 v[116:119], v[156:159], v[172:175], v[116:119]
	v_mfma_f32_16x16x32_bf16 v[112:115], v[160:163], v[168:171], v[112:115]
	v_mfma_f32_16x16x32_bf16 v[112:115], v[164:167], v[172:175], v[112:115]
	v_mfma_f32_16x16x32_bf16 v[100:103], v[152:155], v[176:179], v[100:103]
	v_mfma_f32_16x16x32_bf16 v[100:103], v[156:159], v[180:183], v[100:103]
	v_mfma_f32_16x16x32_bf16 v[92:95], v[160:163], v[176:179], v[92:95]
	v_mfma_f32_16x16x32_bf16 v[92:95], v[164:167], v[180:183], v[92:95]
	v_mfma_f32_16x16x32_bf16 v[84:87], v[152:155], v[184:187], v[84:87]
	v_mfma_f32_16x16x32_bf16 v[84:87], v[156:159], v[188:191], v[84:87]
	v_mfma_f32_16x16x32_bf16 v[76:79], v[160:163], v[184:187], v[76:79]
	v_mfma_f32_16x16x32_bf16 v[76:79], v[164:167], v[188:191], v[76:79]
	v_mfma_f32_16x16x32_bf16 v[68:71], v[152:155], v[192:195], v[68:71]
	v_mfma_f32_16x16x32_bf16 v[68:71], v[156:159], v[200:203], v[68:71]
	v_mfma_f32_16x16x32_bf16 v[64:67], v[160:163], v[192:195], v[64:67]
	v_mfma_f32_16x16x32_bf16 v[64:67], v[164:167], v[200:203], v[64:67]
	s_barrier
	s_setprio 0
	s_add_i32 s74, s74, s97
	s_mov_b64 s[28:29], s[36:37]
	s_mov_b32 m0, s74
	ds_read_b128 v[168:171], v151 offset:16384
	ds_read_b128 v[172:175], v151 offset:17408
	ds_read_b128 v[176:179], v151 offset:18432
	ds_read_b128 v[180:183], v151 offset:19456
	ds_read_b128 v[184:187], v151 offset:20480
	ds_read_b128 v[188:191], v151 offset:21504
	ds_read_b128 v[192:195], v151 offset:22528
	ds_read_b128 v[200:203], v151 offset:23552
	s_nop 0
	global_load_lds_dwordx4 v147, s[28:29]
	s_add_i32 m0, s74, 0x2000
	s_nop 0
	global_load_lds_dwordx4 v149, s[28:29]
	s_add_u32 s28, s36, 0x80000
	s_addc_u32 s29, s37, 0
	s_add_i32 s74, s84, s97
	s_mov_b32 m0, s74
	s_nop 0
	global_load_lds_dwordx4 v147, s[28:29]
	s_add_i32 m0, s74, 0x2000
	s_nop 0
	global_load_lds_dwordx4 v149, s[28:29]
	s_mov_b64 s[28:29], s[38:39]
	s_mov_b32 m0, s48
	s_nop 0
	global_load_lds_dwordx4 v146, s[28:29]
	s_mov_b32 m0, s49
	s_nop 0
	global_load_lds_dwordx4 v148, s[28:29]
	s_waitcnt vmcnt(8) lgkmcnt(0)
	s_setprio 1
	s_barrier
	v_mfma_f32_16x16x32_bf16 v[60:63], v[128:131], v[168:171], v[60:63]
	v_mfma_f32_16x16x32_bf16 v[60:63], v[132:135], v[172:175], v[60:63]
	v_mfma_f32_16x16x32_bf16 v[56:59], v[136:139], v[168:171], v[56:59]
	v_mfma_f32_16x16x32_bf16 v[56:59], v[140:143], v[172:175], v[56:59]
	v_mfma_f32_16x16x32_bf16 v[48:51], v[128:131], v[176:179], v[48:51]
	v_mfma_f32_16x16x32_bf16 v[48:51], v[132:135], v[180:183], v[48:51]
	v_mfma_f32_16x16x32_bf16 v[40:43], v[136:139], v[176:179], v[40:43]
	v_mfma_f32_16x16x32_bf16 v[40:43], v[140:143], v[180:183], v[40:43]
	v_mfma_f32_16x16x32_bf16 v[32:35], v[128:131], v[184:187], v[32:35]
	v_mfma_f32_16x16x32_bf16 v[32:35], v[132:135], v[188:191], v[32:35]
	v_mfma_f32_16x16x32_bf16 v[24:27], v[136:139], v[184:187], v[24:27]
	v_mfma_f32_16x16x32_bf16 v[24:27], v[140:143], v[188:191], v[24:27]
	v_mfma_f32_16x16x32_bf16 v[16:19], v[128:131], v[192:195], v[16:19]
	v_mfma_f32_16x16x32_bf16 v[16:19], v[132:135], v[200:203], v[16:19]
	v_mfma_f32_16x16x32_bf16 v[8:11], v[136:139], v[192:195], v[8:11]
	v_mfma_f32_16x16x32_bf16 v[8:11], v[140:143], v[200:203], v[8:11]
	v_mfma_f32_16x16x32_bf16 v[52:55], v[152:155], v[168:171], v[52:55]
	v_mfma_f32_16x16x32_bf16 v[52:55], v[156:159], v[172:175], v[52:55]
	v_mfma_f32_16x16x32_bf16 v[44:47], v[160:163], v[168:171], v[44:47]
	v_mfma_f32_16x16x32_bf16 v[44:47], v[164:167], v[172:175], v[44:47]
	v_mfma_f32_16x16x32_bf16 v[36:39], v[152:155], v[176:179], v[36:39]
	v_mfma_f32_16x16x32_bf16 v[36:39], v[156:159], v[180:183], v[36:39]
	v_mfma_f32_16x16x32_bf16 v[28:31], v[160:163], v[176:179], v[28:31]
	v_mfma_f32_16x16x32_bf16 v[28:31], v[164:167], v[180:183], v[28:31]
	v_mfma_f32_16x16x32_bf16 v[20:23], v[152:155], v[184:187], v[20:23]
	v_mfma_f32_16x16x32_bf16 v[20:23], v[156:159], v[188:191], v[20:23]
	v_mfma_f32_16x16x32_bf16 v[12:15], v[160:163], v[184:187], v[12:15]
	v_mfma_f32_16x16x32_bf16 v[12:15], v[164:167], v[188:191], v[12:15]
	v_mfma_f32_16x16x32_bf16 v[4:7], v[152:155], v[192:195], v[4:7]
	v_mfma_f32_16x16x32_bf16 v[4:7], v[156:159], v[200:203], v[4:7]
	v_mfma_f32_16x16x32_bf16 v[0:3], v[160:163], v[192:195], v[0:3]
	v_mfma_f32_16x16x32_bf16 v[0:3], v[164:167], v[200:203], v[0:3]
	s_barrier
	s_setprio 0
	s_add_i32 s74, 0, 0x18000
	s_add_i32 s84, 0, 0x1c000
	v_add_u32_e32 v140, s74, v150
	v_add_u32_e32 v144, s84, v150
	ds_read_b128 v[128:131], v140
	ds_read_b128 v[132:135], v140 offset:1024
	ds_read_b128 v[136:139], v140 offset:2048
	ds_read_b128 v[140:143], v140 offset:3072
	ds_read_b128 v[152:155], v144
	ds_read_b128 v[156:159], v144 offset:1024
	ds_read_b128 v[160:163], v144 offset:2048
	ds_read_b128 v[164:167], v144 offset:3072
	s_add_u32 s28, s38, 0x80000
	s_addc_u32 s29, s39, 0
	s_mov_b32 m0, s56
	ds_read_b128 v[168:171], v151 offset:32768
	ds_read_b128 v[172:175], v151 offset:33792
	ds_read_b128 v[176:179], v151 offset:34816
	ds_read_b128 v[180:183], v151 offset:35840
	ds_read_b128 v[184:187], v151 offset:36864
	ds_read_b128 v[188:191], v151 offset:37888
	ds_read_b128 v[192:195], v151 offset:38912
	ds_read_b128 v[200:203], v151 offset:39936
	s_nop 0
	global_load_lds_dwordx4 v146, s[28:29]
	s_mov_b32 m0, s57
	s_nop 0
	global_load_lds_dwordx4 v148, s[28:29]
	s_waitcnt vmcnt(8) lgkmcnt(0)
	s_setprio 1
	s_barrier
	v_mfma_f32_16x16x32_bf16 v[124:127], v[128:131], v[168:171], v[124:127]
	v_mfma_f32_16x16x32_bf16 v[124:127], v[132:135], v[172:175], v[124:127]
	v_mfma_f32_16x16x32_bf16 v[120:123], v[136:139], v[168:171], v[120:123]
	v_mfma_f32_16x16x32_bf16 v[120:123], v[140:143], v[172:175], v[120:123]
	v_mfma_f32_16x16x32_bf16 v[108:111], v[128:131], v[176:179], v[108:111]
	v_mfma_f32_16x16x32_bf16 v[108:111], v[132:135], v[180:183], v[108:111]
	v_mfma_f32_16x16x32_bf16 v[104:107], v[136:139], v[176:179], v[104:107]
	v_mfma_f32_16x16x32_bf16 v[104:107], v[140:143], v[180:183], v[104:107]
	v_mfma_f32_16x16x32_bf16 v[96:99], v[128:131], v[184:187], v[96:99]
	v_mfma_f32_16x16x32_bf16 v[96:99], v[132:135], v[188:191], v[96:99]
	v_mfma_f32_16x16x32_bf16 v[88:91], v[136:139], v[184:187], v[88:91]
	v_mfma_f32_16x16x32_bf16 v[88:91], v[140:143], v[188:191], v[88:91]
	v_mfma_f32_16x16x32_bf16 v[80:83], v[128:131], v[192:195], v[80:83]
	v_mfma_f32_16x16x32_bf16 v[80:83], v[132:135], v[200:203], v[80:83]
	v_mfma_f32_16x16x32_bf16 v[72:75], v[136:139], v[192:195], v[72:75]
	v_mfma_f32_16x16x32_bf16 v[72:75], v[140:143], v[200:203], v[72:75]
	v_mfma_f32_16x16x32_bf16 v[116:119], v[152:155], v[168:171], v[116:119]
	v_mfma_f32_16x16x32_bf16 v[116:119], v[156:159], v[172:175], v[116:119]
	v_mfma_f32_16x16x32_bf16 v[112:115], v[160:163], v[168:171], v[112:115]
	v_mfma_f32_16x16x32_bf16 v[112:115], v[164:167], v[172:175], v[112:115]
	v_mfma_f32_16x16x32_bf16 v[100:103], v[152:155], v[176:179], v[100:103]
	v_mfma_f32_16x16x32_bf16 v[100:103], v[156:159], v[180:183], v[100:103]
	v_mfma_f32_16x16x32_bf16 v[92:95], v[160:163], v[176:179], v[92:95]
	v_mfma_f32_16x16x32_bf16 v[92:95], v[164:167], v[180:183], v[92:95]
	v_mfma_f32_16x16x32_bf16 v[84:87], v[152:155], v[184:187], v[84:87]
	v_mfma_f32_16x16x32_bf16 v[84:87], v[156:159], v[188:191], v[84:87]
	v_mfma_f32_16x16x32_bf16 v[76:79], v[160:163], v[184:187], v[76:79]
	v_mfma_f32_16x16x32_bf16 v[76:79], v[164:167], v[188:191], v[76:79]
	v_mfma_f32_16x16x32_bf16 v[68:71], v[152:155], v[192:195], v[68:71]
	v_mfma_f32_16x16x32_bf16 v[68:71], v[156:159], v[200:203], v[68:71]
	v_mfma_f32_16x16x32_bf16 v[64:67], v[160:163], v[192:195], v[64:67]
	v_mfma_f32_16x16x32_bf16 v[64:67], v[164:167], v[200:203], v[64:67]
	s_barrier
	s_setprio 0
	s_add_u32 s28, s36, 0x80
	s_addc_u32 s29, s37, 0
	s_add_i32 s38, s74, s97
	s_mov_b32 m0, s38
	ds_read_b128 v[168:171], v151 offset:49152
	ds_read_b128 v[172:175], v151 offset:50176
	ds_read_b128 v[176:179], v151 offset:51200
	ds_read_b128 v[180:183], v151 offset:52224
	ds_read_b128 v[184:187], v151 offset:53248
	ds_read_b128 v[188:191], v151 offset:54272
	ds_read_b128 v[192:195], v151 offset:55296
	ds_read_b128 v[200:203], v151 offset:56320
	s_nop 0
	global_load_lds_dwordx4 v147, s[28:29]
	s_add_i32 m0, s38, 0x2000
	s_nop 0
	global_load_lds_dwordx4 v149, s[28:29]
	s_add_u32 s28, s36, 0x80080
	s_addc_u32 s29, s37, 0
	s_add_i32 s36, s84, s97
	s_mov_b32 m0, s36
	s_nop 0
	global_load_lds_dwordx4 v147, s[28:29]
	s_add_i32 m0, s36, 0x2000
	s_nop 0
	global_load_lds_dwordx4 v149, s[28:29]
	s_mov_b32 m0, s82
	s_nop 0
	global_load_lds_dwordx4 v146, s[34:35]
	s_mov_b32 m0, s83
	s_nop 0
	global_load_lds_dwordx4 v148, s[34:35]
	s_waitcnt vmcnt(8) lgkmcnt(0)
	s_setprio 1
	s_barrier
	v_mfma_f32_16x16x32_bf16 v[60:63], v[128:131], v[168:171], v[60:63]
	v_mfma_f32_16x16x32_bf16 v[60:63], v[132:135], v[172:175], v[60:63]
	v_mfma_f32_16x16x32_bf16 v[56:59], v[136:139], v[168:171], v[56:59]
	v_mfma_f32_16x16x32_bf16 v[56:59], v[140:143], v[172:175], v[56:59]
	v_mfma_f32_16x16x32_bf16 v[48:51], v[128:131], v[176:179], v[48:51]
	v_mfma_f32_16x16x32_bf16 v[48:51], v[132:135], v[180:183], v[48:51]
	v_mfma_f32_16x16x32_bf16 v[40:43], v[136:139], v[176:179], v[40:43]
	v_mfma_f32_16x16x32_bf16 v[40:43], v[140:143], v[180:183], v[40:43]
	v_mfma_f32_16x16x32_bf16 v[32:35], v[128:131], v[184:187], v[32:35]
	v_mfma_f32_16x16x32_bf16 v[32:35], v[132:135], v[188:191], v[32:35]
	v_mfma_f32_16x16x32_bf16 v[24:27], v[136:139], v[184:187], v[24:27]
	v_mfma_f32_16x16x32_bf16 v[24:27], v[140:143], v[188:191], v[24:27]
	v_mfma_f32_16x16x32_bf16 v[16:19], v[128:131], v[192:195], v[16:19]
	v_mfma_f32_16x16x32_bf16 v[16:19], v[132:135], v[200:203], v[16:19]
	v_mfma_f32_16x16x32_bf16 v[8:11], v[136:139], v[192:195], v[8:11]
	v_mfma_f32_16x16x32_bf16 v[8:11], v[140:143], v[200:203], v[8:11]
	v_mfma_f32_16x16x32_bf16 v[52:55], v[152:155], v[168:171], v[52:55]
	v_mfma_f32_16x16x32_bf16 v[52:55], v[156:159], v[172:175], v[52:55]
	v_mfma_f32_16x16x32_bf16 v[44:47], v[160:163], v[168:171], v[44:47]
	v_mfma_f32_16x16x32_bf16 v[44:47], v[164:167], v[172:175], v[44:47]
	v_mfma_f32_16x16x32_bf16 v[36:39], v[152:155], v[176:179], v[36:39]
	v_mfma_f32_16x16x32_bf16 v[36:39], v[156:159], v[180:183], v[36:39]
	v_mfma_f32_16x16x32_bf16 v[28:31], v[160:163], v[176:179], v[28:31]
	v_mfma_f32_16x16x32_bf16 v[28:31], v[164:167], v[180:183], v[28:31]
	v_mfma_f32_16x16x32_bf16 v[20:23], v[152:155], v[184:187], v[20:23]
	v_mfma_f32_16x16x32_bf16 v[20:23], v[156:159], v[188:191], v[20:23]
	v_mfma_f32_16x16x32_bf16 v[12:15], v[160:163], v[184:187], v[12:15]
	v_mfma_f32_16x16x32_bf16 v[12:15], v[164:167], v[188:191], v[12:15]
	v_mfma_f32_16x16x32_bf16 v[4:7], v[152:155], v[192:195], v[4:7]
	v_mfma_f32_16x16x32_bf16 v[4:7], v[156:159], v[200:203], v[4:7]
	v_mfma_f32_16x16x32_bf16 v[0:3], v[160:163], v[192:195], v[0:3]
	v_mfma_f32_16x16x32_bf16 v[0:3], v[164:167], v[200:203], v[0:3]
	s_barrier
	s_setprio 0
	s_add_i32 s69, s69, 2
	s_add_u32 s21, s21, 0x100
	s_addc_u32 s27, s27, 0
	s_cmp_gt_u32 s69, 29
	s_mov_b64 s[28:29], s[30:31]
	s_cbranch_scc0 .LBB0_676
	s_and_b64 vcc, exec, s[60:61]
	s_cbranch_vccz .LBB0_679
	s_barrier

.LBB0_788:
	s_add_u32 s30, s28, 0x100
	s_addc_u32 s31, s29, 0
	s_cmp_eq_u32 s17, 4
	s_cselect_b32 s38, s20, s30
	s_cselect_b32 s39, s21, s31
	s_cselect_b32 s36, s22, s5
	s_cselect_b32 s37, s23, s15
	s_add_u32 s34, s38, 0x80
	s_addc_u32 s35, s39, 0
	s_add_i32 s83, 0, 0x10000
	s_add_i32 s84, 0, 0x14000
	v_add_u32_e32 v146, s83, v136
	v_add_u32_e32 v162, s84, v136
	ds_read_b128 v[128:131], v146
	ds_read_b128 v[138:141], v146 offset:1024
	ds_read_b128 v[142:145], v146 offset:2048
	ds_read_b128 v[146:149], v146 offset:3072
	ds_read_b128 v[150:153], v162
	ds_read_b128 v[154:157], v162 offset:1024
	ds_read_b128 v[158:161], v162 offset:2048
	ds_read_b128 v[162:165], v162 offset:3072
	s_add_u32 s28, s28, 0x20080
	s_addc_u32 s29, s29, 0
	s_add_i32 m0, s27, 0xc000
	ds_read_b128 v[166:169], v137
	ds_read_b128 v[170:173], v137 offset:1024
	ds_read_b128 v[174:177], v137 offset:2048
	ds_read_b128 v[178:181], v137 offset:3072
	ds_read_b128 v[182:185], v137 offset:4096
	ds_read_b128 v[186:189], v137 offset:5120
	ds_read_b128 v[190:193], v137 offset:6144
	ds_read_b128 v[200:203], v137 offset:7168
	s_nop 0
	global_load_lds_dwordx4 v132, s[28:29]
	s_add_i32 m0, s27, 0xe000
	s_nop 0
	global_load_lds_dwordx4 v134, s[28:29]
	s_waitcnt vmcnt(8) lgkmcnt(0)
	s_setprio 1
	s_barrier
	v_mfma_f32_16x16x32_bf16 v[124:127], v[128:131], v[166:169], v[124:127]
	v_mfma_f32_16x16x32_bf16 v[124:127], v[138:141], v[170:173], v[124:127]
	v_mfma_f32_16x16x32_bf16 v[120:123], v[142:145], v[166:169], v[120:123]
	v_mfma_f32_16x16x32_bf16 v[120:123], v[146:149], v[170:173], v[120:123]
	v_mfma_f32_16x16x32_bf16 v[108:111], v[128:131], v[174:177], v[108:111]
	v_mfma_f32_16x16x32_bf16 v[108:111], v[138:141], v[178:181], v[108:111]
	v_mfma_f32_16x16x32_bf16 v[104:107], v[142:145], v[174:177], v[104:107]
	v_mfma_f32_16x16x32_bf16 v[104:107], v[146:149], v[178:181], v[104:107]
	v_mfma_f32_16x16x32_bf16 v[92:95], v[128:131], v[182:185], v[92:95]
	v_mfma_f32_16x16x32_bf16 v[92:95], v[138:141], v[186:189], v[92:95]
	v_mfma_f32_16x16x32_bf16 v[88:91], v[142:145], v[182:185], v[88:91]
	v_mfma_f32_16x16x32_bf16 v[88:91], v[146:149], v[186:189], v[88:91]
	v_mfma_f32_16x16x32_bf16 v[76:79], v[128:131], v[190:193], v[76:79]
	v_mfma_f32_16x16x32_bf16 v[76:79], v[138:141], v[200:203], v[76:79]
	v_mfma_f32_16x16x32_bf16 v[72:75], v[142:145], v[190:193], v[72:75]
	v_mfma_f32_16x16x32_bf16 v[72:75], v[146:149], v[200:203], v[72:75]
	v_mfma_f32_16x16x32_bf16 v[116:119], v[150:153], v[166:169], v[116:119]
	v_mfma_f32_16x16x32_bf16 v[116:119], v[154:157], v[170:173], v[116:119]
	v_mfma_f32_16x16x32_bf16 v[112:115], v[158:161], v[166:169], v[112:115]
	v_mfma_f32_16x16x32_bf16 v[112:115], v[162:165], v[170:173], v[112:115]
	v_mfma_f32_16x16x32_bf16 v[100:103], v[150:153], v[174:177], v[100:103]
	v_mfma_f32_16x16x32_bf16 v[100:103], v[154:157], v[178:181], v[100:103]
	v_mfma_f32_16x16x32_bf16 v[96:99], v[158:161], v[174:177], v[96:99]
	v_mfma_f32_16x16x32_bf16 v[96:99], v[162:165], v[178:181], v[96:99]
	v_mfma_f32_16x16x32_bf16 v[84:87], v[150:153], v[182:185], v[84:87]
	v_mfma_f32_16x16x32_bf16 v[84:87], v[154:157], v[186:189], v[84:87]
	v_mfma_f32_16x16x32_bf16 v[80:83], v[158:161], v[182:185], v[80:83]
	v_mfma_f32_16x16x32_bf16 v[80:83], v[162:165], v[186:189], v[80:83]
	v_mfma_f32_16x16x32_bf16 v[68:71], v[150:153], v[190:193], v[68:71]
	v_mfma_f32_16x16x32_bf16 v[68:71], v[154:157], v[200:203], v[68:71]
	v_mfma_f32_16x16x32_bf16 v[64:67], v[158:161], v[190:193], v[64:67]
	v_mfma_f32_16x16x32_bf16 v[64:67], v[162:165], v[200:203], v[64:67]
	s_barrier
	s_setprio 0
	s_add_i32 s83, s83, s97
	s_mov_b64 s[28:29], s[36:37]
	s_mov_b32 m0, s83
	ds_read_b128 v[166:169], v137 offset:16384
	ds_read_b128 v[170:173], v137 offset:17408
	ds_read_b128 v[174:177], v137 offset:18432
	ds_read_b128 v[178:181], v137 offset:19456
	ds_read_b128 v[182:185], v137 offset:20480
	ds_read_b128 v[186:189], v137 offset:21504
	ds_read_b128 v[190:193], v137 offset:22528
	ds_read_b128 v[200:203], v137 offset:23552
	s_nop 0
	global_load_lds_dwordx4 v133, s[28:29]
	s_add_i32 m0, s83, 0x2000
	s_nop 0
	global_load_lds_dwordx4 v135, s[28:29]
	s_add_u32 s28, s36, 0x20000
	s_addc_u32 s29, s37, 0
	s_add_i32 s83, s84, s97
	s_mov_b32 m0, s83
	s_nop 0
	global_load_lds_dwordx4 v133, s[28:29]
	s_add_i32 m0, s83, 0x2000
	s_nop 0
	global_load_lds_dwordx4 v135, s[28:29]
	s_mov_b64 s[28:29], s[38:39]
	s_mov_b32 m0, s27
	s_nop 0
	global_load_lds_dwordx4 v132, s[28:29]
	s_mov_b32 m0, s69
	s_nop 0
	global_load_lds_dwordx4 v134, s[28:29]
	s_waitcnt vmcnt(8) lgkmcnt(0)
	s_setprio 1
	s_barrier
	v_mfma_f32_16x16x32_bf16 v[60:63], v[128:131], v[166:169], v[60:63]
	v_mfma_f32_16x16x32_bf16 v[60:63], v[138:141], v[170:173], v[60:63]
	v_mfma_f32_16x16x32_bf16 v[56:59], v[142:145], v[166:169], v[56:59]
	v_mfma_f32_16x16x32_bf16 v[56:59], v[146:149], v[170:173], v[56:59]
	v_mfma_f32_16x16x32_bf16 v[44:47], v[128:131], v[174:177], v[44:47]
	v_mfma_f32_16x16x32_bf16 v[44:47], v[138:141], v[178:181], v[44:47]
	v_mfma_f32_16x16x32_bf16 v[40:43], v[142:145], v[174:177], v[40:43]
	v_mfma_f32_16x16x32_bf16 v[40:43], v[146:149], v[178:181], v[40:43]
	v_mfma_f32_16x16x32_bf16 v[28:31], v[128:131], v[182:185], v[28:31]
	v_mfma_f32_16x16x32_bf16 v[28:31], v[138:141], v[186:189], v[28:31]
	v_mfma_f32_16x16x32_bf16 v[24:27], v[142:145], v[182:185], v[24:27]
	v_mfma_f32_16x16x32_bf16 v[24:27], v[146:149], v[186:189], v[24:27]
	v_mfma_f32_16x16x32_bf16 v[12:15], v[128:131], v[190:193], v[12:15]
	v_mfma_f32_16x16x32_bf16 v[12:15], v[138:141], v[200:203], v[12:15]
	v_mfma_f32_16x16x32_bf16 v[8:11], v[142:145], v[190:193], v[8:11]
	v_mfma_f32_16x16x32_bf16 v[8:11], v[146:149], v[200:203], v[8:11]
	v_mfma_f32_16x16x32_bf16 v[52:55], v[150:153], v[166:169], v[52:55]
	v_mfma_f32_16x16x32_bf16 v[52:55], v[154:157], v[170:173], v[52:55]
	v_mfma_f32_16x16x32_bf16 v[48:51], v[158:161], v[166:169], v[48:51]
	v_mfma_f32_16x16x32_bf16 v[48:51], v[162:165], v[170:173], v[48:51]
	v_mfma_f32_16x16x32_bf16 v[36:39], v[150:153], v[174:177], v[36:39]
	v_mfma_f32_16x16x32_bf16 v[36:39], v[154:157], v[178:181], v[36:39]
	v_mfma_f32_16x16x32_bf16 v[32:35], v[158:161], v[174:177], v[32:35]
	v_mfma_f32_16x16x32_bf16 v[32:35], v[162:165], v[178:181], v[32:35]
	v_mfma_f32_16x16x32_bf16 v[20:23], v[150:153], v[182:185], v[20:23]
	v_mfma_f32_16x16x32_bf16 v[20:23], v[154:157], v[186:189], v[20:23]
	v_mfma_f32_16x16x32_bf16 v[16:19], v[158:161], v[182:185], v[16:19]
	v_mfma_f32_16x16x32_bf16 v[16:19], v[162:165], v[186:189], v[16:19]
	v_mfma_f32_16x16x32_bf16 v[4:7], v[150:153], v[190:193], v[4:7]
	v_mfma_f32_16x16x32_bf16 v[4:7], v[154:157], v[200:203], v[4:7]
	v_mfma_f32_16x16x32_bf16 v[0:3], v[158:161], v[190:193], v[0:3]
	v_mfma_f32_16x16x32_bf16 v[0:3], v[162:165], v[200:203], v[0:3]
	s_barrier
	s_setprio 0
	s_add_i32 s83, 0, 0x18000
	s_add_i32 s84, 0, 0x1c000
	v_add_u32_e32 v146, s83, v136
	v_add_u32_e32 v162, s84, v136
	ds_read_b128 v[128:131], v146
	ds_read_b128 v[138:141], v146 offset:1024
	ds_read_b128 v[142:145], v146 offset:2048
	ds_read_b128 v[146:149], v146 offset:3072
	ds_read_b128 v[150:153], v162
	ds_read_b128 v[154:157], v162 offset:1024
	ds_read_b128 v[158:161], v162 offset:2048
	ds_read_b128 v[162:165], v162 offset:3072
	s_add_u32 s28, s38, 0x20000
	s_addc_u32 s29, s39, 0
	s_mov_b32 m0, s71
	ds_read_b128 v[166:169], v137 offset:32768
	ds_read_b128 v[170:173], v137 offset:33792
	ds_read_b128 v[174:177], v137 offset:34816
	ds_read_b128 v[178:181], v137 offset:35840
	ds_read_b128 v[182:185], v137 offset:36864
	ds_read_b128 v[186:189], v137 offset:37888
	ds_read_b128 v[190:193], v137 offset:38912
	ds_read_b128 v[200:203], v137 offset:39936
	s_nop 0
	global_load_lds_dwordx4 v132, s[28:29]
	s_mov_b32 m0, s72
	s_nop 0
	global_load_lds_dwordx4 v134, s[28:29]
	s_waitcnt vmcnt(8) lgkmcnt(0)
	s_setprio 1
	s_barrier
	v_mfma_f32_16x16x32_bf16 v[124:127], v[128:131], v[166:169], v[124:127]
	v_mfma_f32_16x16x32_bf16 v[124:127], v[138:141], v[170:173], v[124:127]
	v_mfma_f32_16x16x32_bf16 v[120:123], v[142:145], v[166:169], v[120:123]
	v_mfma_f32_16x16x32_bf16 v[120:123], v[146:149], v[170:173], v[120:123]
	v_mfma_f32_16x16x32_bf16 v[108:111], v[128:131], v[174:177], v[108:111]
	v_mfma_f32_16x16x32_bf16 v[108:111], v[138:141], v[178:181], v[108:111]
	v_mfma_f32_16x16x32_bf16 v[104:107], v[142:145], v[174:177], v[104:107]
	v_mfma_f32_16x16x32_bf16 v[104:107], v[146:149], v[178:181], v[104:107]
	v_mfma_f32_16x16x32_bf16 v[92:95], v[128:131], v[182:185], v[92:95]
	v_mfma_f32_16x16x32_bf16 v[92:95], v[138:141], v[186:189], v[92:95]
	v_mfma_f32_16x16x32_bf16 v[88:91], v[142:145], v[182:185], v[88:91]
	v_mfma_f32_16x16x32_bf16 v[88:91], v[146:149], v[186:189], v[88:91]
	v_mfma_f32_16x16x32_bf16 v[76:79], v[128:131], v[190:193], v[76:79]
	v_mfma_f32_16x16x32_bf16 v[76:79], v[138:141], v[200:203], v[76:79]
	v_mfma_f32_16x16x32_bf16 v[72:75], v[142:145], v[190:193], v[72:75]
	v_mfma_f32_16x16x32_bf16 v[72:75], v[146:149], v[200:203], v[72:75]
	v_mfma_f32_16x16x32_bf16 v[116:119], v[150:153], v[166:169], v[116:119]
	v_mfma_f32_16x16x32_bf16 v[116:119], v[154:157], v[170:173], v[116:119]
	v_mfma_f32_16x16x32_bf16 v[112:115], v[158:161], v[166:169], v[112:115]
	v_mfma_f32_16x16x32_bf16 v[112:115], v[162:165], v[170:173], v[112:115]
	v_mfma_f32_16x16x32_bf16 v[100:103], v[150:153], v[174:177], v[100:103]
	v_mfma_f32_16x16x32_bf16 v[100:103], v[154:157], v[178:181], v[100:103]
	v_mfma_f32_16x16x32_bf16 v[96:99], v[158:161], v[174:177], v[96:99]
	v_mfma_f32_16x16x32_bf16 v[96:99], v[162:165], v[178:181], v[96:99]
	v_mfma_f32_16x16x32_bf16 v[84:87], v[150:153], v[182:185], v[84:87]
	v_mfma_f32_16x16x32_bf16 v[84:87], v[154:157], v[186:189], v[84:87]
	v_mfma_f32_16x16x32_bf16 v[80:83], v[158:161], v[182:185], v[80:83]
	v_mfma_f32_16x16x32_bf16 v[80:83], v[162:165], v[186:189], v[80:83]
	v_mfma_f32_16x16x32_bf16 v[68:71], v[150:153], v[190:193], v[68:71]
	v_mfma_f32_16x16x32_bf16 v[68:71], v[154:157], v[200:203], v[68:71]
	v_mfma_f32_16x16x32_bf16 v[64:67], v[158:161], v[190:193], v[64:67]
	v_mfma_f32_16x16x32_bf16 v[64:67], v[162:165], v[200:203], v[64:67]
	s_barrier
	s_setprio 0
	s_add_u32 s28, s36, 0x80
	s_addc_u32 s29, s37, 0
	s_add_i32 s38, s83, s97
	s_mov_b32 m0, s38
	ds_read_b128 v[166:169], v137 offset:49152
	ds_read_b128 v[170:173], v137 offset:50176
	ds_read_b128 v[174:177], v137 offset:51200
	ds_read_b128 v[178:181], v137 offset:52224
	ds_read_b128 v[182:185], v137 offset:53248
	ds_read_b128 v[186:189], v137 offset:54272
	ds_read_b128 v[190:193], v137 offset:55296
	ds_read_b128 v[200:203], v137 offset:56320
	s_nop 0
	global_load_lds_dwordx4 v133, s[28:29]
	s_add_i32 m0, s38, 0x2000
	s_nop 0
	global_load_lds_dwordx4 v135, s[28:29]
	s_add_u32 s28, s36, 0x20080
	s_addc_u32 s29, s37, 0
	s_add_i32 s36, s84, s97
	s_mov_b32 m0, s36
	s_nop 0
	global_load_lds_dwordx4 v133, s[28:29]
	s_add_i32 m0, s36, 0x2000
	s_nop 0
	global_load_lds_dwordx4 v135, s[28:29]
	s_mov_b32 m0, s80
	s_nop 0
	global_load_lds_dwordx4 v132, s[34:35]
	s_mov_b32 m0, s81
	s_nop 0
	global_load_lds_dwordx4 v134, s[34:35]
	s_waitcnt vmcnt(8) lgkmcnt(0)
	s_setprio 1
	s_barrier
	v_mfma_f32_16x16x32_bf16 v[60:63], v[128:131], v[166:169], v[60:63]
	v_mfma_f32_16x16x32_bf16 v[60:63], v[138:141], v[170:173], v[60:63]
	v_mfma_f32_16x16x32_bf16 v[56:59], v[142:145], v[166:169], v[56:59]
	v_mfma_f32_16x16x32_bf16 v[56:59], v[146:149], v[170:173], v[56:59]
	v_mfma_f32_16x16x32_bf16 v[44:47], v[128:131], v[174:177], v[44:47]
	v_mfma_f32_16x16x32_bf16 v[44:47], v[138:141], v[178:181], v[44:47]
	v_mfma_f32_16x16x32_bf16 v[40:43], v[142:145], v[174:177], v[40:43]
	v_mfma_f32_16x16x32_bf16 v[40:43], v[146:149], v[178:181], v[40:43]
	v_mfma_f32_16x16x32_bf16 v[28:31], v[128:131], v[182:185], v[28:31]
	v_mfma_f32_16x16x32_bf16 v[28:31], v[138:141], v[186:189], v[28:31]
	v_mfma_f32_16x16x32_bf16 v[24:27], v[142:145], v[182:185], v[24:27]
	v_mfma_f32_16x16x32_bf16 v[24:27], v[146:149], v[186:189], v[24:27]
	v_mfma_f32_16x16x32_bf16 v[12:15], v[128:131], v[190:193], v[12:15]
	v_mfma_f32_16x16x32_bf16 v[12:15], v[138:141], v[200:203], v[12:15]
	v_mfma_f32_16x16x32_bf16 v[8:11], v[142:145], v[190:193], v[8:11]
	v_mfma_f32_16x16x32_bf16 v[8:11], v[146:149], v[200:203], v[8:11]
	v_mfma_f32_16x16x32_bf16 v[52:55], v[150:153], v[166:169], v[52:55]
	v_mfma_f32_16x16x32_bf16 v[52:55], v[154:157], v[170:173], v[52:55]
	v_mfma_f32_16x16x32_bf16 v[48:51], v[158:161], v[166:169], v[48:51]
	v_mfma_f32_16x16x32_bf16 v[48:51], v[162:165], v[170:173], v[48:51]
	v_mfma_f32_16x16x32_bf16 v[36:39], v[150:153], v[174:177], v[36:39]
	v_mfma_f32_16x16x32_bf16 v[36:39], v[154:157], v[178:181], v[36:39]
	v_mfma_f32_16x16x32_bf16 v[32:35], v[158:161], v[174:177], v[32:35]
	v_mfma_f32_16x16x32_bf16 v[32:35], v[162:165], v[178:181], v[32:35]
	v_mfma_f32_16x16x32_bf16 v[20:23], v[150:153], v[182:185], v[20:23]
	v_mfma_f32_16x16x32_bf16 v[20:23], v[154:157], v[186:189], v[20:23]
	v_mfma_f32_16x16x32_bf16 v[16:19], v[158:161], v[182:185], v[16:19]
	v_mfma_f32_16x16x32_bf16 v[16:19], v[162:165], v[186:189], v[16:19]
	v_mfma_f32_16x16x32_bf16 v[4:7], v[150:153], v[190:193], v[4:7]
	v_mfma_f32_16x16x32_bf16 v[4:7], v[154:157], v[200:203], v[4:7]
	v_mfma_f32_16x16x32_bf16 v[0:3], v[158:161], v[190:193], v[0:3]
	v_mfma_f32_16x16x32_bf16 v[0:3], v[162:165], v[200:203], v[0:3]
	s_barrier
	s_setprio 0
	s_add_i32 s17, s17, 2
	s_add_u32 s5, s5, 0x100
	s_addc_u32 s15, s15, 0
	s_cmp_gt_u32 s17, 5
	s_mov_b64 s[28:29], s[30:31]
	s_cbranch_scc0 .LBB0_788
	s_and_b64 vcc, exec, s[60:61]
	s_cbranch_vccz .LBB0_791
	s_barrier

.LBB0_1050:
	s_cmp_eq_u32 s83, 28
	s_cselect_b32 s56, s5, s39
	s_cselect_b32 s57, s4, s69
	s_cselect_b32 s84, s37, s72
	s_cselect_b32 s85, s11, s74
	s_add_u32 s12, s56, 0x80
	s_addc_u32 s13, s57, 0
	s_add_i32 vcc_lo, 0, 0x10000
	s_add_i32 vcc_hi, 0, 0x14000
	v_add_u32_e32 v136, vcc_lo, v184
	v_add_u32_e32 v156, vcc_hi, v184
	ds_read_b128 v[104:107], v136
	ds_read_b128 v[108:111], v136 offset:1024
	ds_read_b128 v[132:135], v136 offset:2048
	ds_read_b128 v[136:139], v136 offset:3072
	ds_read_b128 v[144:147], v156
	ds_read_b128 v[148:151], v156 offset:1024
	ds_read_b128 v[152:155], v156 offset:2048
	ds_read_b128 v[156:159], v156 offset:3072
	s_mov_b64 s[86:87], s[8:9]
	s_add_i32 m0, s92, 0xc000
	ds_read_b128 v[160:163], v185
	ds_read_b128 v[164:167], v185 offset:1024
	ds_read_b128 v[168:171], v185 offset:2048
	ds_read_b128 v[172:175], v185 offset:3072
	ds_read_b128 v[186:189], v185 offset:4096
	ds_read_b128 v[190:193], v185 offset:5120
	ds_read_b128 v[200:203], v185 offset:6144
	ds_read_b128 v[204:207], v185 offset:7168
	s_nop 0
	global_load_lds_dwordx4 v179, s[86:87]
	s_add_i32 m0, s92, 0xe000
	s_nop 0
	global_load_lds_dwordx4 v182, s[86:87]
	s_waitcnt vmcnt(8) lgkmcnt(0)
	s_setprio 1
	s_barrier
	v_mfma_f32_16x16x32_bf16 v[140:143], v[104:107], v[160:163], v[140:143]
	v_mfma_f32_16x16x32_bf16 v[140:143], v[108:111], v[164:167], v[140:143]
	v_mfma_f32_16x16x32_bf16 v[128:131], v[132:135], v[160:163], v[128:131]
	v_mfma_f32_16x16x32_bf16 v[128:131], v[136:139], v[164:167], v[128:131]
	v_mfma_f32_16x16x32_bf16 v[124:127], v[104:107], v[168:171], v[124:127]
	v_mfma_f32_16x16x32_bf16 v[124:127], v[108:111], v[172:175], v[124:127]
	v_mfma_f32_16x16x32_bf16 v[112:115], v[132:135], v[168:171], v[112:115]
	v_mfma_f32_16x16x32_bf16 v[112:115], v[136:139], v[172:175], v[112:115]
	v_mfma_f32_16x16x32_bf16 v[96:99], v[104:107], v[186:189], v[96:99]
	v_mfma_f32_16x16x32_bf16 v[96:99], v[108:111], v[190:193], v[96:99]
	v_mfma_f32_16x16x32_bf16 v[88:91], v[132:135], v[186:189], v[88:91]
	v_mfma_f32_16x16x32_bf16 v[88:91], v[136:139], v[190:193], v[88:91]
	v_mfma_f32_16x16x32_bf16 v[84:87], v[104:107], v[200:203], v[84:87]
	v_mfma_f32_16x16x32_bf16 v[84:87], v[108:111], v[204:207], v[84:87]
	v_mfma_f32_16x16x32_bf16 v[72:75], v[132:135], v[200:203], v[72:75]
	v_mfma_f32_16x16x32_bf16 v[72:75], v[136:139], v[204:207], v[72:75]
	v_mfma_f32_16x16x32_bf16 v[120:123], v[144:147], v[160:163], v[120:123]
	v_mfma_f32_16x16x32_bf16 v[120:123], v[148:151], v[164:167], v[120:123]
	v_mfma_f32_16x16x32_bf16 v[116:119], v[152:155], v[160:163], v[116:119]
	v_mfma_f32_16x16x32_bf16 v[116:119], v[156:159], v[164:167], v[116:119]
	v_mfma_f32_16x16x32_bf16 v[100:103], v[144:147], v[168:171], v[100:103]
	v_mfma_f32_16x16x32_bf16 v[100:103], v[148:151], v[172:175], v[100:103]
	v_mfma_f32_16x16x32_bf16 v[92:95], v[152:155], v[168:171], v[92:95]
	v_mfma_f32_16x16x32_bf16 v[92:95], v[156:159], v[172:175], v[92:95]
	v_mfma_f32_16x16x32_bf16 v[80:83], v[144:147], v[186:189], v[80:83]
	v_mfma_f32_16x16x32_bf16 v[80:83], v[148:151], v[190:193], v[80:83]
	v_mfma_f32_16x16x32_bf16 v[76:79], v[152:155], v[186:189], v[76:79]
	v_mfma_f32_16x16x32_bf16 v[76:79], v[156:159], v[190:193], v[76:79]
	v_mfma_f32_16x16x32_bf16 v[68:71], v[144:147], v[200:203], v[68:71]
	v_mfma_f32_16x16x32_bf16 v[68:71], v[148:151], v[204:207], v[68:71]
	v_mfma_f32_16x16x32_bf16 v[64:67], v[152:155], v[200:203], v[64:67]
	v_mfma_f32_16x16x32_bf16 v[64:67], v[156:159], v[204:207], v[64:67]
	s_barrier
	s_setprio 0
	s_add_i32 vcc_lo, vcc_lo, s97
	s_mov_b64 s[86:87], s[84:85]
	s_mov_b32 m0, vcc_lo
	ds_read_b128 v[160:163], v185 offset:16384
	ds_read_b128 v[164:167], v185 offset:17408
	ds_read_b128 v[168:171], v185 offset:18432
	ds_read_b128 v[172:175], v185 offset:19456
	ds_read_b128 v[186:189], v185 offset:20480
	ds_read_b128 v[190:193], v185 offset:21504
	ds_read_b128 v[200:203], v185 offset:22528
	ds_read_b128 v[204:207], v185 offset:23552
	s_nop 0
	global_load_lds_dwordx4 v181, s[86:87]
	s_add_i32 m0, vcc_lo, 0x2000
	s_nop 0
	global_load_lds_dwordx4 v183, s[86:87]
	s_add_u32 s86, s84, 0x80000
	s_addc_u32 s87, s85, 0
	s_add_i32 vcc_lo, vcc_hi, s97
	s_mov_b32 m0, vcc_lo
	s_nop 0
	global_load_lds_dwordx4 v181, s[86:87]
	s_add_i32 m0, vcc_lo, 0x2000
	s_nop 0
	global_load_lds_dwordx4 v183, s[86:87]
	s_mov_b64 s[86:87], s[56:57]
	s_mov_b32 m0, s92
	s_nop 0
	global_load_lds_dwordx4 v179, s[86:87]
	s_mov_b32 m0, s93
	s_nop 0
	global_load_lds_dwordx4 v182, s[86:87]
	s_waitcnt vmcnt(8) lgkmcnt(0)
	s_setprio 1
	s_barrier
	v_mfma_f32_16x16x32_bf16 v[60:63], v[104:107], v[160:163], v[60:63]
	v_mfma_f32_16x16x32_bf16 v[60:63], v[108:111], v[164:167], v[60:63]
	v_mfma_f32_16x16x32_bf16 v[56:59], v[132:135], v[160:163], v[56:59]
	v_mfma_f32_16x16x32_bf16 v[56:59], v[136:139], v[164:167], v[56:59]
	v_mfma_f32_16x16x32_bf16 v[48:51], v[104:107], v[168:171], v[48:51]
	v_mfma_f32_16x16x32_bf16 v[48:51], v[108:111], v[172:175], v[48:51]
	v_mfma_f32_16x16x32_bf16 v[40:43], v[132:135], v[168:171], v[40:43]
	v_mfma_f32_16x16x32_bf16 v[40:43], v[136:139], v[172:175], v[40:43]
	v_mfma_f32_16x16x32_bf16 v[32:35], v[104:107], v[186:189], v[32:35]
	v_mfma_f32_16x16x32_bf16 v[32:35], v[108:111], v[190:193], v[32:35]
	v_mfma_f32_16x16x32_bf16 v[24:27], v[132:135], v[186:189], v[24:27]
	v_mfma_f32_16x16x32_bf16 v[24:27], v[136:139], v[190:193], v[24:27]
	v_mfma_f32_16x16x32_bf16 v[16:19], v[104:107], v[200:203], v[16:19]
	v_mfma_f32_16x16x32_bf16 v[16:19], v[108:111], v[204:207], v[16:19]
	v_mfma_f32_16x16x32_bf16 v[8:11], v[132:135], v[200:203], v[8:11]
	v_mfma_f32_16x16x32_bf16 v[8:11], v[136:139], v[204:207], v[8:11]
	v_mfma_f32_16x16x32_bf16 v[52:55], v[144:147], v[160:163], v[52:55]
	v_mfma_f32_16x16x32_bf16 v[52:55], v[148:151], v[164:167], v[52:55]
	v_mfma_f32_16x16x32_bf16 v[44:47], v[152:155], v[160:163], v[44:47]
	v_mfma_f32_16x16x32_bf16 v[44:47], v[156:159], v[164:167], v[44:47]
	v_mfma_f32_16x16x32_bf16 v[36:39], v[144:147], v[168:171], v[36:39]
	v_mfma_f32_16x16x32_bf16 v[36:39], v[148:151], v[172:175], v[36:39]
	v_mfma_f32_16x16x32_bf16 v[28:31], v[152:155], v[168:171], v[28:31]
	v_mfma_f32_16x16x32_bf16 v[28:31], v[156:159], v[172:175], v[28:31]
	v_mfma_f32_16x16x32_bf16 v[20:23], v[144:147], v[186:189], v[20:23]
	v_mfma_f32_16x16x32_bf16 v[20:23], v[148:151], v[190:193], v[20:23]
	v_mfma_f32_16x16x32_bf16 v[12:15], v[152:155], v[186:189], v[12:15]
	v_mfma_f32_16x16x32_bf16 v[12:15], v[156:159], v[190:193], v[12:15]
	v_mfma_f32_16x16x32_bf16 v[4:7], v[144:147], v[200:203], v[4:7]
	v_mfma_f32_16x16x32_bf16 v[4:7], v[148:151], v[204:207], v[4:7]
	v_mfma_f32_16x16x32_bf16 v[0:3], v[152:155], v[200:203], v[0:3]
	v_mfma_f32_16x16x32_bf16 v[0:3], v[156:159], v[204:207], v[0:3]
	s_barrier
	s_setprio 0
	s_add_i32 s86, 0, 0x18000
	s_add_i32 s87, 0, 0x1c000
	v_add_u32_e32 v136, s86, v184
	v_add_u32_e32 v156, s87, v184
	ds_read_b128 v[104:107], v136
	ds_read_b128 v[108:111], v136 offset:1024
	ds_read_b128 v[132:135], v136 offset:2048
	ds_read_b128 v[136:139], v136 offset:3072
	ds_read_b128 v[144:147], v156
	ds_read_b128 v[148:151], v156 offset:1024
	ds_read_b128 v[152:155], v156 offset:2048
	ds_read_b128 v[156:159], v156 offset:3072
	s_add_u32 s56, s56, 0x80000
	s_addc_u32 s57, s57, 0
	s_mov_b32 m0, s80
	ds_read_b128 v[160:163], v185 offset:32768
	ds_read_b128 v[164:167], v185 offset:33792
	ds_read_b128 v[168:171], v185 offset:34816
	ds_read_b128 v[172:175], v185 offset:35840
	ds_read_b128 v[186:189], v185 offset:36864
	ds_read_b128 v[190:193], v185 offset:37888
	ds_read_b128 v[200:203], v185 offset:38912
	ds_read_b128 v[204:207], v185 offset:39936
	s_nop 0
	global_load_lds_dwordx4 v179, s[56:57]
	s_mov_b32 m0, s48
	s_nop 0
	global_load_lds_dwordx4 v182, s[56:57]
	s_waitcnt vmcnt(8) lgkmcnt(0)
	s_setprio 1
	s_barrier
	v_mfma_f32_16x16x32_bf16 v[140:143], v[104:107], v[160:163], v[140:143]
	v_mfma_f32_16x16x32_bf16 v[140:143], v[108:111], v[164:167], v[140:143]
	v_mfma_f32_16x16x32_bf16 v[128:131], v[132:135], v[160:163], v[128:131]
	v_mfma_f32_16x16x32_bf16 v[128:131], v[136:139], v[164:167], v[128:131]
	v_mfma_f32_16x16x32_bf16 v[124:127], v[104:107], v[168:171], v[124:127]
	v_mfma_f32_16x16x32_bf16 v[124:127], v[108:111], v[172:175], v[124:127]
	v_mfma_f32_16x16x32_bf16 v[112:115], v[132:135], v[168:171], v[112:115]
	v_mfma_f32_16x16x32_bf16 v[112:115], v[136:139], v[172:175], v[112:115]
	v_mfma_f32_16x16x32_bf16 v[96:99], v[104:107], v[186:189], v[96:99]
	v_mfma_f32_16x16x32_bf16 v[96:99], v[108:111], v[190:193], v[96:99]
	v_mfma_f32_16x16x32_bf16 v[88:91], v[132:135], v[186:189], v[88:91]
	v_mfma_f32_16x16x32_bf16 v[88:91], v[136:139], v[190:193], v[88:91]
	v_mfma_f32_16x16x32_bf16 v[84:87], v[104:107], v[200:203], v[84:87]
	v_mfma_f32_16x16x32_bf16 v[84:87], v[108:111], v[204:207], v[84:87]
	v_mfma_f32_16x16x32_bf16 v[72:75], v[132:135], v[200:203], v[72:75]
	v_mfma_f32_16x16x32_bf16 v[72:75], v[136:139], v[204:207], v[72:75]
	v_mfma_f32_16x16x32_bf16 v[120:123], v[144:147], v[160:163], v[120:123]
	v_mfma_f32_16x16x32_bf16 v[120:123], v[148:151], v[164:167], v[120:123]
	v_mfma_f32_16x16x32_bf16 v[116:119], v[152:155], v[160:163], v[116:119]
	v_mfma_f32_16x16x32_bf16 v[116:119], v[156:159], v[164:167], v[116:119]
	v_mfma_f32_16x16x32_bf16 v[100:103], v[144:147], v[168:171], v[100:103]
	v_mfma_f32_16x16x32_bf16 v[100:103], v[148:151], v[172:175], v[100:103]
	v_mfma_f32_16x16x32_bf16 v[92:95], v[152:155], v[168:171], v[92:95]
	v_mfma_f32_16x16x32_bf16 v[92:95], v[156:159], v[172:175], v[92:95]
	v_mfma_f32_16x16x32_bf16 v[80:83], v[144:147], v[186:189], v[80:83]
	v_mfma_f32_16x16x32_bf16 v[80:83], v[148:151], v[190:193], v[80:83]
	v_mfma_f32_16x16x32_bf16 v[76:79], v[152:155], v[186:189], v[76:79]
	v_mfma_f32_16x16x32_bf16 v[76:79], v[156:159], v[190:193], v[76:79]
	v_mfma_f32_16x16x32_bf16 v[68:71], v[144:147], v[200:203], v[68:71]
	v_mfma_f32_16x16x32_bf16 v[68:71], v[148:151], v[204:207], v[68:71]
	v_mfma_f32_16x16x32_bf16 v[64:67], v[152:155], v[200:203], v[64:67]
	v_mfma_f32_16x16x32_bf16 v[64:67], v[156:159], v[204:207], v[64:67]
	s_barrier
	s_setprio 0
	s_add_u32 s56, s84, 0x80
	s_addc_u32 s57, s85, 0
	s_add_i32 s86, s86, s97
	s_mov_b32 m0, s86
	ds_read_b128 v[160:163], v185 offset:49152
	ds_read_b128 v[164:167], v185 offset:50176
	ds_read_b128 v[168:171], v185 offset:51200
	ds_read_b128 v[172:175], v185 offset:52224
	ds_read_b128 v[186:189], v185 offset:53248
	ds_read_b128 v[190:193], v185 offset:54272
	ds_read_b128 v[200:203], v185 offset:55296
	ds_read_b128 v[204:207], v185 offset:56320
	s_nop 0
	global_load_lds_dwordx4 v181, s[56:57]
	s_add_i32 m0, s86, 0x2000
	s_nop 0
	global_load_lds_dwordx4 v183, s[56:57]
	s_add_u32 s56, s84, 0x80080
	s_addc_u32 s57, s85, 0
	s_add_i32 s84, s87, s97
	s_mov_b32 m0, s84
	s_nop 0
	global_load_lds_dwordx4 v181, s[56:57]
	s_add_i32 m0, s84, 0x2000
	s_nop 0
	global_load_lds_dwordx4 v183, s[56:57]
	s_mov_b32 m0, s81
	s_nop 0
	global_load_lds_dwordx4 v179, s[12:13]
	s_mov_b32 m0, s70
	s_nop 0
	global_load_lds_dwordx4 v182, s[12:13]
	s_waitcnt vmcnt(8) lgkmcnt(0)
	s_setprio 1
	s_barrier
	v_mfma_f32_16x16x32_bf16 v[60:63], v[104:107], v[160:163], v[60:63]
	v_mfma_f32_16x16x32_bf16 v[60:63], v[108:111], v[164:167], v[60:63]
	v_mfma_f32_16x16x32_bf16 v[56:59], v[132:135], v[160:163], v[56:59]
	v_mfma_f32_16x16x32_bf16 v[56:59], v[136:139], v[164:167], v[56:59]
	v_mfma_f32_16x16x32_bf16 v[48:51], v[104:107], v[168:171], v[48:51]
	v_mfma_f32_16x16x32_bf16 v[48:51], v[108:111], v[172:175], v[48:51]
	v_mfma_f32_16x16x32_bf16 v[40:43], v[132:135], v[168:171], v[40:43]
	v_mfma_f32_16x16x32_bf16 v[40:43], v[136:139], v[172:175], v[40:43]
	v_mfma_f32_16x16x32_bf16 v[32:35], v[104:107], v[186:189], v[32:35]
	v_mfma_f32_16x16x32_bf16 v[32:35], v[108:111], v[190:193], v[32:35]
	v_mfma_f32_16x16x32_bf16 v[24:27], v[132:135], v[186:189], v[24:27]
	v_mfma_f32_16x16x32_bf16 v[24:27], v[136:139], v[190:193], v[24:27]
	v_mfma_f32_16x16x32_bf16 v[16:19], v[104:107], v[200:203], v[16:19]
	v_mfma_f32_16x16x32_bf16 v[16:19], v[108:111], v[204:207], v[16:19]
	v_mfma_f32_16x16x32_bf16 v[8:11], v[132:135], v[200:203], v[8:11]
	v_mfma_f32_16x16x32_bf16 v[8:11], v[136:139], v[204:207], v[8:11]
	v_mfma_f32_16x16x32_bf16 v[52:55], v[144:147], v[160:163], v[52:55]
	v_mfma_f32_16x16x32_bf16 v[52:55], v[148:151], v[164:167], v[52:55]
	v_mfma_f32_16x16x32_bf16 v[44:47], v[152:155], v[160:163], v[44:47]
	v_mfma_f32_16x16x32_bf16 v[44:47], v[156:159], v[164:167], v[44:47]
	v_mfma_f32_16x16x32_bf16 v[36:39], v[144:147], v[168:171], v[36:39]
	v_mfma_f32_16x16x32_bf16 v[36:39], v[148:151], v[172:175], v[36:39]
	v_mfma_f32_16x16x32_bf16 v[28:31], v[152:155], v[168:171], v[28:31]
	v_mfma_f32_16x16x32_bf16 v[28:31], v[156:159], v[172:175], v[28:31]
	v_mfma_f32_16x16x32_bf16 v[20:23], v[144:147], v[186:189], v[20:23]
	v_mfma_f32_16x16x32_bf16 v[20:23], v[148:151], v[190:193], v[20:23]
	v_mfma_f32_16x16x32_bf16 v[12:15], v[152:155], v[186:189], v[12:15]
	v_mfma_f32_16x16x32_bf16 v[12:15], v[156:159], v[190:193], v[12:15]
	v_mfma_f32_16x16x32_bf16 v[4:7], v[144:147], v[200:203], v[4:7]
	v_mfma_f32_16x16x32_bf16 v[4:7], v[148:151], v[204:207], v[4:7]
	v_mfma_f32_16x16x32_bf16 v[0:3], v[152:155], v[200:203], v[0:3]
	v_mfma_f32_16x16x32_bf16 v[0:3], v[156:159], v[204:207], v[0:3]
	s_barrier
	s_setprio 0
	s_add_i32 s83, s83, 2
	s_add_u32 s39, s39, 0x100
	s_addc_u32 s69, s69, 0
	s_add_u32 s72, s72, 0x100
	s_addc_u32 s74, s74, 0
	s_add_u32 s8, s8, 0x100
	s_addc_u32 s9, s9, 0
	s_cmp_gt_u32 s83, 29
	s_cbranch_scc0 .LBB0_1050
	s_and_b64 vcc, exec, s[60:61]
	s_cbranch_vccz .LBB0_1053
	s_barrier

.LBB0_1127:
	s_cmp_eq_u32 s21, 4
	s_cselect_b32 s38, s22, s4
	s_cselect_b32 s39, s23, s5
	s_cselect_b32 s36, s24, s15
	s_cselect_b32 s37, s25, s17
	s_add_u32 s34, s38, 0x80
	s_addc_u32 s35, s39, 0
	s_add_i32 s65, 0, 0x10000
	s_add_i32 s69, 0, 0x14000
	v_add_u32_e32 v132, s65, v154
	v_add_u32_e32 v148, s69, v154
	ds_read_b128 v[112:115], v132
	ds_read_b128 v[120:123], v132 offset:1024
	ds_read_b128 v[128:131], v132 offset:2048
	ds_read_b128 v[132:135], v132 offset:3072
	ds_read_b128 v[144:147], v148
	ds_read_b128 v[156:159], v148 offset:1024
	ds_read_b128 v[160:163], v148 offset:2048
	ds_read_b128 v[164:167], v148 offset:3072
	s_add_u32 s56, s4, 0x7ff80
	s_addc_u32 s57, s5, 0
	s_add_i32 m0, s27, 0xc000
	ds_read_b128 v[168:171], v155
	ds_read_b128 v[172:175], v155 offset:1024
	ds_read_b128 v[176:179], v155 offset:2048
	ds_read_b128 v[180:183], v155 offset:3072
	ds_read_b128 v[184:187], v155 offset:4096
	ds_read_b128 v[188:191], v155 offset:5120
	ds_read_b128 v[192:195], v155 offset:6144
	ds_read_b128 v[200:203], v155 offset:7168
	s_nop 0
	global_load_lds_dwordx4 v151, s[56:57]
	s_add_i32 m0, s27, 0xe000
	s_nop 0
	global_load_lds_dwordx4 v150, s[56:57]
	s_waitcnt vmcnt(8) lgkmcnt(0)
	s_setprio 1
	s_barrier
	v_mfma_f32_16x16x32_bf16 v[140:143], v[112:115], v[168:171], v[140:143]
	v_mfma_f32_16x16x32_bf16 v[140:143], v[120:123], v[172:175], v[140:143]
	v_mfma_f32_16x16x32_bf16 v[136:139], v[128:131], v[168:171], v[136:139]
	v_mfma_f32_16x16x32_bf16 v[136:139], v[132:135], v[172:175], v[136:139]
	v_mfma_f32_16x16x32_bf16 v[108:111], v[112:115], v[176:179], v[108:111]
	v_mfma_f32_16x16x32_bf16 v[108:111], v[120:123], v[180:183], v[108:111]
	v_mfma_f32_16x16x32_bf16 v[104:107], v[128:131], v[176:179], v[104:107]
	v_mfma_f32_16x16x32_bf16 v[104:107], v[132:135], v[180:183], v[104:107]
	v_mfma_f32_16x16x32_bf16 v[92:95], v[112:115], v[184:187], v[92:95]
	v_mfma_f32_16x16x32_bf16 v[92:95], v[120:123], v[188:191], v[92:95]
	v_mfma_f32_16x16x32_bf16 v[88:91], v[128:131], v[184:187], v[88:91]
	v_mfma_f32_16x16x32_bf16 v[88:91], v[132:135], v[188:191], v[88:91]
	v_mfma_f32_16x16x32_bf16 v[76:79], v[112:115], v[192:195], v[76:79]
	v_mfma_f32_16x16x32_bf16 v[76:79], v[120:123], v[200:203], v[76:79]
	v_mfma_f32_16x16x32_bf16 v[72:75], v[128:131], v[192:195], v[72:75]
	v_mfma_f32_16x16x32_bf16 v[72:75], v[132:135], v[200:203], v[72:75]
	v_mfma_f32_16x16x32_bf16 v[124:127], v[144:147], v[168:171], v[124:127]
	v_mfma_f32_16x16x32_bf16 v[124:127], v[156:159], v[172:175], v[124:127]
	v_mfma_f32_16x16x32_bf16 v[116:119], v[160:163], v[168:171], v[116:119]
	v_mfma_f32_16x16x32_bf16 v[116:119], v[164:167], v[172:175], v[116:119]
	v_mfma_f32_16x16x32_bf16 v[100:103], v[144:147], v[176:179], v[100:103]
	v_mfma_f32_16x16x32_bf16 v[100:103], v[156:159], v[180:183], v[100:103]
	v_mfma_f32_16x16x32_bf16 v[96:99], v[160:163], v[176:179], v[96:99]
	v_mfma_f32_16x16x32_bf16 v[96:99], v[164:167], v[180:183], v[96:99]
	v_mfma_f32_16x16x32_bf16 v[84:87], v[144:147], v[184:187], v[84:87]
	v_mfma_f32_16x16x32_bf16 v[84:87], v[156:159], v[188:191], v[84:87]
	v_mfma_f32_16x16x32_bf16 v[80:83], v[160:163], v[184:187], v[80:83]
	v_mfma_f32_16x16x32_bf16 v[80:83], v[164:167], v[188:191], v[80:83]
	v_mfma_f32_16x16x32_bf16 v[68:71], v[144:147], v[192:195], v[68:71]
	v_mfma_f32_16x16x32_bf16 v[68:71], v[156:159], v[200:203], v[68:71]
	v_mfma_f32_16x16x32_bf16 v[64:67], v[160:163], v[192:195], v[64:67]
	v_mfma_f32_16x16x32_bf16 v[64:67], v[164:167], v[200:203], v[64:67]
	s_barrier
	s_setprio 0
	s_add_i32 s65, s65, s97
	s_mov_b64 s[56:57], s[36:37]
	s_mov_b32 m0, s65
	ds_read_b128 v[168:171], v155 offset:16384
	ds_read_b128 v[172:175], v155 offset:17408
	ds_read_b128 v[176:179], v155 offset:18432
	ds_read_b128 v[180:183], v155 offset:19456
	ds_read_b128 v[184:187], v155 offset:20480
	ds_read_b128 v[188:191], v155 offset:21504
	ds_read_b128 v[192:195], v155 offset:22528
	ds_read_b128 v[200:203], v155 offset:23552
	s_nop 0
	global_load_lds_dwordx4 v152, s[56:57]
	s_add_i32 m0, s65, 0x2000
	s_nop 0
	global_load_lds_dwordx4 v153, s[56:57]
	s_add_u32 s56, s36, 0x80000
	s_addc_u32 s57, s37, 0
	s_add_i32 s65, s69, s97
	s_mov_b32 m0, s65
	s_nop 0
	global_load_lds_dwordx4 v152, s[56:57]
	s_add_i32 m0, s65, 0x2000
	s_nop 0
	global_load_lds_dwordx4 v153, s[56:57]
	s_mov_b64 s[56:57], s[38:39]
	s_mov_b32 m0, s27
	s_nop 0
	global_load_lds_dwordx4 v151, s[56:57]
	s_mov_b32 m0, s29
	s_nop 0
	global_load_lds_dwordx4 v150, s[56:57]
	s_waitcnt vmcnt(8) lgkmcnt(0)
	s_setprio 1
	s_barrier
	v_mfma_f32_16x16x32_bf16 v[60:63], v[112:115], v[168:171], v[60:63]
	v_mfma_f32_16x16x32_bf16 v[60:63], v[120:123], v[172:175], v[60:63]
	v_mfma_f32_16x16x32_bf16 v[56:59], v[128:131], v[168:171], v[56:59]
	v_mfma_f32_16x16x32_bf16 v[56:59], v[132:135], v[172:175], v[56:59]
	v_mfma_f32_16x16x32_bf16 v[52:55], v[112:115], v[176:179], v[52:55]
	v_mfma_f32_16x16x32_bf16 v[52:55], v[120:123], v[180:183], v[52:55]
	v_mfma_f32_16x16x32_bf16 v[44:47], v[128:131], v[176:179], v[44:47]
	v_mfma_f32_16x16x32_bf16 v[44:47], v[132:135], v[180:183], v[44:47]
	v_mfma_f32_16x16x32_bf16 v[36:39], v[112:115], v[184:187], v[36:39]
	v_mfma_f32_16x16x32_bf16 v[36:39], v[120:123], v[188:191], v[36:39]
	v_mfma_f32_16x16x32_bf16 v[28:31], v[128:131], v[184:187], v[28:31]
	v_mfma_f32_16x16x32_bf16 v[28:31], v[132:135], v[188:191], v[28:31]
	v_mfma_f32_16x16x32_bf16 v[20:23], v[112:115], v[192:195], v[20:23]
	v_mfma_f32_16x16x32_bf16 v[20:23], v[120:123], v[200:203], v[20:23]
	v_mfma_f32_16x16x32_bf16 v[8:11], v[128:131], v[192:195], v[8:11]
	v_mfma_f32_16x16x32_bf16 v[8:11], v[132:135], v[200:203], v[8:11]
	v_mfma_f32_16x16x32_bf16 v[48:51], v[144:147], v[168:171], v[48:51]
	v_mfma_f32_16x16x32_bf16 v[48:51], v[156:159], v[172:175], v[48:51]
	v_mfma_f32_16x16x32_bf16 v[40:43], v[160:163], v[168:171], v[40:43]
	v_mfma_f32_16x16x32_bf16 v[40:43], v[164:167], v[172:175], v[40:43]
	v_mfma_f32_16x16x32_bf16 v[32:35], v[144:147], v[176:179], v[32:35]
	v_mfma_f32_16x16x32_bf16 v[32:35], v[156:159], v[180:183], v[32:35]
	v_mfma_f32_16x16x32_bf16 v[24:27], v[160:163], v[176:179], v[24:27]
	v_mfma_f32_16x16x32_bf16 v[24:27], v[164:167], v[180:183], v[24:27]
	v_mfma_f32_16x16x32_bf16 v[16:19], v[144:147], v[184:187], v[16:19]
	v_mfma_f32_16x16x32_bf16 v[16:19], v[156:159], v[188:191], v[16:19]
	v_mfma_f32_16x16x32_bf16 v[12:15], v[160:163], v[184:187], v[12:15]
	v_mfma_f32_16x16x32_bf16 v[12:15], v[164:167], v[188:191], v[12:15]
	v_mfma_f32_16x16x32_bf16 v[4:7], v[144:147], v[192:195], v[4:7]
	v_mfma_f32_16x16x32_bf16 v[4:7], v[156:159], v[200:203], v[4:7]
	v_mfma_f32_16x16x32_bf16 v[0:3], v[160:163], v[192:195], v[0:3]
	v_mfma_f32_16x16x32_bf16 v[0:3], v[164:167], v[200:203], v[0:3]
	s_barrier
	s_setprio 0
	s_add_i32 s56, 0, 0x18000
	s_add_i32 s57, 0, 0x1c000
	v_add_u32_e32 v132, s56, v154
	v_add_u32_e32 v148, s57, v154
	ds_read_b128 v[112:115], v132
	ds_read_b128 v[120:123], v132 offset:1024
	ds_read_b128 v[128:131], v132 offset:2048
	ds_read_b128 v[132:135], v132 offset:3072
	ds_read_b128 v[144:147], v148
	ds_read_b128 v[156:159], v148 offset:1024
	ds_read_b128 v[160:163], v148 offset:2048
	ds_read_b128 v[164:167], v148 offset:3072
	s_add_u32 s38, s38, 0x80000
	s_addc_u32 s39, s39, 0
	s_mov_b32 m0, s31
	ds_read_b128 v[168:171], v155 offset:32768
	ds_read_b128 v[172:175], v155 offset:33792
	ds_read_b128 v[176:179], v155 offset:34816
	ds_read_b128 v[180:183], v155 offset:35840
	ds_read_b128 v[184:187], v155 offset:36864
	ds_read_b128 v[188:191], v155 offset:37888
	ds_read_b128 v[192:195], v155 offset:38912
	ds_read_b128 v[200:203], v155 offset:39936
	s_nop 0
	global_load_lds_dwordx4 v151, s[38:39]
	s_mov_b32 m0, s46
	s_nop 0
	global_load_lds_dwordx4 v150, s[38:39]
	s_waitcnt vmcnt(8) lgkmcnt(0)
	s_setprio 1
	s_barrier
	v_mfma_f32_16x16x32_bf16 v[140:143], v[112:115], v[168:171], v[140:143]
	v_mfma_f32_16x16x32_bf16 v[140:143], v[120:123], v[172:175], v[140:143]
	v_mfma_f32_16x16x32_bf16 v[136:139], v[128:131], v[168:171], v[136:139]
	v_mfma_f32_16x16x32_bf16 v[136:139], v[132:135], v[172:175], v[136:139]
	v_mfma_f32_16x16x32_bf16 v[108:111], v[112:115], v[176:179], v[108:111]
	v_mfma_f32_16x16x32_bf16 v[108:111], v[120:123], v[180:183], v[108:111]
	v_mfma_f32_16x16x32_bf16 v[104:107], v[128:131], v[176:179], v[104:107]
	v_mfma_f32_16x16x32_bf16 v[104:107], v[132:135], v[180:183], v[104:107]
	v_mfma_f32_16x16x32_bf16 v[92:95], v[112:115], v[184:187], v[92:95]
	v_mfma_f32_16x16x32_bf16 v[92:95], v[120:123], v[188:191], v[92:95]
	v_mfma_f32_16x16x32_bf16 v[88:91], v[128:131], v[184:187], v[88:91]
	v_mfma_f32_16x16x32_bf16 v[88:91], v[132:135], v[188:191], v[88:91]
	v_mfma_f32_16x16x32_bf16 v[76:79], v[112:115], v[192:195], v[76:79]
	v_mfma_f32_16x16x32_bf16 v[76:79], v[120:123], v[200:203], v[76:79]
	v_mfma_f32_16x16x32_bf16 v[72:75], v[128:131], v[192:195], v[72:75]
	v_mfma_f32_16x16x32_bf16 v[72:75], v[132:135], v[200:203], v[72:75]
	v_mfma_f32_16x16x32_bf16 v[124:127], v[144:147], v[168:171], v[124:127]
	v_mfma_f32_16x16x32_bf16 v[124:127], v[156:159], v[172:175], v[124:127]
	v_mfma_f32_16x16x32_bf16 v[116:119], v[160:163], v[168:171], v[116:119]
	v_mfma_f32_16x16x32_bf16 v[116:119], v[164:167], v[172:175], v[116:119]
	v_mfma_f32_16x16x32_bf16 v[100:103], v[144:147], v[176:179], v[100:103]
	v_mfma_f32_16x16x32_bf16 v[100:103], v[156:159], v[180:183], v[100:103]
	v_mfma_f32_16x16x32_bf16 v[96:99], v[160:163], v[176:179], v[96:99]
	v_mfma_f32_16x16x32_bf16 v[96:99], v[164:167], v[180:183], v[96:99]
	v_mfma_f32_16x16x32_bf16 v[84:87], v[144:147], v[184:187], v[84:87]
	v_mfma_f32_16x16x32_bf16 v[84:87], v[156:159], v[188:191], v[84:87]
	v_mfma_f32_16x16x32_bf16 v[80:83], v[160:163], v[184:187], v[80:83]
	v_mfma_f32_16x16x32_bf16 v[80:83], v[164:167], v[188:191], v[80:83]
	v_mfma_f32_16x16x32_bf16 v[68:71], v[144:147], v[192:195], v[68:71]
	v_mfma_f32_16x16x32_bf16 v[68:71], v[156:159], v[200:203], v[68:71]
	v_mfma_f32_16x16x32_bf16 v[64:67], v[160:163], v[192:195], v[64:67]
	v_mfma_f32_16x16x32_bf16 v[64:67], v[164:167], v[200:203], v[64:67]
	s_barrier
	s_setprio 0
	s_add_u32 s38, s36, 0x80
	s_addc_u32 s39, s37, 0
	s_add_i32 s56, s56, s97
	s_mov_b32 m0, s56
	ds_read_b128 v[168:171], v155 offset:49152
	ds_read_b128 v[172:175], v155 offset:50176
	ds_read_b128 v[176:179], v155 offset:51200
	ds_read_b128 v[180:183], v155 offset:52224
	ds_read_b128 v[184:187], v155 offset:53248
	ds_read_b128 v[188:191], v155 offset:54272
	ds_read_b128 v[192:195], v155 offset:55296
	ds_read_b128 v[200:203], v155 offset:56320
	s_nop 0
	global_load_lds_dwordx4 v152, s[38:39]
	s_add_i32 m0, s56, 0x2000
	s_add_u32 s36, s36, 0x80080
	s_addc_u32 s37, s37, 0
	global_load_lds_dwordx4 v153, s[38:39]
	s_add_i32 s38, s57, s97
	s_mov_b32 m0, s38
	s_nop 0
	global_load_lds_dwordx4 v152, s[36:37]
	s_add_i32 m0, s38, 0x2000
	s_nop 0
	global_load_lds_dwordx4 v153, s[36:37]
	s_mov_b32 m0, s47
	s_nop 0
	global_load_lds_dwordx4 v151, s[34:35]
	s_mov_b32 m0, s48
	s_nop 0
	global_load_lds_dwordx4 v150, s[34:35]
	s_waitcnt vmcnt(8) lgkmcnt(0)
	s_setprio 1
	s_barrier
	v_mfma_f32_16x16x32_bf16 v[60:63], v[112:115], v[168:171], v[60:63]
	v_mfma_f32_16x16x32_bf16 v[60:63], v[120:123], v[172:175], v[60:63]
	v_mfma_f32_16x16x32_bf16 v[56:59], v[128:131], v[168:171], v[56:59]
	v_mfma_f32_16x16x32_bf16 v[56:59], v[132:135], v[172:175], v[56:59]
	v_mfma_f32_16x16x32_bf16 v[52:55], v[112:115], v[176:179], v[52:55]
	v_mfma_f32_16x16x32_bf16 v[52:55], v[120:123], v[180:183], v[52:55]
	v_mfma_f32_16x16x32_bf16 v[44:47], v[128:131], v[176:179], v[44:47]
	v_mfma_f32_16x16x32_bf16 v[44:47], v[132:135], v[180:183], v[44:47]
	v_mfma_f32_16x16x32_bf16 v[36:39], v[112:115], v[184:187], v[36:39]
	v_mfma_f32_16x16x32_bf16 v[36:39], v[120:123], v[188:191], v[36:39]
	v_mfma_f32_16x16x32_bf16 v[28:31], v[128:131], v[184:187], v[28:31]
	v_mfma_f32_16x16x32_bf16 v[28:31], v[132:135], v[188:191], v[28:31]
	v_mfma_f32_16x16x32_bf16 v[20:23], v[112:115], v[192:195], v[20:23]
	v_mfma_f32_16x16x32_bf16 v[20:23], v[120:123], v[200:203], v[20:23]
	v_mfma_f32_16x16x32_bf16 v[8:11], v[128:131], v[192:195], v[8:11]
	v_mfma_f32_16x16x32_bf16 v[8:11], v[132:135], v[200:203], v[8:11]
	v_mfma_f32_16x16x32_bf16 v[48:51], v[144:147], v[168:171], v[48:51]
	v_mfma_f32_16x16x32_bf16 v[48:51], v[156:159], v[172:175], v[48:51]
	v_mfma_f32_16x16x32_bf16 v[40:43], v[160:163], v[168:171], v[40:43]
	v_mfma_f32_16x16x32_bf16 v[40:43], v[164:167], v[172:175], v[40:43]
	v_mfma_f32_16x16x32_bf16 v[32:35], v[144:147], v[176:179], v[32:35]
	v_mfma_f32_16x16x32_bf16 v[32:35], v[156:159], v[180:183], v[32:35]
	v_mfma_f32_16x16x32_bf16 v[24:27], v[160:163], v[176:179], v[24:27]
	v_mfma_f32_16x16x32_bf16 v[24:27], v[164:167], v[180:183], v[24:27]
	v_mfma_f32_16x16x32_bf16 v[16:19], v[144:147], v[184:187], v[16:19]
	v_mfma_f32_16x16x32_bf16 v[16:19], v[156:159], v[188:191], v[16:19]
	v_mfma_f32_16x16x32_bf16 v[12:15], v[160:163], v[184:187], v[12:15]
	v_mfma_f32_16x16x32_bf16 v[12:15], v[164:167], v[188:191], v[12:15]
	v_mfma_f32_16x16x32_bf16 v[4:7], v[144:147], v[192:195], v[4:7]
	v_mfma_f32_16x16x32_bf16 v[4:7], v[156:159], v[200:203], v[4:7]
	v_mfma_f32_16x16x32_bf16 v[0:3], v[160:163], v[192:195], v[0:3]
	v_mfma_f32_16x16x32_bf16 v[0:3], v[164:167], v[200:203], v[0:3]
	s_barrier
	s_setprio 0
	s_add_i32 s21, s21, 2
	s_add_u32 s4, s4, 0x100
	s_addc_u32 s5, s5, 0
	s_add_u32 s15, s15, 0x100
	s_addc_u32 s17, s17, 0
	s_cmp_gt_u32 s21, 5
	s_cbranch_scc0 .LBB0_1127
	s_and_b64 vcc, exec, s[60:61]
	s_cbranch_vccz .LBB0_1130
	s_barrier

.LBB0_1253:
	s_add_u32 s34, s10, 0x100
	s_addc_u32 s35, s11, 0
	s_cmp_eq_u32 vcc_hi, 28
	s_cselect_b32 s40, s5, s34
	s_cselect_b32 s41, s4, s35
	s_cselect_b32 s38, s25, s27
	s_cselect_b32 s39, s9, vcc_lo
	s_add_u32 s36, s40, 0x80
	s_addc_u32 s37, s41, 0
	s_add_i32 s75, 0, 0x10000
	s_add_i32 s46, 0, 0x14000
	v_add_u32_e32 v140, s75, v196
	v_add_u32_e32 v156, s46, v196
	ds_read_b128 v[128:131], v140
	ds_read_b128 v[132:135], v140 offset:1024
	ds_read_b128 v[136:139], v140 offset:2048
	ds_read_b128 v[140:143], v140 offset:3072
	ds_read_b128 v[144:147], v156
	ds_read_b128 v[148:151], v156 offset:1024
	ds_read_b128 v[152:155], v156 offset:2048
	ds_read_b128 v[156:159], v156 offset:3072
	s_add_u32 s10, s10, 0x80080
	s_addc_u32 s11, s11, 0
	s_add_i32 m0, s15, 0xc000
	ds_read_b128 v[160:163], v200
	ds_read_b128 v[164:167], v200 offset:1024
	ds_read_b128 v[168:171], v200 offset:2048
	ds_read_b128 v[172:175], v200 offset:3072
	ds_read_b128 v[176:179], v200 offset:4096
	ds_read_b128 v[180:183], v200 offset:5120
	ds_read_b128 v[184:187], v200 offset:6144
	ds_read_b128 v[188:191], v200 offset:7168
	s_nop 0
	global_load_lds_dwordx4 v192, s[10:11]
	s_add_i32 m0, s15, 0xe000
	s_nop 0
	global_load_lds_dwordx4 v194, s[10:11]
	s_waitcnt vmcnt(8) lgkmcnt(0)
	s_setprio 1
	s_barrier
	v_mfma_f32_16x16x32_bf16 v[124:127], v[128:131], v[160:163], v[124:127]
	v_mfma_f32_16x16x32_bf16 v[124:127], v[132:135], v[164:167], v[124:127]
	v_mfma_f32_16x16x32_bf16 v[60:63], v[136:139], v[160:163], v[60:63]
	v_mfma_f32_16x16x32_bf16 v[60:63], v[140:143], v[164:167], v[60:63]
	v_mfma_f32_16x16x32_bf16 v[120:123], v[128:131], v[168:171], v[120:123]
	v_mfma_f32_16x16x32_bf16 v[120:123], v[132:135], v[172:175], v[120:123]
	v_mfma_f32_16x16x32_bf16 v[56:59], v[136:139], v[168:171], v[56:59]
	v_mfma_f32_16x16x32_bf16 v[56:59], v[140:143], v[172:175], v[56:59]
	v_mfma_f32_16x16x32_bf16 v[116:119], v[128:131], v[176:179], v[116:119]
	v_mfma_f32_16x16x32_bf16 v[116:119], v[132:135], v[180:183], v[116:119]
	v_mfma_f32_16x16x32_bf16 v[52:55], v[136:139], v[176:179], v[52:55]
	v_mfma_f32_16x16x32_bf16 v[52:55], v[140:143], v[180:183], v[52:55]
	v_mfma_f32_16x16x32_bf16 v[112:115], v[128:131], v[184:187], v[112:115]
	v_mfma_f32_16x16x32_bf16 v[112:115], v[132:135], v[188:191], v[112:115]
	v_mfma_f32_16x16x32_bf16 v[48:51], v[136:139], v[184:187], v[48:51]
	v_mfma_f32_16x16x32_bf16 v[48:51], v[140:143], v[188:191], v[48:51]
	v_mfma_f32_16x16x32_bf16 v[108:111], v[144:147], v[160:163], v[108:111]
	v_mfma_f32_16x16x32_bf16 v[108:111], v[148:151], v[164:167], v[108:111]
	v_mfma_f32_16x16x32_bf16 v[44:47], v[152:155], v[160:163], v[44:47]
	v_mfma_f32_16x16x32_bf16 v[44:47], v[156:159], v[164:167], v[44:47]
	v_mfma_f32_16x16x32_bf16 v[104:107], v[144:147], v[168:171], v[104:107]
	v_mfma_f32_16x16x32_bf16 v[104:107], v[148:151], v[172:175], v[104:107]
	v_mfma_f32_16x16x32_bf16 v[40:43], v[152:155], v[168:171], v[40:43]
	v_mfma_f32_16x16x32_bf16 v[40:43], v[156:159], v[172:175], v[40:43]
	v_mfma_f32_16x16x32_bf16 v[100:103], v[144:147], v[176:179], v[100:103]
	v_mfma_f32_16x16x32_bf16 v[100:103], v[148:151], v[180:183], v[100:103]
	v_mfma_f32_16x16x32_bf16 v[36:39], v[152:155], v[176:179], v[36:39]
	v_mfma_f32_16x16x32_bf16 v[36:39], v[156:159], v[180:183], v[36:39]
	v_mfma_f32_16x16x32_bf16 v[96:99], v[144:147], v[184:187], v[96:99]
	v_mfma_f32_16x16x32_bf16 v[96:99], v[148:151], v[188:191], v[96:99]
	v_mfma_f32_16x16x32_bf16 v[32:35], v[152:155], v[184:187], v[32:35]
	v_mfma_f32_16x16x32_bf16 v[32:35], v[156:159], v[188:191], v[32:35]
	s_barrier
	s_setprio 0
	s_add_i32 s47, s75, s97
	s_mov_b64 s[10:11], s[38:39]
	s_mov_b32 m0, s47
	ds_read_b128 v[160:163], v200 offset:16384
	ds_read_b128 v[164:167], v200 offset:17408
	ds_read_b128 v[168:171], v200 offset:18432
	ds_read_b128 v[172:175], v200 offset:19456
	ds_read_b128 v[176:179], v200 offset:20480
	ds_read_b128 v[180:183], v200 offset:21504
	ds_read_b128 v[184:187], v200 offset:22528
	ds_read_b128 v[188:191], v200 offset:23552
	s_nop 0
	global_load_lds_dwordx4 v193, s[10:11]
	s_add_i32 m0, s47, 0x2000
	s_nop 0
	global_load_lds_dwordx4 v195, s[10:11]
	s_add_u32 s10, s38, 0x80000
	s_addc_u32 s11, s39, 0
	s_add_i32 s46, s46, s97
	s_mov_b32 m0, s46
	s_nop 0
	global_load_lds_dwordx4 v193, s[10:11]
	s_add_i32 m0, s46, 0x2000
	s_nop 0
	global_load_lds_dwordx4 v195, s[10:11]
	s_mov_b64 s[10:11], s[40:41]
	s_mov_b32 m0, s15
	s_nop 0
	global_load_lds_dwordx4 v192, s[10:11]
	s_mov_b32 m0, s69
	s_nop 0
	global_load_lds_dwordx4 v194, s[10:11]
	s_waitcnt vmcnt(8) lgkmcnt(0)
	s_setprio 1
	s_barrier
	v_mfma_f32_16x16x32_bf16 v[92:95], v[128:131], v[160:163], v[92:95]
	v_mfma_f32_16x16x32_bf16 v[92:95], v[132:135], v[164:167], v[92:95]
	v_mfma_f32_16x16x32_bf16 v[28:31], v[136:139], v[160:163], v[28:31]
	v_mfma_f32_16x16x32_bf16 v[28:31], v[140:143], v[164:167], v[28:31]
	v_mfma_f32_16x16x32_bf16 v[88:91], v[128:131], v[168:171], v[88:91]
	v_mfma_f32_16x16x32_bf16 v[88:91], v[132:135], v[172:175], v[88:91]
	v_mfma_f32_16x16x32_bf16 v[16:19], v[136:139], v[168:171], v[16:19]
	v_mfma_f32_16x16x32_bf16 v[16:19], v[140:143], v[172:175], v[16:19]
	v_mfma_f32_16x16x32_bf16 v[84:87], v[128:131], v[176:179], v[84:87]
	v_mfma_f32_16x16x32_bf16 v[84:87], v[132:135], v[180:183], v[84:87]
	v_mfma_f32_16x16x32_bf16 v[20:23], v[136:139], v[176:179], v[20:23]
	v_mfma_f32_16x16x32_bf16 v[20:23], v[140:143], v[180:183], v[20:23]
	v_mfma_f32_16x16x32_bf16 v[80:83], v[128:131], v[184:187], v[80:83]
	v_mfma_f32_16x16x32_bf16 v[80:83], v[132:135], v[188:191], v[80:83]
	v_mfma_f32_16x16x32_bf16 v[8:11], v[136:139], v[184:187], v[8:11]
	v_mfma_f32_16x16x32_bf16 v[8:11], v[140:143], v[188:191], v[8:11]
	v_mfma_f32_16x16x32_bf16 v[76:79], v[144:147], v[160:163], v[76:79]
	v_mfma_f32_16x16x32_bf16 v[76:79], v[148:151], v[164:167], v[76:79]
	v_mfma_f32_16x16x32_bf16 v[24:27], v[152:155], v[160:163], v[24:27]
	v_mfma_f32_16x16x32_bf16 v[24:27], v[156:159], v[164:167], v[24:27]
	v_mfma_f32_16x16x32_bf16 v[72:75], v[144:147], v[168:171], v[72:75]
	v_mfma_f32_16x16x32_bf16 v[72:75], v[148:151], v[172:175], v[72:75]
	v_mfma_f32_16x16x32_bf16 v[12:15], v[152:155], v[168:171], v[12:15]
	v_mfma_f32_16x16x32_bf16 v[12:15], v[156:159], v[172:175], v[12:15]
	v_mfma_f32_16x16x32_bf16 v[68:71], v[144:147], v[176:179], v[68:71]
	v_mfma_f32_16x16x32_bf16 v[68:71], v[148:151], v[180:183], v[68:71]
	v_mfma_f32_16x16x32_bf16 v[4:7], v[152:155], v[176:179], v[4:7]
	v_mfma_f32_16x16x32_bf16 v[4:7], v[156:159], v[180:183], v[4:7]
	v_mfma_f32_16x16x32_bf16 v[64:67], v[144:147], v[184:187], v[64:67]
	v_mfma_f32_16x16x32_bf16 v[64:67], v[148:151], v[188:191], v[64:67]
	v_mfma_f32_16x16x32_bf16 v[0:3], v[152:155], v[184:187], v[0:3]
	v_mfma_f32_16x16x32_bf16 v[0:3], v[156:159], v[188:191], v[0:3]
	s_barrier
	s_setprio 0
	s_add_i32 s46, 0, 0x18000
	s_add_i32 s47, 0, 0x1c000
	v_add_u32_e32 v140, s46, v196
	v_add_u32_e32 v156, s47, v196
	ds_read_b128 v[128:131], v140
	ds_read_b128 v[132:135], v140 offset:1024
	ds_read_b128 v[136:139], v140 offset:2048
	ds_read_b128 v[140:143], v140 offset:3072
	ds_read_b128 v[144:147], v156
	ds_read_b128 v[148:151], v156 offset:1024
	ds_read_b128 v[152:155], v156 offset:2048
	ds_read_b128 v[156:159], v156 offset:3072
	s_add_u32 s10, s40, 0x80000
	s_addc_u32 s11, s41, 0
	s_mov_b32 m0, s78
	ds_read_b128 v[160:163], v200 offset:32768
	ds_read_b128 v[164:167], v200 offset:33792
	ds_read_b128 v[168:171], v200 offset:34816
	ds_read_b128 v[172:175], v200 offset:35840
	ds_read_b128 v[176:179], v200 offset:36864
	ds_read_b128 v[180:183], v200 offset:37888
	ds_read_b128 v[184:187], v200 offset:38912
	ds_read_b128 v[188:191], v200 offset:39936
	s_nop 0
	global_load_lds_dwordx4 v192, s[10:11]
	s_mov_b32 m0, s80
	s_nop 0
	global_load_lds_dwordx4 v194, s[10:11]
	s_waitcnt vmcnt(8) lgkmcnt(0)
	s_setprio 1
	s_barrier
	v_mfma_f32_16x16x32_bf16 v[124:127], v[128:131], v[160:163], v[124:127]
	v_mfma_f32_16x16x32_bf16 v[124:127], v[132:135], v[164:167], v[124:127]
	v_mfma_f32_16x16x32_bf16 v[60:63], v[136:139], v[160:163], v[60:63]
	v_mfma_f32_16x16x32_bf16 v[60:63], v[140:143], v[164:167], v[60:63]
	v_mfma_f32_16x16x32_bf16 v[120:123], v[128:131], v[168:171], v[120:123]
	v_mfma_f32_16x16x32_bf16 v[120:123], v[132:135], v[172:175], v[120:123]
	v_mfma_f32_16x16x32_bf16 v[56:59], v[136:139], v[168:171], v[56:59]
	v_mfma_f32_16x16x32_bf16 v[56:59], v[140:143], v[172:175], v[56:59]
	v_mfma_f32_16x16x32_bf16 v[116:119], v[128:131], v[176:179], v[116:119]
	v_mfma_f32_16x16x32_bf16 v[116:119], v[132:135], v[180:183], v[116:119]
	v_mfma_f32_16x16x32_bf16 v[52:55], v[136:139], v[176:179], v[52:55]
	v_mfma_f32_16x16x32_bf16 v[52:55], v[140:143], v[180:183], v[52:55]
	v_mfma_f32_16x16x32_bf16 v[112:115], v[128:131], v[184:187], v[112:115]
	v_mfma_f32_16x16x32_bf16 v[112:115], v[132:135], v[188:191], v[112:115]
	v_mfma_f32_16x16x32_bf16 v[48:51], v[136:139], v[184:187], v[48:51]
	v_mfma_f32_16x16x32_bf16 v[48:51], v[140:143], v[188:191], v[48:51]
	v_mfma_f32_16x16x32_bf16 v[108:111], v[144:147], v[160:163], v[108:111]
	v_mfma_f32_16x16x32_bf16 v[108:111], v[148:151], v[164:167], v[108:111]
	v_mfma_f32_16x16x32_bf16 v[44:47], v[152:155], v[160:163], v[44:47]
	v_mfma_f32_16x16x32_bf16 v[44:47], v[156:159], v[164:167], v[44:47]
	v_mfma_f32_16x16x32_bf16 v[104:107], v[144:147], v[168:171], v[104:107]
	v_mfma_f32_16x16x32_bf16 v[104:107], v[148:151], v[172:175], v[104:107]
	v_mfma_f32_16x16x32_bf16 v[40:43], v[152:155], v[168:171], v[40:43]
	v_mfma_f32_16x16x32_bf16 v[40:43], v[156:159], v[172:175], v[40:43]
	v_mfma_f32_16x16x32_bf16 v[100:103], v[144:147], v[176:179], v[100:103]
	v_mfma_f32_16x16x32_bf16 v[100:103], v[148:151], v[180:183], v[100:103]
	v_mfma_f32_16x16x32_bf16 v[36:39], v[152:155], v[176:179], v[36:39]
	v_mfma_f32_16x16x32_bf16 v[36:39], v[156:159], v[180:183], v[36:39]
	v_mfma_f32_16x16x32_bf16 v[96:99], v[144:147], v[184:187], v[96:99]
	v_mfma_f32_16x16x32_bf16 v[96:99], v[148:151], v[188:191], v[96:99]
	v_mfma_f32_16x16x32_bf16 v[32:35], v[152:155], v[184:187], v[32:35]
	v_mfma_f32_16x16x32_bf16 v[32:35], v[156:159], v[188:191], v[32:35]
	s_barrier
	s_setprio 0
	s_add_u32 s10, s38, 0x80
	s_addc_u32 s11, s39, 0
	s_add_i32 s40, s46, s97
	s_mov_b32 m0, s40
	ds_read_b128 v[160:163], v200 offset:49152
	ds_read_b128 v[164:167], v200 offset:50176
	ds_read_b128 v[168:171], v200 offset:51200
	ds_read_b128 v[172:175], v200 offset:52224
	ds_read_b128 v[176:179], v200 offset:53248
	ds_read_b128 v[180:183], v200 offset:54272
	ds_read_b128 v[184:187], v200 offset:55296
	ds_read_b128 v[188:191], v200 offset:56320
	s_nop 0
	global_load_lds_dwordx4 v193, s[10:11]
	s_add_i32 m0, s40, 0x2000
	s_nop 0
	global_load_lds_dwordx4 v195, s[10:11]
	s_add_u32 s10, s38, 0x80080
	s_addc_u32 s11, s39, 0
	s_add_i32 s38, s47, s97
	s_mov_b32 m0, s38
	s_nop 0
	global_load_lds_dwordx4 v193, s[10:11]
	s_add_i32 m0, s38, 0x2000
	s_nop 0
	global_load_lds_dwordx4 v195, s[10:11]
	s_mov_b32 m0, s85
	s_nop 0
	global_load_lds_dwordx4 v192, s[36:37]
	s_mov_b32 m0, s86
	s_nop 0
	global_load_lds_dwordx4 v194, s[36:37]
	s_waitcnt vmcnt(8) lgkmcnt(0)
	s_setprio 1
	s_barrier
	v_mfma_f32_16x16x32_bf16 v[92:95], v[128:131], v[160:163], v[92:95]
	v_mfma_f32_16x16x32_bf16 v[92:95], v[132:135], v[164:167], v[92:95]
	v_mfma_f32_16x16x32_bf16 v[28:31], v[136:139], v[160:163], v[28:31]
	v_mfma_f32_16x16x32_bf16 v[28:31], v[140:143], v[164:167], v[28:31]
	v_mfma_f32_16x16x32_bf16 v[88:91], v[128:131], v[168:171], v[88:91]
	v_mfma_f32_16x16x32_bf16 v[88:91], v[132:135], v[172:175], v[88:91]
	v_mfma_f32_16x16x32_bf16 v[16:19], v[136:139], v[168:171], v[16:19]
	v_mfma_f32_16x16x32_bf16 v[16:19], v[140:143], v[172:175], v[16:19]
	v_mfma_f32_16x16x32_bf16 v[84:87], v[128:131], v[176:179], v[84:87]
	v_mfma_f32_16x16x32_bf16 v[84:87], v[132:135], v[180:183], v[84:87]
	v_mfma_f32_16x16x32_bf16 v[20:23], v[136:139], v[176:179], v[20:23]
	v_mfma_f32_16x16x32_bf16 v[20:23], v[140:143], v[180:183], v[20:23]
	v_mfma_f32_16x16x32_bf16 v[80:83], v[128:131], v[184:187], v[80:83]
	v_mfma_f32_16x16x32_bf16 v[80:83], v[132:135], v[188:191], v[80:83]
	v_mfma_f32_16x16x32_bf16 v[8:11], v[136:139], v[184:187], v[8:11]
	v_mfma_f32_16x16x32_bf16 v[8:11], v[140:143], v[188:191], v[8:11]
	v_mfma_f32_16x16x32_bf16 v[76:79], v[144:147], v[160:163], v[76:79]
	v_mfma_f32_16x16x32_bf16 v[76:79], v[148:151], v[164:167], v[76:79]
	v_mfma_f32_16x16x32_bf16 v[24:27], v[152:155], v[160:163], v[24:27]
	v_mfma_f32_16x16x32_bf16 v[24:27], v[156:159], v[164:167], v[24:27]
	v_mfma_f32_16x16x32_bf16 v[72:75], v[144:147], v[168:171], v[72:75]
	v_mfma_f32_16x16x32_bf16 v[72:75], v[148:151], v[172:175], v[72:75]
	v_mfma_f32_16x16x32_bf16 v[12:15], v[152:155], v[168:171], v[12:15]
	v_mfma_f32_16x16x32_bf16 v[12:15], v[156:159], v[172:175], v[12:15]
	v_mfma_f32_16x16x32_bf16 v[68:71], v[144:147], v[176:179], v[68:71]
	v_mfma_f32_16x16x32_bf16 v[68:71], v[148:151], v[180:183], v[68:71]
	v_mfma_f32_16x16x32_bf16 v[4:7], v[152:155], v[176:179], v[4:7]
	v_mfma_f32_16x16x32_bf16 v[4:7], v[156:159], v[180:183], v[4:7]
	v_mfma_f32_16x16x32_bf16 v[64:67], v[144:147], v[184:187], v[64:67]
	v_mfma_f32_16x16x32_bf16 v[64:67], v[148:151], v[188:191], v[64:67]
	v_mfma_f32_16x16x32_bf16 v[0:3], v[152:155], v[184:187], v[0:3]
	v_mfma_f32_16x16x32_bf16 v[0:3], v[156:159], v[188:191], v[0:3]
	s_barrier
	s_setprio 0
	s_add_i32 vcc_hi, vcc_hi, 2
	s_add_u32 s27, s27, 0x100
	s_addc_u32 vcc_lo, vcc_lo, 0
	s_cmp_gt_u32 vcc_hi, 29
	s_mov_b64 s[10:11], s[34:35]
	s_cbranch_scc0 .LBB0_1253
	v_mbcnt_lo_u32_b32 v205, -1, 0
	v_mbcnt_hi_u32_b32 v205, -1, v205
	v_and_b32_e32 v201, 15, v205
	v_ashrrev_i32_e32 v205, 1, v205
	v_and_b32_e32 v205, -8, v205
	v_add_u32_e32 v160, s68, v205
	v_lshl_add_u32 v176, s8, 7, v160
	v_ashrrev_i32_e32 v177, 31, v176
	v_lshlrev_b64 v[128:129], 2, v[176:177]
	v_lshl_add_u64 v[180:181], s[16:17], 0, v[128:129]
	v_add_co_u32_e32 v136, vcc, 0xb000, v180
	s_mov_b32 s4, 0x16000
	s_nop 0
	v_addc_co_u32_e32 v137, vcc, 0, v181, vcc
	v_add_co_u32_e32 v184, vcc, s4, v180
	v_lshl_add_u64 v[178:179], s[20:21], 0, v[128:129]
	s_nop 0
	v_addc_co_u32_e32 v185, vcc, 0, v181, vcc
	s_movk_i32 s4, 0x5000
	v_add_co_u32_e32 v182, vcc, s4, v178
	s_nop 0
	s_nop 0
	v_addc_co_u32_e32 v183, vcc, 0, v179, vcc
	v_add_co_u32_e32 v186, vcc, s4, v180
	s_mov_b32 s4, 0x10000
	s_nop 0
	v_addc_co_u32_e32 v187, vcc, 0, v181, vcc
	v_add_co_u32_e32 v188, vcc, s4, v180
	s_mov_b32 s4, 0x1b000
	s_nop 0
	v_addc_co_u32_e32 v189, vcc, 0, v181, vcc
	global_load_dwordx4 v[128:131], v[178:179], off
	global_load_dwordx4 v[132:135], v[180:181], off
	global_load_dwordx4 v[148:151], v[136:137], off
	global_load_dwordx4 v[216:219], v[136:137], off offset:16
	global_load_dwordx4 v[152:155], v[184:185], off
	s_nop 0
	global_load_dwordx4 v[136:139], v[182:183], off offset:2048
	global_load_dwordx4 v[140:143], v[186:187], off offset:2048
	global_load_dwordx4 v[144:147], v[188:189], off offset:2048
	v_add_co_u32_e32 v190, vcc, s4, v180
	s_nop 0
	s_nop 0
	v_addc_co_u32_e32 v191, vcc, 0, v181, vcc
	global_load_dwordx4 v[156:159], v[190:191], off offset:2048
	global_load_dwordx4 v[224:227], v[178:179], off offset:16
	global_load_dwordx4 v[228:231], v[180:181], off offset:16
	global_load_dwordx4 v[232:235], v[184:185], off offset:16
	global_load_dwordx4 v[236:239], v[188:189], off offset:2064
	global_load_dwordx4 v[240:243], v[182:183], off offset:2064
	global_load_dwordx4 v[244:247], v[186:187], off offset:2064
	global_load_dwordx4 v[248:251], v[190:191], off offset:2064
	s_and_b64 vcc, exec, s[60:61]
	s_cbranch_vccz .LBB0_1256
	s_barrier

.LBB0_1290:
	s_cmp_eq_u32 s21, 12
	s_cselect_b32 s40, s24, s4
	s_cselect_b32 s41, s25, s5
	s_cselect_b32 s38, s30, s15
	s_cselect_b32 s39, s31, s17
	s_add_u32 s36, s40, 0x80
	s_addc_u32 s37, s41, 0
	s_add_i32 s23, 0, 0x10000
	v_add_u32_e32 v128, s23, v134
	s_add_i32 s46, 0, 0x14000
	ds_read_b128 v[136:139], v128
	ds_read_b128 v[140:143], v128 offset:1024
	ds_read_b128 v[144:147], v128 offset:2048
	ds_read_b128 v[148:151], v128 offset:3072
	v_add_u32_e32 v128, s46, v134
	ds_read_b128 v[152:155], v128
	ds_read_b128 v[156:159], v128 offset:1024
	ds_read_b128 v[160:163], v128 offset:2048
	ds_read_b128 v[164:167], v128 offset:3072
	s_mov_b64 s[74:75], s[34:35]
	s_add_i32 m0, s27, 0xc000
	ds_read_b128 v[168:171], v135
	ds_read_b128 v[172:175], v135 offset:1024
	ds_read_b128 v[176:179], v135 offset:2048
	ds_read_b128 v[180:183], v135 offset:3072
	ds_read_b128 v[184:187], v135 offset:4096
	ds_read_b128 v[188:191], v135 offset:5120
	ds_read_b128 v[192:195], v135 offset:6144
	ds_read_b128 v[200:203], v135 offset:7168
	s_nop 0
	global_load_lds_dwordx4 v133, s[74:75]
	s_add_i32 m0, s27, 0xe000
	s_nop 0
	global_load_lds_dwordx4 v131, s[74:75]
	s_waitcnt vmcnt(8) lgkmcnt(0)
	s_setprio 1
	s_barrier
	v_mfma_f32_16x16x32_bf16 v[124:127], v[136:139], v[168:171], v[124:127]
	v_mfma_f32_16x16x32_bf16 v[124:127], v[140:143], v[172:175], v[124:127]
	v_mfma_f32_16x16x32_bf16 v[120:123], v[144:147], v[168:171], v[120:123]
	v_mfma_f32_16x16x32_bf16 v[120:123], v[148:151], v[172:175], v[120:123]
	v_mfma_f32_16x16x32_bf16 v[116:119], v[136:139], v[176:179], v[116:119]
	v_mfma_f32_16x16x32_bf16 v[116:119], v[140:143], v[180:183], v[116:119]
	v_mfma_f32_16x16x32_bf16 v[108:111], v[144:147], v[176:179], v[108:111]
	v_mfma_f32_16x16x32_bf16 v[108:111], v[148:151], v[180:183], v[108:111]
	v_mfma_f32_16x16x32_bf16 v[100:103], v[136:139], v[184:187], v[100:103]
	v_mfma_f32_16x16x32_bf16 v[100:103], v[140:143], v[188:191], v[100:103]
	v_mfma_f32_16x16x32_bf16 v[92:95], v[144:147], v[184:187], v[92:95]
	v_mfma_f32_16x16x32_bf16 v[92:95], v[148:151], v[188:191], v[92:95]
	v_mfma_f32_16x16x32_bf16 v[84:87], v[136:139], v[192:195], v[84:87]
	v_mfma_f32_16x16x32_bf16 v[84:87], v[140:143], v[200:203], v[84:87]
	v_mfma_f32_16x16x32_bf16 v[76:79], v[144:147], v[192:195], v[76:79]
	v_mfma_f32_16x16x32_bf16 v[76:79], v[148:151], v[200:203], v[76:79]
	v_mfma_f32_16x16x32_bf16 v[112:115], v[152:155], v[168:171], v[112:115]
	v_mfma_f32_16x16x32_bf16 v[112:115], v[156:159], v[172:175], v[112:115]
	v_mfma_f32_16x16x32_bf16 v[104:107], v[160:163], v[168:171], v[104:107]
	v_mfma_f32_16x16x32_bf16 v[104:107], v[164:167], v[172:175], v[104:107]
	v_mfma_f32_16x16x32_bf16 v[96:99], v[152:155], v[176:179], v[96:99]
	v_mfma_f32_16x16x32_bf16 v[96:99], v[156:159], v[180:183], v[96:99]
	v_mfma_f32_16x16x32_bf16 v[88:91], v[160:163], v[176:179], v[88:91]
	v_mfma_f32_16x16x32_bf16 v[88:91], v[164:167], v[180:183], v[88:91]
	v_mfma_f32_16x16x32_bf16 v[80:83], v[152:155], v[184:187], v[80:83]
	v_mfma_f32_16x16x32_bf16 v[80:83], v[156:159], v[188:191], v[80:83]
	v_mfma_f32_16x16x32_bf16 v[72:75], v[160:163], v[184:187], v[72:75]
	v_mfma_f32_16x16x32_bf16 v[72:75], v[164:167], v[188:191], v[72:75]
	v_mfma_f32_16x16x32_bf16 v[68:71], v[152:155], v[192:195], v[68:71]
	v_mfma_f32_16x16x32_bf16 v[68:71], v[156:159], v[200:203], v[68:71]
	v_mfma_f32_16x16x32_bf16 v[64:67], v[160:163], v[192:195], v[64:67]
	v_mfma_f32_16x16x32_bf16 v[64:67], v[164:167], v[200:203], v[64:67]
	s_barrier
	s_setprio 0
	s_add_i32 s23, s23, s97
	s_mov_b64 s[74:75], s[38:39]
	s_mov_b32 m0, s23
	ds_read_b128 v[168:171], v135 offset:16384
	ds_read_b128 v[172:175], v135 offset:17408
	ds_read_b128 v[176:179], v135 offset:18432
	ds_read_b128 v[180:183], v135 offset:19456
	ds_read_b128 v[184:187], v135 offset:20480
	ds_read_b128 v[188:191], v135 offset:21504
	ds_read_b128 v[192:195], v135 offset:22528
	ds_read_b128 v[200:203], v135 offset:23552
	s_nop 0
	global_load_lds_dwordx4 v132, s[74:75]
	s_add_i32 m0, s23, 0x2000
	s_nop 0
	global_load_lds_dwordx4 v130, s[74:75]
	s_add_u32 s74, s38, 0x80000
	s_addc_u32 s75, s39, 0
	s_add_i32 s23, s46, s97
	s_mov_b32 m0, s23
	s_nop 0
	global_load_lds_dwordx4 v132, s[74:75]
	s_add_i32 m0, s23, 0x2000
	s_nop 0
	global_load_lds_dwordx4 v130, s[74:75]
	s_mov_b64 s[74:75], s[40:41]
	s_mov_b32 m0, s27
	s_nop 0
	global_load_lds_dwordx4 v133, s[74:75]
	s_mov_b32 m0, s29
	s_nop 0
	global_load_lds_dwordx4 v131, s[74:75]
	s_waitcnt vmcnt(8) lgkmcnt(0)
	s_setprio 1
	s_barrier
	v_mfma_f32_16x16x32_bf16 v[60:63], v[136:139], v[168:171], v[60:63]
	v_mfma_f32_16x16x32_bf16 v[60:63], v[140:143], v[172:175], v[60:63]
	v_mfma_f32_16x16x32_bf16 v[56:59], v[144:147], v[168:171], v[56:59]
	v_mfma_f32_16x16x32_bf16 v[56:59], v[148:151], v[172:175], v[56:59]
	v_mfma_f32_16x16x32_bf16 v[52:55], v[136:139], v[176:179], v[52:55]
	v_mfma_f32_16x16x32_bf16 v[52:55], v[140:143], v[180:183], v[52:55]
	v_mfma_f32_16x16x32_bf16 v[44:47], v[144:147], v[176:179], v[44:47]
	v_mfma_f32_16x16x32_bf16 v[44:47], v[148:151], v[180:183], v[44:47]
	v_mfma_f32_16x16x32_bf16 v[36:39], v[136:139], v[184:187], v[36:39]
	v_mfma_f32_16x16x32_bf16 v[36:39], v[140:143], v[188:191], v[36:39]
	v_mfma_f32_16x16x32_bf16 v[28:31], v[144:147], v[184:187], v[28:31]
	v_mfma_f32_16x16x32_bf16 v[28:31], v[148:151], v[188:191], v[28:31]
	v_mfma_f32_16x16x32_bf16 v[20:23], v[136:139], v[192:195], v[20:23]
	v_mfma_f32_16x16x32_bf16 v[20:23], v[140:143], v[200:203], v[20:23]
	v_mfma_f32_16x16x32_bf16 v[12:15], v[144:147], v[192:195], v[12:15]
	v_mfma_f32_16x16x32_bf16 v[12:15], v[148:151], v[200:203], v[12:15]
	v_mfma_f32_16x16x32_bf16 v[48:51], v[152:155], v[168:171], v[48:51]
	v_mfma_f32_16x16x32_bf16 v[48:51], v[156:159], v[172:175], v[48:51]
	v_mfma_f32_16x16x32_bf16 v[40:43], v[160:163], v[168:171], v[40:43]
	v_mfma_f32_16x16x32_bf16 v[40:43], v[164:167], v[172:175], v[40:43]
	v_mfma_f32_16x16x32_bf16 v[32:35], v[152:155], v[176:179], v[32:35]
	v_mfma_f32_16x16x32_bf16 v[32:35], v[156:159], v[180:183], v[32:35]
	v_mfma_f32_16x16x32_bf16 v[24:27], v[160:163], v[176:179], v[24:27]
	v_mfma_f32_16x16x32_bf16 v[24:27], v[164:167], v[180:183], v[24:27]
	v_mfma_f32_16x16x32_bf16 v[16:19], v[152:155], v[184:187], v[16:19]
	v_mfma_f32_16x16x32_bf16 v[16:19], v[156:159], v[188:191], v[16:19]
	v_mfma_f32_16x16x32_bf16 v[8:11], v[160:163], v[184:187], v[8:11]
	v_mfma_f32_16x16x32_bf16 v[8:11], v[164:167], v[188:191], v[8:11]
	v_mfma_f32_16x16x32_bf16 v[4:7], v[152:155], v[192:195], v[4:7]
	v_mfma_f32_16x16x32_bf16 v[4:7], v[156:159], v[200:203], v[4:7]
	v_mfma_f32_16x16x32_bf16 v[0:3], v[160:163], v[192:195], v[0:3]
	v_mfma_f32_16x16x32_bf16 v[0:3], v[164:167], v[200:203], v[0:3]
	s_barrier
	s_setprio 0
	s_add_i32 s23, 0, 0x18000
	v_add_u32_e32 v128, s23, v134
	s_add_i32 s46, 0, 0x1c000
	ds_read_b128 v[136:139], v128
	ds_read_b128 v[140:143], v128 offset:1024
	ds_read_b128 v[144:147], v128 offset:2048
	ds_read_b128 v[148:151], v128 offset:3072
	v_add_u32_e32 v128, s46, v134
	ds_read_b128 v[152:155], v128
	ds_read_b128 v[156:159], v128 offset:1024
	ds_read_b128 v[160:163], v128 offset:2048
	ds_read_b128 v[164:167], v128 offset:3072
	s_add_u32 s40, s40, 0x80000
	s_addc_u32 s41, s41, 0
	s_mov_b32 m0, s56
	ds_read_b128 v[168:171], v135 offset:32768
	ds_read_b128 v[172:175], v135 offset:33792
	ds_read_b128 v[176:179], v135 offset:34816
	ds_read_b128 v[180:183], v135 offset:35840
	ds_read_b128 v[184:187], v135 offset:36864
	ds_read_b128 v[188:191], v135 offset:37888
	ds_read_b128 v[192:195], v135 offset:38912
	ds_read_b128 v[200:203], v135 offset:39936
	s_nop 0
	global_load_lds_dwordx4 v133, s[40:41]
	s_mov_b32 m0, s57
	s_nop 0
	global_load_lds_dwordx4 v131, s[40:41]
	s_waitcnt vmcnt(8) lgkmcnt(0)
	s_setprio 1
	s_barrier
	v_mfma_f32_16x16x32_bf16 v[124:127], v[136:139], v[168:171], v[124:127]
	v_mfma_f32_16x16x32_bf16 v[124:127], v[140:143], v[172:175], v[124:127]
	v_mfma_f32_16x16x32_bf16 v[120:123], v[144:147], v[168:171], v[120:123]
	v_mfma_f32_16x16x32_bf16 v[120:123], v[148:151], v[172:175], v[120:123]
	v_mfma_f32_16x16x32_bf16 v[116:119], v[136:139], v[176:179], v[116:119]
	v_mfma_f32_16x16x32_bf16 v[116:119], v[140:143], v[180:183], v[116:119]
	v_mfma_f32_16x16x32_bf16 v[108:111], v[144:147], v[176:179], v[108:111]
	v_mfma_f32_16x16x32_bf16 v[108:111], v[148:151], v[180:183], v[108:111]
	v_mfma_f32_16x16x32_bf16 v[100:103], v[136:139], v[184:187], v[100:103]
	v_mfma_f32_16x16x32_bf16 v[100:103], v[140:143], v[188:191], v[100:103]
	v_mfma_f32_16x16x32_bf16 v[92:95], v[144:147], v[184:187], v[92:95]
	v_mfma_f32_16x16x32_bf16 v[92:95], v[148:151], v[188:191], v[92:95]
	v_mfma_f32_16x16x32_bf16 v[84:87], v[136:139], v[192:195], v[84:87]
	v_mfma_f32_16x16x32_bf16 v[84:87], v[140:143], v[200:203], v[84:87]
	v_mfma_f32_16x16x32_bf16 v[76:79], v[144:147], v[192:195], v[76:79]
	v_mfma_f32_16x16x32_bf16 v[76:79], v[148:151], v[200:203], v[76:79]
	v_mfma_f32_16x16x32_bf16 v[112:115], v[152:155], v[168:171], v[112:115]
	v_mfma_f32_16x16x32_bf16 v[112:115], v[156:159], v[172:175], v[112:115]
	v_mfma_f32_16x16x32_bf16 v[104:107], v[160:163], v[168:171], v[104:107]
	v_mfma_f32_16x16x32_bf16 v[104:107], v[164:167], v[172:175], v[104:107]
	v_mfma_f32_16x16x32_bf16 v[96:99], v[152:155], v[176:179], v[96:99]
	v_mfma_f32_16x16x32_bf16 v[96:99], v[156:159], v[180:183], v[96:99]
	v_mfma_f32_16x16x32_bf16 v[88:91], v[160:163], v[176:179], v[88:91]
	v_mfma_f32_16x16x32_bf16 v[88:91], v[164:167], v[180:183], v[88:91]
	v_mfma_f32_16x16x32_bf16 v[80:83], v[152:155], v[184:187], v[80:83]
	v_mfma_f32_16x16x32_bf16 v[80:83], v[156:159], v[188:191], v[80:83]
	v_mfma_f32_16x16x32_bf16 v[72:75], v[160:163], v[184:187], v[72:75]
	v_mfma_f32_16x16x32_bf16 v[72:75], v[164:167], v[188:191], v[72:75]
	v_mfma_f32_16x16x32_bf16 v[68:71], v[152:155], v[192:195], v[68:71]
	v_mfma_f32_16x16x32_bf16 v[68:71], v[156:159], v[200:203], v[68:71]
	v_mfma_f32_16x16x32_bf16 v[64:67], v[160:163], v[192:195], v[64:67]
	v_mfma_f32_16x16x32_bf16 v[64:67], v[164:167], v[200:203], v[64:67]
	s_barrier
	s_setprio 0
	s_add_u32 s40, s38, 0x80
	s_addc_u32 s41, s39, 0
	s_add_i32 s23, s23, s97
	s_mov_b32 m0, s23
	ds_read_b128 v[168:171], v135 offset:49152
	ds_read_b128 v[172:175], v135 offset:50176
	ds_read_b128 v[176:179], v135 offset:51200
	ds_read_b128 v[180:183], v135 offset:52224
	ds_read_b128 v[184:187], v135 offset:53248
	ds_read_b128 v[188:191], v135 offset:54272
	ds_read_b128 v[192:195], v135 offset:55296
	ds_read_b128 v[200:203], v135 offset:56320
	s_nop 0
	global_load_lds_dwordx4 v132, s[40:41]
	s_add_i32 m0, s23, 0x2000
	s_add_u32 s38, s38, 0x80080
	s_addc_u32 s39, s39, 0
	s_add_i32 s23, s46, s97
	s_nop 0
	global_load_lds_dwordx4 v130, s[40:41]
	s_mov_b32 m0, s23
	s_nop 0
	global_load_lds_dwordx4 v132, s[38:39]
	s_add_i32 m0, s23, 0x2000
	s_nop 0
	global_load_lds_dwordx4 v130, s[38:39]
	s_mov_b32 m0, s70
	s_nop 0
	global_load_lds_dwordx4 v133, s[36:37]
	s_mov_b32 m0, s71
	s_nop 0
	global_load_lds_dwordx4 v131, s[36:37]
	s_waitcnt vmcnt(8) lgkmcnt(0)
	s_setprio 1
	s_barrier
	v_mfma_f32_16x16x32_bf16 v[60:63], v[136:139], v[168:171], v[60:63]
	v_mfma_f32_16x16x32_bf16 v[60:63], v[140:143], v[172:175], v[60:63]
	v_mfma_f32_16x16x32_bf16 v[56:59], v[144:147], v[168:171], v[56:59]
	v_mfma_f32_16x16x32_bf16 v[56:59], v[148:151], v[172:175], v[56:59]
	v_mfma_f32_16x16x32_bf16 v[52:55], v[136:139], v[176:179], v[52:55]
	v_mfma_f32_16x16x32_bf16 v[52:55], v[140:143], v[180:183], v[52:55]
	v_mfma_f32_16x16x32_bf16 v[44:47], v[144:147], v[176:179], v[44:47]
	v_mfma_f32_16x16x32_bf16 v[44:47], v[148:151], v[180:183], v[44:47]
	v_mfma_f32_16x16x32_bf16 v[36:39], v[136:139], v[184:187], v[36:39]
	v_mfma_f32_16x16x32_bf16 v[36:39], v[140:143], v[188:191], v[36:39]
	v_mfma_f32_16x16x32_bf16 v[28:31], v[144:147], v[184:187], v[28:31]
	v_mfma_f32_16x16x32_bf16 v[28:31], v[148:151], v[188:191], v[28:31]
	v_mfma_f32_16x16x32_bf16 v[20:23], v[136:139], v[192:195], v[20:23]
	v_mfma_f32_16x16x32_bf16 v[20:23], v[140:143], v[200:203], v[20:23]
	v_mfma_f32_16x16x32_bf16 v[12:15], v[144:147], v[192:195], v[12:15]
	v_mfma_f32_16x16x32_bf16 v[12:15], v[148:151], v[200:203], v[12:15]
	v_mfma_f32_16x16x32_bf16 v[48:51], v[152:155], v[168:171], v[48:51]
	v_mfma_f32_16x16x32_bf16 v[48:51], v[156:159], v[172:175], v[48:51]
	v_mfma_f32_16x16x32_bf16 v[40:43], v[160:163], v[168:171], v[40:43]
	v_mfma_f32_16x16x32_bf16 v[40:43], v[164:167], v[172:175], v[40:43]
	v_mfma_f32_16x16x32_bf16 v[32:35], v[152:155], v[176:179], v[32:35]
	v_mfma_f32_16x16x32_bf16 v[32:35], v[156:159], v[180:183], v[32:35]
	v_mfma_f32_16x16x32_bf16 v[24:27], v[160:163], v[176:179], v[24:27]
	v_mfma_f32_16x16x32_bf16 v[24:27], v[164:167], v[180:183], v[24:27]
	v_mfma_f32_16x16x32_bf16 v[16:19], v[152:155], v[184:187], v[16:19]
	v_mfma_f32_16x16x32_bf16 v[16:19], v[156:159], v[188:191], v[16:19]
	v_mfma_f32_16x16x32_bf16 v[8:11], v[160:163], v[184:187], v[8:11]
	v_mfma_f32_16x16x32_bf16 v[8:11], v[164:167], v[188:191], v[8:11]
	v_mfma_f32_16x16x32_bf16 v[4:7], v[152:155], v[192:195], v[4:7]
	v_mfma_f32_16x16x32_bf16 v[4:7], v[156:159], v[200:203], v[4:7]
	v_mfma_f32_16x16x32_bf16 v[0:3], v[160:163], v[192:195], v[0:3]
	v_mfma_f32_16x16x32_bf16 v[0:3], v[164:167], v[200:203], v[0:3]
	s_barrier
	s_setprio 0
	s_add_i32 s21, s21, 2
	s_add_u32 s4, s4, 0x100
	s_addc_u32 s5, s5, 0
	s_add_u32 s15, s15, 0x100
	s_addc_u32 s17, s17, 0
	s_add_u32 s34, s34, 0x100
	s_addc_u32 s35, s35, 0
	s_cmp_gt_u32 s21, 13
	s_cbranch_scc0 .LBB0_1290
	s_and_b64 vcc, exec, s[60:61]
	s_cbranch_vccz .LBB0_1293
	s_barrier

.LBB0_1425:
	s_cmpk_eq_i32 s80, 0x54
	s_cselect_b32 s56, s48, s4
	s_cselect_b32 s57, s49, s5
	s_cselect_b32 s74, s70, s15
	s_cselect_b32 s75, s71, s72
	s_add_u32 s16, s56, 0x80
	s_addc_u32 s17, s57, 0
	s_add_i32 s81, 0, 0x10000
	s_add_i32 vcc_lo, 0, 0x14000
	v_add_u32_e32 v136, s81, v172
	v_add_u32_e32 v156, vcc_lo, v172
	ds_read_b128 v[120:123], v136
	ds_read_b128 v[124:127], v136 offset:1024
	ds_read_b128 v[132:135], v136 offset:2048
	ds_read_b128 v[136:139], v136 offset:3072
	ds_read_b128 v[144:147], v156
	ds_read_b128 v[148:151], v156 offset:1024
	ds_read_b128 v[152:155], v156 offset:2048
	ds_read_b128 v[156:159], v156 offset:3072
	s_mov_b64 s[12:13], s[28:29]
	s_add_i32 m0, s2, 0xc000
	ds_read_b128 v[160:163], v173
	ds_read_b128 v[164:167], v173 offset:1024
	ds_read_b128 v[174:177], v173 offset:2048
	ds_read_b128 v[178:181], v173 offset:3072
	ds_read_b128 v[182:185], v173 offset:4096
	ds_read_b128 v[186:189], v173 offset:5120
	ds_read_b128 v[190:193], v173 offset:6144
	ds_read_b128 v[200:203], v173 offset:7168
	s_nop 0
	global_load_lds_dwordx4 v168, s[12:13]
	s_add_i32 m0, s2, 0xe000
	s_nop 0
	global_load_lds_dwordx4 v170, s[12:13]
	s_waitcnt vmcnt(8) lgkmcnt(0)
	s_setprio 1
	s_barrier
	v_mfma_f32_16x16x32_bf16 v[140:143], v[120:123], v[160:163], v[140:143]
	v_mfma_f32_16x16x32_bf16 v[140:143], v[124:127], v[164:167], v[140:143]
	v_mfma_f32_16x16x32_bf16 v[128:131], v[132:135], v[160:163], v[128:131]
	v_mfma_f32_16x16x32_bf16 v[128:131], v[136:139], v[164:167], v[128:131]
	v_mfma_f32_16x16x32_bf16 v[116:119], v[120:123], v[174:177], v[116:119]
	v_mfma_f32_16x16x32_bf16 v[116:119], v[124:127], v[178:181], v[116:119]
	v_mfma_f32_16x16x32_bf16 v[104:107], v[132:135], v[174:177], v[104:107]
	v_mfma_f32_16x16x32_bf16 v[104:107], v[136:139], v[178:181], v[104:107]
	v_mfma_f32_16x16x32_bf16 v[96:99], v[120:123], v[182:185], v[96:99]
	v_mfma_f32_16x16x32_bf16 v[96:99], v[124:127], v[186:189], v[96:99]
	v_mfma_f32_16x16x32_bf16 v[88:91], v[132:135], v[182:185], v[88:91]
	v_mfma_f32_16x16x32_bf16 v[88:91], v[136:139], v[186:189], v[88:91]
	v_mfma_f32_16x16x32_bf16 v[84:87], v[120:123], v[190:193], v[84:87]
	v_mfma_f32_16x16x32_bf16 v[84:87], v[124:127], v[200:203], v[84:87]
	v_mfma_f32_16x16x32_bf16 v[72:75], v[132:135], v[190:193], v[72:75]
	v_mfma_f32_16x16x32_bf16 v[72:75], v[136:139], v[200:203], v[72:75]
	v_mfma_f32_16x16x32_bf16 v[112:115], v[144:147], v[160:163], v[112:115]
	v_mfma_f32_16x16x32_bf16 v[112:115], v[148:151], v[164:167], v[112:115]
	v_mfma_f32_16x16x32_bf16 v[108:111], v[152:155], v[160:163], v[108:111]
	v_mfma_f32_16x16x32_bf16 v[108:111], v[156:159], v[164:167], v[108:111]
	v_mfma_f32_16x16x32_bf16 v[100:103], v[144:147], v[174:177], v[100:103]
	v_mfma_f32_16x16x32_bf16 v[100:103], v[148:151], v[178:181], v[100:103]
	v_mfma_f32_16x16x32_bf16 v[92:95], v[152:155], v[174:177], v[92:95]
	v_mfma_f32_16x16x32_bf16 v[92:95], v[156:159], v[178:181], v[92:95]
	v_mfma_f32_16x16x32_bf16 v[80:83], v[144:147], v[182:185], v[80:83]
	v_mfma_f32_16x16x32_bf16 v[80:83], v[148:151], v[186:189], v[80:83]
	v_mfma_f32_16x16x32_bf16 v[76:79], v[152:155], v[182:185], v[76:79]
	v_mfma_f32_16x16x32_bf16 v[76:79], v[156:159], v[186:189], v[76:79]
	v_mfma_f32_16x16x32_bf16 v[68:71], v[144:147], v[190:193], v[68:71]
	v_mfma_f32_16x16x32_bf16 v[68:71], v[148:151], v[200:203], v[68:71]
	v_mfma_f32_16x16x32_bf16 v[64:67], v[152:155], v[190:193], v[64:67]
	v_mfma_f32_16x16x32_bf16 v[64:67], v[156:159], v[200:203], v[64:67]
	s_barrier
	s_setprio 0
	s_add_i32 s81, s81, s97
	s_mov_b64 s[12:13], s[74:75]
	s_mov_b32 m0, s81
	ds_read_b128 v[160:163], v173 offset:16384
	ds_read_b128 v[164:167], v173 offset:17408
	ds_read_b128 v[174:177], v173 offset:18432
	ds_read_b128 v[178:181], v173 offset:19456
	ds_read_b128 v[182:185], v173 offset:20480
	ds_read_b128 v[186:189], v173 offset:21504
	ds_read_b128 v[190:193], v173 offset:22528
	ds_read_b128 v[200:203], v173 offset:23552
	s_nop 0
	global_load_lds_dwordx4 v169, s[12:13]
	s_add_i32 m0, s81, 0x2000
	s_nop 0
	global_load_lds_dwordx4 v171, s[12:13]
	s_add_u32 s12, s74, 0x160000
	s_addc_u32 s13, s75, 0
	s_add_i32 s81, vcc_lo, s97
	s_mov_b32 m0, s81
	s_nop 0
	global_load_lds_dwordx4 v169, s[12:13]
	s_add_i32 m0, s81, 0x2000
	s_nop 0
	global_load_lds_dwordx4 v171, s[12:13]
	s_mov_b64 s[12:13], s[56:57]
	s_mov_b32 m0, s2
	s_nop 0
	global_load_lds_dwordx4 v168, s[12:13]
	s_mov_b32 m0, s65
	s_nop 0
	global_load_lds_dwordx4 v170, s[12:13]
	s_waitcnt vmcnt(8) lgkmcnt(0)
	s_setprio 1
	s_barrier
	v_mfma_f32_16x16x32_bf16 v[60:63], v[120:123], v[160:163], v[60:63]
	v_mfma_f32_16x16x32_bf16 v[60:63], v[124:127], v[164:167], v[60:63]
	v_mfma_f32_16x16x32_bf16 v[56:59], v[132:135], v[160:163], v[56:59]
	v_mfma_f32_16x16x32_bf16 v[56:59], v[136:139], v[164:167], v[56:59]
	v_mfma_f32_16x16x32_bf16 v[48:51], v[120:123], v[174:177], v[48:51]
	v_mfma_f32_16x16x32_bf16 v[48:51], v[124:127], v[178:181], v[48:51]
	v_mfma_f32_16x16x32_bf16 v[40:43], v[132:135], v[174:177], v[40:43]
	v_mfma_f32_16x16x32_bf16 v[40:43], v[136:139], v[178:181], v[40:43]
	v_mfma_f32_16x16x32_bf16 v[32:35], v[120:123], v[182:185], v[32:35]
	v_mfma_f32_16x16x32_bf16 v[32:35], v[124:127], v[186:189], v[32:35]
	v_mfma_f32_16x16x32_bf16 v[24:27], v[132:135], v[182:185], v[24:27]
	v_mfma_f32_16x16x32_bf16 v[24:27], v[136:139], v[186:189], v[24:27]
	v_mfma_f32_16x16x32_bf16 v[16:19], v[120:123], v[190:193], v[16:19]
	v_mfma_f32_16x16x32_bf16 v[16:19], v[124:127], v[200:203], v[16:19]
	v_mfma_f32_16x16x32_bf16 v[8:11], v[132:135], v[190:193], v[8:11]
	v_mfma_f32_16x16x32_bf16 v[8:11], v[136:139], v[200:203], v[8:11]
	v_mfma_f32_16x16x32_bf16 v[52:55], v[144:147], v[160:163], v[52:55]
	v_mfma_f32_16x16x32_bf16 v[52:55], v[148:151], v[164:167], v[52:55]
	v_mfma_f32_16x16x32_bf16 v[44:47], v[152:155], v[160:163], v[44:47]
	v_mfma_f32_16x16x32_bf16 v[44:47], v[156:159], v[164:167], v[44:47]
	v_mfma_f32_16x16x32_bf16 v[36:39], v[144:147], v[174:177], v[36:39]
	v_mfma_f32_16x16x32_bf16 v[36:39], v[148:151], v[178:181], v[36:39]
	v_mfma_f32_16x16x32_bf16 v[28:31], v[152:155], v[174:177], v[28:31]
	v_mfma_f32_16x16x32_bf16 v[28:31], v[156:159], v[178:181], v[28:31]
	v_mfma_f32_16x16x32_bf16 v[20:23], v[144:147], v[182:185], v[20:23]
	v_mfma_f32_16x16x32_bf16 v[20:23], v[148:151], v[186:189], v[20:23]
	v_mfma_f32_16x16x32_bf16 v[12:15], v[152:155], v[182:185], v[12:15]
	v_mfma_f32_16x16x32_bf16 v[12:15], v[156:159], v[186:189], v[12:15]
	v_mfma_f32_16x16x32_bf16 v[4:7], v[144:147], v[190:193], v[4:7]
	v_mfma_f32_16x16x32_bf16 v[4:7], v[148:151], v[200:203], v[4:7]
	v_mfma_f32_16x16x32_bf16 v[0:3], v[152:155], v[190:193], v[0:3]
	v_mfma_f32_16x16x32_bf16 v[0:3], v[156:159], v[200:203], v[0:3]
	s_barrier
	s_setprio 0
	s_add_i32 s81, 0, 0x18000
	s_add_i32 vcc_lo, 0, 0x1c000
	v_add_u32_e32 v136, s81, v172
	v_add_u32_e32 v156, vcc_lo, v172
	ds_read_b128 v[120:123], v136
	ds_read_b128 v[124:127], v136 offset:1024
	ds_read_b128 v[132:135], v136 offset:2048
	ds_read_b128 v[136:139], v136 offset:3072
	ds_read_b128 v[144:147], v156
	ds_read_b128 v[148:151], v156 offset:1024
	ds_read_b128 v[152:155], v156 offset:2048
	ds_read_b128 v[156:159], v156 offset:3072
	s_add_u32 s12, s56, 0x160000
	s_addc_u32 s13, s57, 0
	s_mov_b32 m0, s93
	ds_read_b128 v[160:163], v173 offset:32768
	ds_read_b128 v[164:167], v173 offset:33792
	ds_read_b128 v[174:177], v173 offset:34816
	ds_read_b128 v[178:181], v173 offset:35840
	ds_read_b128 v[182:185], v173 offset:36864
	ds_read_b128 v[186:189], v173 offset:37888
	ds_read_b128 v[190:193], v173 offset:38912
	ds_read_b128 v[200:203], v173 offset:39936
	s_nop 0
	global_load_lds_dwordx4 v168, s[12:13]
	s_mov_b32 m0, s92
	s_nop 0
	global_load_lds_dwordx4 v170, s[12:13]
	s_waitcnt vmcnt(8) lgkmcnt(0)
	s_setprio 1
	s_barrier
	v_mfma_f32_16x16x32_bf16 v[140:143], v[120:123], v[160:163], v[140:143]
	v_mfma_f32_16x16x32_bf16 v[140:143], v[124:127], v[164:167], v[140:143]
	v_mfma_f32_16x16x32_bf16 v[128:131], v[132:135], v[160:163], v[128:131]
	v_mfma_f32_16x16x32_bf16 v[128:131], v[136:139], v[164:167], v[128:131]
	v_mfma_f32_16x16x32_bf16 v[116:119], v[120:123], v[174:177], v[116:119]
	v_mfma_f32_16x16x32_bf16 v[116:119], v[124:127], v[178:181], v[116:119]
	v_mfma_f32_16x16x32_bf16 v[104:107], v[132:135], v[174:177], v[104:107]
	v_mfma_f32_16x16x32_bf16 v[104:107], v[136:139], v[178:181], v[104:107]
	v_mfma_f32_16x16x32_bf16 v[96:99], v[120:123], v[182:185], v[96:99]
	v_mfma_f32_16x16x32_bf16 v[96:99], v[124:127], v[186:189], v[96:99]
	v_mfma_f32_16x16x32_bf16 v[88:91], v[132:135], v[182:185], v[88:91]
	v_mfma_f32_16x16x32_bf16 v[88:91], v[136:139], v[186:189], v[88:91]
	v_mfma_f32_16x16x32_bf16 v[84:87], v[120:123], v[190:193], v[84:87]
	v_mfma_f32_16x16x32_bf16 v[84:87], v[124:127], v[200:203], v[84:87]
	v_mfma_f32_16x16x32_bf16 v[72:75], v[132:135], v[190:193], v[72:75]
	v_mfma_f32_16x16x32_bf16 v[72:75], v[136:139], v[200:203], v[72:75]
	v_mfma_f32_16x16x32_bf16 v[112:115], v[144:147], v[160:163], v[112:115]
	v_mfma_f32_16x16x32_bf16 v[112:115], v[148:151], v[164:167], v[112:115]
	v_mfma_f32_16x16x32_bf16 v[108:111], v[152:155], v[160:163], v[108:111]
	v_mfma_f32_16x16x32_bf16 v[108:111], v[156:159], v[164:167], v[108:111]
	v_mfma_f32_16x16x32_bf16 v[100:103], v[144:147], v[174:177], v[100:103]
	v_mfma_f32_16x16x32_bf16 v[100:103], v[148:151], v[178:181], v[100:103]
	v_mfma_f32_16x16x32_bf16 v[92:95], v[152:155], v[174:177], v[92:95]
	v_mfma_f32_16x16x32_bf16 v[92:95], v[156:159], v[178:181], v[92:95]
	v_mfma_f32_16x16x32_bf16 v[80:83], v[144:147], v[182:185], v[80:83]
	v_mfma_f32_16x16x32_bf16 v[80:83], v[148:151], v[186:189], v[80:83]
	v_mfma_f32_16x16x32_bf16 v[76:79], v[152:155], v[182:185], v[76:79]
	v_mfma_f32_16x16x32_bf16 v[76:79], v[156:159], v[186:189], v[76:79]
	v_mfma_f32_16x16x32_bf16 v[68:71], v[144:147], v[190:193], v[68:71]
	v_mfma_f32_16x16x32_bf16 v[68:71], v[148:151], v[200:203], v[68:71]
	v_mfma_f32_16x16x32_bf16 v[64:67], v[152:155], v[190:193], v[64:67]
	v_mfma_f32_16x16x32_bf16 v[64:67], v[156:159], v[200:203], v[64:67]
	s_barrier
	s_setprio 0
	s_add_u32 s12, s74, 0x80
	s_addc_u32 s13, s75, 0
	s_add_i32 s56, s81, s97
	s_mov_b32 m0, s56
	ds_read_b128 v[160:163], v173 offset:49152
	ds_read_b128 v[164:167], v173 offset:50176
	ds_read_b128 v[174:177], v173 offset:51200
	ds_read_b128 v[178:181], v173 offset:52224
	ds_read_b128 v[182:185], v173 offset:53248
	ds_read_b128 v[186:189], v173 offset:54272
	ds_read_b128 v[190:193], v173 offset:55296
	ds_read_b128 v[200:203], v173 offset:56320
	s_nop 0
	global_load_lds_dwordx4 v169, s[12:13]
	s_add_i32 m0, s56, 0x2000
	s_nop 0
	global_load_lds_dwordx4 v171, s[12:13]
	s_add_u32 s12, s74, 0x160080
	s_addc_u32 s13, s75, 0
	s_add_i32 s56, vcc_lo, s97
	s_mov_b32 m0, s56
	s_nop 0
	global_load_lds_dwordx4 v169, s[12:13]
	s_add_i32 m0, s56, 0x2000
	s_nop 0
	global_load_lds_dwordx4 v171, s[12:13]
	s_mov_b32 m0, s19
	s_nop 0
	global_load_lds_dwordx4 v168, s[16:17]
	s_mov_b32 m0, s89
	s_nop 0
	global_load_lds_dwordx4 v170, s[16:17]
	s_waitcnt vmcnt(8) lgkmcnt(0)
	s_setprio 1
	s_barrier
	v_mfma_f32_16x16x32_bf16 v[60:63], v[120:123], v[160:163], v[60:63]
	v_mfma_f32_16x16x32_bf16 v[60:63], v[124:127], v[164:167], v[60:63]
	v_mfma_f32_16x16x32_bf16 v[56:59], v[132:135], v[160:163], v[56:59]
	v_mfma_f32_16x16x32_bf16 v[56:59], v[136:139], v[164:167], v[56:59]
	v_mfma_f32_16x16x32_bf16 v[48:51], v[120:123], v[174:177], v[48:51]
	v_mfma_f32_16x16x32_bf16 v[48:51], v[124:127], v[178:181], v[48:51]
	v_mfma_f32_16x16x32_bf16 v[40:43], v[132:135], v[174:177], v[40:43]
	v_mfma_f32_16x16x32_bf16 v[40:43], v[136:139], v[178:181], v[40:43]
	v_mfma_f32_16x16x32_bf16 v[32:35], v[120:123], v[182:185], v[32:35]
	v_mfma_f32_16x16x32_bf16 v[32:35], v[124:127], v[186:189], v[32:35]
	v_mfma_f32_16x16x32_bf16 v[24:27], v[132:135], v[182:185], v[24:27]
	v_mfma_f32_16x16x32_bf16 v[24:27], v[136:139], v[186:189], v[24:27]
	v_mfma_f32_16x16x32_bf16 v[16:19], v[120:123], v[190:193], v[16:19]
	v_mfma_f32_16x16x32_bf16 v[16:19], v[124:127], v[200:203], v[16:19]
	v_mfma_f32_16x16x32_bf16 v[8:11], v[132:135], v[190:193], v[8:11]
	v_mfma_f32_16x16x32_bf16 v[8:11], v[136:139], v[200:203], v[8:11]
	v_mfma_f32_16x16x32_bf16 v[52:55], v[144:147], v[160:163], v[52:55]
	v_mfma_f32_16x16x32_bf16 v[52:55], v[148:151], v[164:167], v[52:55]
	v_mfma_f32_16x16x32_bf16 v[44:47], v[152:155], v[160:163], v[44:47]
	v_mfma_f32_16x16x32_bf16 v[44:47], v[156:159], v[164:167], v[44:47]
	v_mfma_f32_16x16x32_bf16 v[36:39], v[144:147], v[174:177], v[36:39]
	v_mfma_f32_16x16x32_bf16 v[36:39], v[148:151], v[178:181], v[36:39]
	v_mfma_f32_16x16x32_bf16 v[28:31], v[152:155], v[174:177], v[28:31]
	v_mfma_f32_16x16x32_bf16 v[28:31], v[156:159], v[178:181], v[28:31]
	v_mfma_f32_16x16x32_bf16 v[20:23], v[144:147], v[182:185], v[20:23]
	v_mfma_f32_16x16x32_bf16 v[20:23], v[148:151], v[186:189], v[20:23]
	v_mfma_f32_16x16x32_bf16 v[12:15], v[152:155], v[182:185], v[12:15]
	v_mfma_f32_16x16x32_bf16 v[12:15], v[156:159], v[186:189], v[12:15]
	v_mfma_f32_16x16x32_bf16 v[4:7], v[144:147], v[190:193], v[4:7]
	v_mfma_f32_16x16x32_bf16 v[4:7], v[148:151], v[200:203], v[4:7]
	v_mfma_f32_16x16x32_bf16 v[0:3], v[152:155], v[190:193], v[0:3]
	v_mfma_f32_16x16x32_bf16 v[0:3], v[156:159], v[200:203], v[0:3]
	s_barrier
	s_setprio 0
	s_add_i32 s80, s80, 2
	s_add_u32 s4, s4, 0x100
	s_addc_u32 s5, s5, 0
	s_add_u32 s15, s15, 0x100
	s_addc_u32 s72, s72, 0
	s_add_u32 s28, s28, 0x100
	s_addc_u32 s29, s29, 0
	s_cmpk_gt_u32 s80, 0x55
	s_cbranch_scc0 .LBB0_1425
	s_and_b64 vcc, exec, s[60:61]
	s_cbranch_vccz .LBB0_1428
	s_barrier

.LBB0_1579:
	s_cmp_eq_u32 s49, 4
	s_cselect_b32 s26, s14, s13
	s_cselect_b32 s27, s15, s21
	s_cselect_b32 s24, s16, s47
	s_cselect_b32 s25, s17, s48
	s_add_u32 s22, s26, 0x80
	s_addc_u32 s23, s27, 0
	s_add_i32 s65, 0, 0x10000
	s_add_i32 s69, 0, 0x14000
	v_add_u32_e32 v132, s65, v154
	v_add_u32_e32 v148, s69, v154
	ds_read_b128 v[112:115], v132
	ds_read_b128 v[120:123], v132 offset:1024
	ds_read_b128 v[128:131], v132 offset:2048
	ds_read_b128 v[132:135], v132 offset:3072
	ds_read_b128 v[144:147], v148
	ds_read_b128 v[156:159], v148 offset:1024
	ds_read_b128 v[160:163], v148 offset:2048
	ds_read_b128 v[164:167], v148 offset:3072
	s_add_u32 s56, s13, 0x15ff80
	s_addc_u32 s57, s21, 0
	s_add_i32 m0, s31, 0xc000
	ds_read_b128 v[168:171], v155
	ds_read_b128 v[172:175], v155 offset:1024
	ds_read_b128 v[176:179], v155 offset:2048
	ds_read_b128 v[180:183], v155 offset:3072
	ds_read_b128 v[184:187], v155 offset:4096
	ds_read_b128 v[188:191], v155 offset:5120
	ds_read_b128 v[192:195], v155 offset:6144
	ds_read_b128 v[200:203], v155 offset:7168
	s_nop 0
	global_load_lds_dwordx4 v151, s[56:57]
	s_add_i32 m0, s31, 0xe000
	s_nop 0
	global_load_lds_dwordx4 v150, s[56:57]
	s_waitcnt vmcnt(8) lgkmcnt(0)
	s_setprio 1
	s_barrier
	v_mfma_f32_16x16x32_bf16 v[140:143], v[112:115], v[168:171], v[140:143]
	v_mfma_f32_16x16x32_bf16 v[140:143], v[120:123], v[172:175], v[140:143]
	v_mfma_f32_16x16x32_bf16 v[136:139], v[128:131], v[168:171], v[136:139]
	v_mfma_f32_16x16x32_bf16 v[136:139], v[132:135], v[172:175], v[136:139]
	v_mfma_f32_16x16x32_bf16 v[108:111], v[112:115], v[176:179], v[108:111]
	v_mfma_f32_16x16x32_bf16 v[108:111], v[120:123], v[180:183], v[108:111]
	v_mfma_f32_16x16x32_bf16 v[104:107], v[128:131], v[176:179], v[104:107]
	v_mfma_f32_16x16x32_bf16 v[104:107], v[132:135], v[180:183], v[104:107]
	v_mfma_f32_16x16x32_bf16 v[92:95], v[112:115], v[184:187], v[92:95]
	v_mfma_f32_16x16x32_bf16 v[92:95], v[120:123], v[188:191], v[92:95]
	v_mfma_f32_16x16x32_bf16 v[88:91], v[128:131], v[184:187], v[88:91]
	v_mfma_f32_16x16x32_bf16 v[88:91], v[132:135], v[188:191], v[88:91]
	v_mfma_f32_16x16x32_bf16 v[76:79], v[112:115], v[192:195], v[76:79]
	v_mfma_f32_16x16x32_bf16 v[76:79], v[120:123], v[200:203], v[76:79]
	v_mfma_f32_16x16x32_bf16 v[72:75], v[128:131], v[192:195], v[72:75]
	v_mfma_f32_16x16x32_bf16 v[72:75], v[132:135], v[200:203], v[72:75]
	v_mfma_f32_16x16x32_bf16 v[124:127], v[144:147], v[168:171], v[124:127]
	v_mfma_f32_16x16x32_bf16 v[124:127], v[156:159], v[172:175], v[124:127]
	v_mfma_f32_16x16x32_bf16 v[116:119], v[160:163], v[168:171], v[116:119]
	v_mfma_f32_16x16x32_bf16 v[116:119], v[164:167], v[172:175], v[116:119]
	v_mfma_f32_16x16x32_bf16 v[100:103], v[144:147], v[176:179], v[100:103]
	v_mfma_f32_16x16x32_bf16 v[100:103], v[156:159], v[180:183], v[100:103]
	v_mfma_f32_16x16x32_bf16 v[96:99], v[160:163], v[176:179], v[96:99]
	v_mfma_f32_16x16x32_bf16 v[96:99], v[164:167], v[180:183], v[96:99]
	v_mfma_f32_16x16x32_bf16 v[84:87], v[144:147], v[184:187], v[84:87]
	v_mfma_f32_16x16x32_bf16 v[84:87], v[156:159], v[188:191], v[84:87]
	v_mfma_f32_16x16x32_bf16 v[80:83], v[160:163], v[184:187], v[80:83]
	v_mfma_f32_16x16x32_bf16 v[80:83], v[164:167], v[188:191], v[80:83]
	v_mfma_f32_16x16x32_bf16 v[68:71], v[144:147], v[192:195], v[68:71]
	v_mfma_f32_16x16x32_bf16 v[68:71], v[156:159], v[200:203], v[68:71]
	v_mfma_f32_16x16x32_bf16 v[64:67], v[160:163], v[192:195], v[64:67]
	v_mfma_f32_16x16x32_bf16 v[64:67], v[164:167], v[200:203], v[64:67]
	s_barrier
	s_setprio 0
	s_add_i32 s65, s65, s97
	s_mov_b64 s[56:57], s[24:25]
	s_mov_b32 m0, s65
	ds_read_b128 v[168:171], v155 offset:16384
	ds_read_b128 v[172:175], v155 offset:17408
	ds_read_b128 v[176:179], v155 offset:18432
	ds_read_b128 v[180:183], v155 offset:19456
	ds_read_b128 v[184:187], v155 offset:20480
	ds_read_b128 v[188:191], v155 offset:21504
	ds_read_b128 v[192:195], v155 offset:22528
	ds_read_b128 v[200:203], v155 offset:23552
	s_nop 0
	global_load_lds_dwordx4 v152, s[56:57]
	s_add_i32 m0, s65, 0x2000
	s_nop 0
	global_load_lds_dwordx4 v153, s[56:57]
	s_add_u32 s56, s24, 0x160000
	s_addc_u32 s57, s25, 0
	s_add_i32 s65, s69, s97
	s_mov_b32 m0, s65
	s_nop 0
	global_load_lds_dwordx4 v152, s[56:57]
	s_add_i32 m0, s65, 0x2000
	s_nop 0
	global_load_lds_dwordx4 v153, s[56:57]
	s_mov_b64 s[56:57], s[26:27]
	s_mov_b32 m0, s31
	s_nop 0
	global_load_lds_dwordx4 v151, s[56:57]
	s_mov_b32 m0, s34
	s_nop 0
	global_load_lds_dwordx4 v150, s[56:57]
	s_waitcnt vmcnt(8) lgkmcnt(0)
	s_setprio 1
	s_barrier
	v_mfma_f32_16x16x32_bf16 v[60:63], v[112:115], v[168:171], v[60:63]
	v_mfma_f32_16x16x32_bf16 v[60:63], v[120:123], v[172:175], v[60:63]
	v_mfma_f32_16x16x32_bf16 v[56:59], v[128:131], v[168:171], v[56:59]
	v_mfma_f32_16x16x32_bf16 v[56:59], v[132:135], v[172:175], v[56:59]
	v_mfma_f32_16x16x32_bf16 v[52:55], v[112:115], v[176:179], v[52:55]
	v_mfma_f32_16x16x32_bf16 v[52:55], v[120:123], v[180:183], v[52:55]
	v_mfma_f32_16x16x32_bf16 v[44:47], v[128:131], v[176:179], v[44:47]
	v_mfma_f32_16x16x32_bf16 v[44:47], v[132:135], v[180:183], v[44:47]
	v_mfma_f32_16x16x32_bf16 v[36:39], v[112:115], v[184:187], v[36:39]
	v_mfma_f32_16x16x32_bf16 v[36:39], v[120:123], v[188:191], v[36:39]
	v_mfma_f32_16x16x32_bf16 v[28:31], v[128:131], v[184:187], v[28:31]
	v_mfma_f32_16x16x32_bf16 v[28:31], v[132:135], v[188:191], v[28:31]
	v_mfma_f32_16x16x32_bf16 v[20:23], v[112:115], v[192:195], v[20:23]
	v_mfma_f32_16x16x32_bf16 v[20:23], v[120:123], v[200:203], v[20:23]
	v_mfma_f32_16x16x32_bf16 v[8:11], v[128:131], v[192:195], v[8:11]
	v_mfma_f32_16x16x32_bf16 v[8:11], v[132:135], v[200:203], v[8:11]
	v_mfma_f32_16x16x32_bf16 v[48:51], v[144:147], v[168:171], v[48:51]
	v_mfma_f32_16x16x32_bf16 v[48:51], v[156:159], v[172:175], v[48:51]
	v_mfma_f32_16x16x32_bf16 v[40:43], v[160:163], v[168:171], v[40:43]
	v_mfma_f32_16x16x32_bf16 v[40:43], v[164:167], v[172:175], v[40:43]
	v_mfma_f32_16x16x32_bf16 v[32:35], v[144:147], v[176:179], v[32:35]
	v_mfma_f32_16x16x32_bf16 v[32:35], v[156:159], v[180:183], v[32:35]
	v_mfma_f32_16x16x32_bf16 v[24:27], v[160:163], v[176:179], v[24:27]
	v_mfma_f32_16x16x32_bf16 v[24:27], v[164:167], v[180:183], v[24:27]
	v_mfma_f32_16x16x32_bf16 v[16:19], v[144:147], v[184:187], v[16:19]
	v_mfma_f32_16x16x32_bf16 v[16:19], v[156:159], v[188:191], v[16:19]
	v_mfma_f32_16x16x32_bf16 v[12:15], v[160:163], v[184:187], v[12:15]
	v_mfma_f32_16x16x32_bf16 v[12:15], v[164:167], v[188:191], v[12:15]
	v_mfma_f32_16x16x32_bf16 v[4:7], v[144:147], v[192:195], v[4:7]
	v_mfma_f32_16x16x32_bf16 v[4:7], v[156:159], v[200:203], v[4:7]
	v_mfma_f32_16x16x32_bf16 v[0:3], v[160:163], v[192:195], v[0:3]
	v_mfma_f32_16x16x32_bf16 v[0:3], v[164:167], v[200:203], v[0:3]
	s_barrier
	s_setprio 0
	s_add_i32 s56, 0, 0x18000
	s_add_i32 s57, 0, 0x1c000
	v_add_u32_e32 v132, s56, v154
	v_add_u32_e32 v148, s57, v154
	ds_read_b128 v[112:115], v132
	ds_read_b128 v[120:123], v132 offset:1024
	ds_read_b128 v[128:131], v132 offset:2048
	ds_read_b128 v[132:135], v132 offset:3072
	ds_read_b128 v[144:147], v148
	ds_read_b128 v[156:159], v148 offset:1024
	ds_read_b128 v[160:163], v148 offset:2048
	ds_read_b128 v[164:167], v148 offset:3072
	s_add_u32 s26, s26, 0x160000
	s_addc_u32 s27, s27, 0
	s_mov_b32 m0, s35
	ds_read_b128 v[168:171], v155 offset:32768
	ds_read_b128 v[172:175], v155 offset:33792
	ds_read_b128 v[176:179], v155 offset:34816
	ds_read_b128 v[180:183], v155 offset:35840
	ds_read_b128 v[184:187], v155 offset:36864
	ds_read_b128 v[188:191], v155 offset:37888
	ds_read_b128 v[192:195], v155 offset:38912
	ds_read_b128 v[200:203], v155 offset:39936
	s_nop 0
	global_load_lds_dwordx4 v151, s[26:27]
	s_mov_b32 m0, s36
	s_nop 0
	global_load_lds_dwordx4 v150, s[26:27]
	s_waitcnt vmcnt(8) lgkmcnt(0)
	s_setprio 1
	s_barrier
	v_mfma_f32_16x16x32_bf16 v[140:143], v[112:115], v[168:171], v[140:143]
	v_mfma_f32_16x16x32_bf16 v[140:143], v[120:123], v[172:175], v[140:143]
	v_mfma_f32_16x16x32_bf16 v[136:139], v[128:131], v[168:171], v[136:139]
	v_mfma_f32_16x16x32_bf16 v[136:139], v[132:135], v[172:175], v[136:139]
	v_mfma_f32_16x16x32_bf16 v[108:111], v[112:115], v[176:179], v[108:111]
	v_mfma_f32_16x16x32_bf16 v[108:111], v[120:123], v[180:183], v[108:111]
	v_mfma_f32_16x16x32_bf16 v[104:107], v[128:131], v[176:179], v[104:107]
	v_mfma_f32_16x16x32_bf16 v[104:107], v[132:135], v[180:183], v[104:107]
	v_mfma_f32_16x16x32_bf16 v[92:95], v[112:115], v[184:187], v[92:95]
	v_mfma_f32_16x16x32_bf16 v[92:95], v[120:123], v[188:191], v[92:95]
	v_mfma_f32_16x16x32_bf16 v[88:91], v[128:131], v[184:187], v[88:91]
	v_mfma_f32_16x16x32_bf16 v[88:91], v[132:135], v[188:191], v[88:91]
	v_mfma_f32_16x16x32_bf16 v[76:79], v[112:115], v[192:195], v[76:79]
	v_mfma_f32_16x16x32_bf16 v[76:79], v[120:123], v[200:203], v[76:79]
	v_mfma_f32_16x16x32_bf16 v[72:75], v[128:131], v[192:195], v[72:75]
	v_mfma_f32_16x16x32_bf16 v[72:75], v[132:135], v[200:203], v[72:75]
	v_mfma_f32_16x16x32_bf16 v[124:127], v[144:147], v[168:171], v[124:127]
	v_mfma_f32_16x16x32_bf16 v[124:127], v[156:159], v[172:175], v[124:127]
	v_mfma_f32_16x16x32_bf16 v[116:119], v[160:163], v[168:171], v[116:119]
	v_mfma_f32_16x16x32_bf16 v[116:119], v[164:167], v[172:175], v[116:119]
	v_mfma_f32_16x16x32_bf16 v[100:103], v[144:147], v[176:179], v[100:103]
	v_mfma_f32_16x16x32_bf16 v[100:103], v[156:159], v[180:183], v[100:103]
	v_mfma_f32_16x16x32_bf16 v[96:99], v[160:163], v[176:179], v[96:99]
	v_mfma_f32_16x16x32_bf16 v[96:99], v[164:167], v[180:183], v[96:99]
	v_mfma_f32_16x16x32_bf16 v[84:87], v[144:147], v[184:187], v[84:87]
	v_mfma_f32_16x16x32_bf16 v[84:87], v[156:159], v[188:191], v[84:87]
	v_mfma_f32_16x16x32_bf16 v[80:83], v[160:163], v[184:187], v[80:83]
	v_mfma_f32_16x16x32_bf16 v[80:83], v[164:167], v[188:191], v[80:83]
	v_mfma_f32_16x16x32_bf16 v[68:71], v[144:147], v[192:195], v[68:71]
	v_mfma_f32_16x16x32_bf16 v[68:71], v[156:159], v[200:203], v[68:71]
	v_mfma_f32_16x16x32_bf16 v[64:67], v[160:163], v[192:195], v[64:67]
	v_mfma_f32_16x16x32_bf16 v[64:67], v[164:167], v[200:203], v[64:67]
	s_barrier
	s_setprio 0
	s_add_u32 s26, s24, 0x80
	s_addc_u32 s27, s25, 0
	s_add_i32 s56, s56, s97
	s_mov_b32 m0, s56
	ds_read_b128 v[168:171], v155 offset:49152
	ds_read_b128 v[172:175], v155 offset:50176
	ds_read_b128 v[176:179], v155 offset:51200
	ds_read_b128 v[180:183], v155 offset:52224
	ds_read_b128 v[184:187], v155 offset:53248
	ds_read_b128 v[188:191], v155 offset:54272
	ds_read_b128 v[192:195], v155 offset:55296
	ds_read_b128 v[200:203], v155 offset:56320
	s_nop 0
	global_load_lds_dwordx4 v152, s[26:27]
	s_add_i32 m0, s56, 0x2000
	s_add_u32 s24, s24, 0x160080
	s_addc_u32 s25, s25, 0
	global_load_lds_dwordx4 v153, s[26:27]
	s_add_i32 s26, s57, s97
	s_mov_b32 m0, s26
	s_nop 0
	global_load_lds_dwordx4 v152, s[24:25]
	s_add_i32 m0, s26, 0x2000
	s_nop 0
	global_load_lds_dwordx4 v153, s[24:25]
	s_mov_b32 m0, s37
	s_nop 0
	global_load_lds_dwordx4 v151, s[22:23]
	s_mov_b32 m0, s38
	s_nop 0
	global_load_lds_dwordx4 v150, s[22:23]
	s_waitcnt vmcnt(8) lgkmcnt(0)
	s_setprio 1
	s_barrier
	v_mfma_f32_16x16x32_bf16 v[60:63], v[112:115], v[168:171], v[60:63]
	v_mfma_f32_16x16x32_bf16 v[60:63], v[120:123], v[172:175], v[60:63]
	v_mfma_f32_16x16x32_bf16 v[56:59], v[128:131], v[168:171], v[56:59]
	v_mfma_f32_16x16x32_bf16 v[56:59], v[132:135], v[172:175], v[56:59]
	v_mfma_f32_16x16x32_bf16 v[52:55], v[112:115], v[176:179], v[52:55]
	v_mfma_f32_16x16x32_bf16 v[52:55], v[120:123], v[180:183], v[52:55]
	v_mfma_f32_16x16x32_bf16 v[44:47], v[128:131], v[176:179], v[44:47]
	v_mfma_f32_16x16x32_bf16 v[44:47], v[132:135], v[180:183], v[44:47]
	v_mfma_f32_16x16x32_bf16 v[36:39], v[112:115], v[184:187], v[36:39]
	v_mfma_f32_16x16x32_bf16 v[36:39], v[120:123], v[188:191], v[36:39]
	v_mfma_f32_16x16x32_bf16 v[28:31], v[128:131], v[184:187], v[28:31]
	v_mfma_f32_16x16x32_bf16 v[28:31], v[132:135], v[188:191], v[28:31]
	v_mfma_f32_16x16x32_bf16 v[20:23], v[112:115], v[192:195], v[20:23]
	v_mfma_f32_16x16x32_bf16 v[20:23], v[120:123], v[200:203], v[20:23]
	v_mfma_f32_16x16x32_bf16 v[8:11], v[128:131], v[192:195], v[8:11]
	v_mfma_f32_16x16x32_bf16 v[8:11], v[132:135], v[200:203], v[8:11]
	v_mfma_f32_16x16x32_bf16 v[48:51], v[144:147], v[168:171], v[48:51]
	v_mfma_f32_16x16x32_bf16 v[48:51], v[156:159], v[172:175], v[48:51]
	v_mfma_f32_16x16x32_bf16 v[40:43], v[160:163], v[168:171], v[40:43]
	v_mfma_f32_16x16x32_bf16 v[40:43], v[164:167], v[172:175], v[40:43]
	v_mfma_f32_16x16x32_bf16 v[32:35], v[144:147], v[176:179], v[32:35]
	v_mfma_f32_16x16x32_bf16 v[32:35], v[156:159], v[180:183], v[32:35]
	v_mfma_f32_16x16x32_bf16 v[24:27], v[160:163], v[176:179], v[24:27]
	v_mfma_f32_16x16x32_bf16 v[24:27], v[164:167], v[180:183], v[24:27]
	v_mfma_f32_16x16x32_bf16 v[16:19], v[144:147], v[184:187], v[16:19]
	v_mfma_f32_16x16x32_bf16 v[16:19], v[156:159], v[188:191], v[16:19]
	v_mfma_f32_16x16x32_bf16 v[12:15], v[160:163], v[184:187], v[12:15]
	v_mfma_f32_16x16x32_bf16 v[12:15], v[164:167], v[188:191], v[12:15]
	v_mfma_f32_16x16x32_bf16 v[4:7], v[144:147], v[192:195], v[4:7]
	v_mfma_f32_16x16x32_bf16 v[4:7], v[156:159], v[200:203], v[4:7]
	v_mfma_f32_16x16x32_bf16 v[0:3], v[160:163], v[192:195], v[0:3]
	v_mfma_f32_16x16x32_bf16 v[0:3], v[164:167], v[200:203], v[0:3]
	s_barrier
	s_setprio 0
	s_add_i32 s49, s49, 2
	s_add_u32 s13, s13, 0x100
	s_addc_u32 s21, s21, 0
	s_add_u32 s47, s47, 0x100
	s_addc_u32 s48, s48, 0
	s_cmp_gt_u32 s49, 5
	s_cbranch_scc0 .LBB0_1579
	s_and_b64 vcc, exec, s[60:61]
	s_cbranch_vccz .LBB0_1582
	s_barrier
